# 256x128 GEMM: the four B-fragment loads of a step issued one per fragment position (4..7) instead of two per position
# baseline (speedup 1.0000x reference)
.Lg256b_w2_tile:
	s_mul_i32 s17, s13, 0x1000
	s_lshl_b32 s3, s15, 5
	s_add_u32 s3, s3, s14
	s_mul_i32 s3, s3, 4
	s_add_u32 s17, s17, s3
	s_add_u32 s10, s24, s17
	s_addc_u32 s11, s25, 0
	s_lshl_b32 s3, s15, 5
	s_add_u32 s3, s3, s14
	s_lshl_b32 s3, s3, 2
	s_lshr_b32 s17, s13, 12
	s_max_u32 s17, s17, 1
	s_sub_u32 s17, s17, 1
	s_mul_i32 s17, s17, 24576
	s_add_u32 s3, s3, s17
	v_add_u32_e32 v234, s3, v225
	s_mov_b64 s[26:27], s[10:11]
	ds_read_b128 v[162:165], v216 offset:14336
	s_waitcnt vmcnt(16) lgkmcnt(7)
	v_mfma_f32_16x16x32_bf16 v[2:5], v[166:169], v[134:137], 0
	v_mfma_f32_16x16x32_bf16 v[6:9], v[174:177], v[134:137], 0
	ds_read_b128 v[134:137], v216 offset:16384
	s_waitcnt lgkmcnt(7)
	v_mfma_f32_16x16x32_bf16 v[10:13], v[166:169], v[138:141], 0
	v_mfma_f32_16x16x32_bf16 v[14:17], v[174:177], v[138:141], 0
	ds_read_b128 v[138:141], v216 offset:18432
	s_waitcnt lgkmcnt(7)
	v_mfma_f32_16x16x32_bf16 v[18:21], v[166:169], v[142:145], 0
	v_mfma_f32_16x16x32_bf16 v[22:25], v[174:177], v[142:145], 0
	ds_read_b128 v[142:145], v216 offset:20480
	s_waitcnt lgkmcnt(7)
	v_mfma_f32_16x16x32_bf16 v[26:29], v[166:169], v[146:149], 0
	v_mfma_f32_16x16x32_bf16 v[30:33], v[174:177], v[146:149], 0
	ds_read_b128 v[146:149], v216 offset:22528
	s_waitcnt lgkmcnt(7)
	v_mfma_f32_16x16x32_bf16 v[34:37], v[166:169], v[150:153], 0
	global_load_dwordx4 v[196:199], v220, s[8:9]
	v_mfma_f32_16x16x32_bf16 v[38:41], v[174:177], v[150:153], 0
	ds_read_b128 v[150:153], v216 offset:24576
	s_waitcnt lgkmcnt(7)
	v_mfma_f32_16x16x32_bf16 v[42:45], v[166:169], v[154:157], 0
	global_load_dwordx4 v[200:203], v220, s[8:9] offset:1024
	v_mfma_f32_16x16x32_bf16 v[46:49], v[174:177], v[154:157], 0
	ds_read_b128 v[154:157], v216 offset:26624
	s_waitcnt lgkmcnt(7)
	v_mfma_f32_16x16x32_bf16 v[50:53], v[166:169], v[158:161], 0
	global_load_dwordx4 v[204:207], v221, s[8:9]
	v_mfma_f32_16x16x32_bf16 v[54:57], v[174:177], v[158:161], 0
	ds_read_b128 v[158:161], v216 offset:28672
	s_waitcnt lgkmcnt(7)
	v_mfma_f32_16x16x32_bf16 v[58:61], v[166:169], v[162:165], 0
	global_load_dwordx4 v[212:215], v221, s[8:9] offset:1024
	v_mfma_f32_16x16x32_bf16 v[62:65], v[174:177], v[162:165], 0
	ds_read_b128 v[162:165], v216 offset:30720
	s_waitcnt lgkmcnt(7)
	v_mfma_f32_16x16x32_bf16 v[66:69], v[166:169], v[134:137], 0
	v_mfma_f32_16x16x32_bf16 v[70:73], v[174:177], v[134:137], 0
	ds_read_b128 v[134:137], v216 offset:1024
	s_waitcnt lgkmcnt(7)
	v_mfma_f32_16x16x32_bf16 v[74:77], v[166:169], v[138:141], 0
	v_mfma_f32_16x16x32_bf16 v[78:81], v[174:177], v[138:141], 0
	ds_read_b128 v[138:141], v216 offset:3072
	s_waitcnt lgkmcnt(7)
	v_mfma_f32_16x16x32_bf16 v[82:85], v[166:169], v[142:145], 0
	v_mfma_f32_16x16x32_bf16 v[86:89], v[174:177], v[142:145], 0
	ds_read_b128 v[142:145], v216 offset:5120
	s_waitcnt lgkmcnt(7)
	v_mfma_f32_16x16x32_bf16 v[90:93], v[166:169], v[146:149], 0
	v_mfma_f32_16x16x32_bf16 v[94:97], v[174:177], v[146:149], 0
	ds_read_b128 v[146:149], v216 offset:7168
	s_waitcnt lgkmcnt(7)
	v_mfma_f32_16x16x32_bf16 v[98:101], v[166:169], v[150:153], 0
	v_mfma_f32_16x16x32_bf16 v[102:105], v[174:177], v[150:153], 0
	ds_read_b128 v[150:153], v216 offset:9216
	s_waitcnt lgkmcnt(7)
	v_mfma_f32_16x16x32_bf16 v[106:109], v[166:169], v[154:157], 0
	v_mfma_f32_16x16x32_bf16 v[110:113], v[174:177], v[154:157], 0
	ds_read_b128 v[154:157], v216 offset:11264
	s_waitcnt lgkmcnt(7)
	v_mfma_f32_16x16x32_bf16 v[114:117], v[166:169], v[158:161], 0
	v_mfma_f32_16x16x32_bf16 v[118:121], v[174:177], v[158:161], 0
	ds_read_b128 v[158:161], v216 offset:13312
	s_waitcnt lgkmcnt(7)
	v_mfma_f32_16x16x32_bf16 v[122:125], v[166:169], v[162:165], 0
	v_mfma_f32_16x16x32_bf16 v[126:129], v[174:177], v[162:165], 0
	ds_read_b128 v[162:165], v216 offset:15360
	s_waitcnt lgkmcnt(7)
	v_mfma_f32_16x16x32_bf16 v[2:5], v[170:173], v[134:137], v[2:5]
	v_mfma_f32_16x16x32_bf16 v[6:9], v[178:181], v[134:137], v[6:9]
	ds_read_b128 v[134:137], v216 offset:17408
	s_waitcnt lgkmcnt(7)
	v_mfma_f32_16x16x32_bf16 v[10:13], v[170:173], v[138:141], v[10:13]
	v_mfma_f32_16x16x32_bf16 v[14:17], v[178:181], v[138:141], v[14:17]
	ds_read_b128 v[138:141], v216 offset:19456
	s_waitcnt lgkmcnt(7)
	v_mfma_f32_16x16x32_bf16 v[18:21], v[170:173], v[142:145], v[18:21]
	v_mfma_f32_16x16x32_bf16 v[22:25], v[178:181], v[142:145], v[22:25]
	ds_read_b128 v[142:145], v216 offset:21504
	s_waitcnt lgkmcnt(7)
	v_mfma_f32_16x16x32_bf16 v[26:29], v[170:173], v[146:149], v[26:29]
	v_mfma_f32_16x16x32_bf16 v[30:33], v[178:181], v[146:149], v[30:33]
	ds_read_b128 v[146:149], v216 offset:23552
	s_waitcnt lgkmcnt(7)
	v_mfma_f32_16x16x32_bf16 v[34:37], v[170:173], v[150:153], v[34:37]
	v_mfma_f32_16x16x32_bf16 v[38:41], v[178:181], v[150:153], v[38:41]
	ds_read_b128 v[150:153], v216 offset:25600
	s_waitcnt lgkmcnt(7)
	v_mfma_f32_16x16x32_bf16 v[42:45], v[170:173], v[154:157], v[42:45]
	v_mfma_f32_16x16x32_bf16 v[46:49], v[178:181], v[154:157], v[46:49]
	ds_read_b128 v[154:157], v216 offset:27648
	s_waitcnt lgkmcnt(7)
	v_mfma_f32_16x16x32_bf16 v[50:53], v[170:173], v[158:161], v[50:53]
	v_mfma_f32_16x16x32_bf16 v[54:57], v[178:181], v[158:161], v[54:57]
	ds_read_b128 v[158:161], v216 offset:29696
	s_waitcnt lgkmcnt(7)
	v_mfma_f32_16x16x32_bf16 v[58:61], v[170:173], v[162:165], v[58:61]
	v_mfma_f32_16x16x32_bf16 v[62:65], v[178:181], v[162:165], v[62:65]
	ds_read_b128 v[162:165], v216 offset:31744
	s_waitcnt vmcnt(12) lgkmcnt(0)
	s_barrier
	v_mfma_f32_16x16x32_bf16 v[66:69], v[170:173], v[134:137], v[66:69]
	s_add_u32 m0, s22, 0x0
	v_mov_b32_e32 v223, v217
	global_load_lds_dwordx4 v223, s[6:7]
	v_mfma_f32_16x16x32_bf16 v[70:73], v[178:181], v[134:137], v[70:73]
	s_add_u32 m0, s22, 0x400
	v_add_u32_e32 v224, 0x40, v217
	global_load_lds_dwordx4 v224, s[6:7]
	ds_read_b128 v[134:137], v216 offset:32768
	s_waitcnt lgkmcnt(7)
	v_mfma_f32_16x16x32_bf16 v[74:77], v[170:173], v[138:141], v[74:77]
	s_add_u32 m0, s22, 0x800
	v_add_u32_e32 v223, 0x20000, v217
	global_load_lds_dwordx4 v223, s[6:7]
	v_mfma_f32_16x16x32_bf16 v[78:81], v[178:181], v[138:141], v[78:81]
	s_add_u32 m0, s22, 0xc00
	v_add_u32_e32 v224, 0x20040, v217
	global_load_lds_dwordx4 v224, s[6:7]
	ds_read_b128 v[138:141], v216 offset:34816
	s_waitcnt lgkmcnt(7)
	v_mfma_f32_16x16x32_bf16 v[82:85], v[170:173], v[142:145], v[82:85]
	s_add_u32 m0, s22, 0x1000
	v_add_u32_e32 v223, 0x40000, v217
	global_load_lds_dwordx4 v223, s[6:7]
	v_mfma_f32_16x16x32_bf16 v[86:89], v[178:181], v[142:145], v[86:89]
	s_add_u32 m0, s22, 0x1400
	v_add_u32_e32 v224, 0x40040, v217
	global_load_lds_dwordx4 v224, s[6:7]
	ds_read_b128 v[142:145], v216 offset:36864
	s_waitcnt lgkmcnt(7)
	v_mfma_f32_16x16x32_bf16 v[90:93], v[170:173], v[146:149], v[90:93]
	s_add_u32 m0, s22, 0x1800
	v_add_u32_e32 v223, 0x60000, v217
	global_load_lds_dwordx4 v223, s[6:7]
	v_mfma_f32_16x16x32_bf16 v[94:97], v[178:181], v[146:149], v[94:97]
	s_add_u32 m0, s22, 0x1c00
	v_add_u32_e32 v224, 0x60040, v217
	global_load_lds_dwordx4 v224, s[6:7]
	ds_read_b128 v[146:149], v216 offset:38912
	s_waitcnt lgkmcnt(7)
	v_mfma_f32_16x16x32_bf16 v[98:101], v[170:173], v[150:153], v[98:101]
	v_mfma_f32_16x16x32_bf16 v[102:105], v[178:181], v[150:153], v[102:105]
	ds_read_b128 v[150:153], v216 offset:40960
	s_waitcnt lgkmcnt(7)
	v_mfma_f32_16x16x32_bf16 v[106:109], v[170:173], v[154:157], v[106:109]
	v_mfma_f32_16x16x32_bf16 v[110:113], v[178:181], v[154:157], v[110:113]
	ds_read_b128 v[154:157], v216 offset:43008
	s_waitcnt lgkmcnt(7)
	v_mfma_f32_16x16x32_bf16 v[114:117], v[170:173], v[158:161], v[114:117]
	v_mfma_f32_16x16x32_bf16 v[118:121], v[178:181], v[158:161], v[118:121]
	ds_read_b128 v[158:161], v216 offset:45056
	s_waitcnt lgkmcnt(7)
	v_mfma_f32_16x16x32_bf16 v[122:125], v[170:173], v[162:165], v[122:125]
	v_mfma_f32_16x16x32_bf16 v[126:129], v[178:181], v[162:165], v[126:129]
	v_add_u32_e32 v217, 0x80, v217
	v_add_u32_e32 v220, 0x800, v220
	v_add_u32_e32 v221, 0x800, v221
	ds_read_b128 v[162:165], v216 offset:47104
	s_waitcnt vmcnt(8) lgkmcnt(7)
	v_mfma_f32_16x16x32_bf16 v[2:5], v[196:199], v[134:137], v[2:5]
	v_mfma_f32_16x16x32_bf16 v[6:9], v[204:207], v[134:137], v[6:9]
	ds_read_b128 v[134:137], v216 offset:49152
	s_waitcnt lgkmcnt(7)
	v_mfma_f32_16x16x32_bf16 v[10:13], v[196:199], v[138:141], v[10:13]
	v_mfma_f32_16x16x32_bf16 v[14:17], v[204:207], v[138:141], v[14:17]
	ds_read_b128 v[138:141], v216 offset:51200
	s_waitcnt lgkmcnt(7)
	v_mfma_f32_16x16x32_bf16 v[18:21], v[196:199], v[142:145], v[18:21]
	v_mfma_f32_16x16x32_bf16 v[22:25], v[204:207], v[142:145], v[22:25]
	ds_read_b128 v[142:145], v216 offset:53248
	s_waitcnt lgkmcnt(7)
	v_mfma_f32_16x16x32_bf16 v[26:29], v[196:199], v[146:149], v[26:29]
	v_mfma_f32_16x16x32_bf16 v[30:33], v[204:207], v[146:149], v[30:33]
	ds_read_b128 v[146:149], v216 offset:55296
	s_waitcnt lgkmcnt(7)
	v_mfma_f32_16x16x32_bf16 v[34:37], v[196:199], v[150:153], v[34:37]
	global_load_dwordx4 v[166:169], v220, s[8:9]
	v_mfma_f32_16x16x32_bf16 v[38:41], v[204:207], v[150:153], v[38:41]
	ds_read_b128 v[150:153], v216 offset:57344
	s_waitcnt lgkmcnt(7)
	v_mfma_f32_16x16x32_bf16 v[42:45], v[196:199], v[154:157], v[42:45]
	global_load_dwordx4 v[170:173], v220, s[8:9] offset:1024
	v_mfma_f32_16x16x32_bf16 v[46:49], v[204:207], v[154:157], v[46:49]
	ds_read_b128 v[154:157], v216 offset:59392
	s_waitcnt lgkmcnt(7)
	v_mfma_f32_16x16x32_bf16 v[50:53], v[196:199], v[158:161], v[50:53]
	global_load_dwordx4 v[174:177], v221, s[8:9]
	v_mfma_f32_16x16x32_bf16 v[54:57], v[204:207], v[158:161], v[54:57]
	ds_read_b128 v[158:161], v216 offset:61440
	s_waitcnt lgkmcnt(7)
	v_mfma_f32_16x16x32_bf16 v[58:61], v[196:199], v[162:165], v[58:61]
	global_load_dwordx4 v[178:181], v221, s[8:9] offset:1024
	v_mfma_f32_16x16x32_bf16 v[62:65], v[204:207], v[162:165], v[62:65]
	ds_read_b128 v[162:165], v216 offset:63488
	s_waitcnt lgkmcnt(7)
	v_mfma_f32_16x16x32_bf16 v[66:69], v[196:199], v[134:137], v[66:69]
	v_mfma_f32_16x16x32_bf16 v[70:73], v[204:207], v[134:137], v[70:73]
	ds_read_b128 v[134:137], v216 offset:33792
	s_waitcnt lgkmcnt(7)
	v_mfma_f32_16x16x32_bf16 v[74:77], v[196:199], v[138:141], v[74:77]
	v_mfma_f32_16x16x32_bf16 v[78:81], v[204:207], v[138:141], v[78:81]
	ds_read_b128 v[138:141], v216 offset:35840
	s_waitcnt lgkmcnt(7)
	v_mfma_f32_16x16x32_bf16 v[82:85], v[196:199], v[142:145], v[82:85]
	v_mfma_f32_16x16x32_bf16 v[86:89], v[204:207], v[142:145], v[86:89]
	ds_read_b128 v[142:145], v216 offset:37888
	s_waitcnt lgkmcnt(7)
	v_mfma_f32_16x16x32_bf16 v[90:93], v[196:199], v[146:149], v[90:93]
	v_mfma_f32_16x16x32_bf16 v[94:97], v[204:207], v[146:149], v[94:97]
	ds_read_b128 v[146:149], v216 offset:39936
	s_waitcnt lgkmcnt(7)
	v_mfma_f32_16x16x32_bf16 v[98:101], v[196:199], v[150:153], v[98:101]
	v_mfma_f32_16x16x32_bf16 v[102:105], v[204:207], v[150:153], v[102:105]
	ds_read_b128 v[150:153], v216 offset:41984
	s_waitcnt lgkmcnt(7)
	v_mfma_f32_16x16x32_bf16 v[106:109], v[196:199], v[154:157], v[106:109]
	v_mfma_f32_16x16x32_bf16 v[110:113], v[204:207], v[154:157], v[110:113]
	ds_read_b128 v[154:157], v216 offset:44032
	s_waitcnt lgkmcnt(7)
	v_mfma_f32_16x16x32_bf16 v[114:117], v[196:199], v[158:161], v[114:117]
	v_mfma_f32_16x16x32_bf16 v[118:121], v[204:207], v[158:161], v[118:121]
	ds_read_b128 v[158:161], v216 offset:46080
	s_waitcnt lgkmcnt(7)
	v_mfma_f32_16x16x32_bf16 v[122:125], v[196:199], v[162:165], v[122:125]
	v_mfma_f32_16x16x32_bf16 v[126:129], v[204:207], v[162:165], v[126:129]
	ds_read_b128 v[162:165], v216 offset:48128
	s_waitcnt lgkmcnt(7)
	v_mfma_f32_16x16x32_bf16 v[2:5], v[200:203], v[134:137], v[2:5]
	v_mfma_f32_16x16x32_bf16 v[6:9], v[212:215], v[134:137], v[6:9]
	ds_read_b128 v[134:137], v216 offset:50176
	s_waitcnt lgkmcnt(7)
	v_mfma_f32_16x16x32_bf16 v[10:13], v[200:203], v[138:141], v[10:13]
	v_mfma_f32_16x16x32_bf16 v[14:17], v[212:215], v[138:141], v[14:17]
	ds_read_b128 v[138:141], v216 offset:52224
	s_waitcnt lgkmcnt(7)
	v_mfma_f32_16x16x32_bf16 v[18:21], v[200:203], v[142:145], v[18:21]
	v_mfma_f32_16x16x32_bf16 v[22:25], v[212:215], v[142:145], v[22:25]
	ds_read_b128 v[142:145], v216 offset:54272
	s_waitcnt lgkmcnt(7)
	v_mfma_f32_16x16x32_bf16 v[26:29], v[200:203], v[146:149], v[26:29]
	v_mfma_f32_16x16x32_bf16 v[30:33], v[212:215], v[146:149], v[30:33]
	ds_read_b128 v[146:149], v216 offset:56320
	s_waitcnt lgkmcnt(7)
	v_mfma_f32_16x16x32_bf16 v[34:37], v[200:203], v[150:153], v[34:37]
	v_mfma_f32_16x16x32_bf16 v[38:41], v[212:215], v[150:153], v[38:41]
	ds_read_b128 v[150:153], v216 offset:58368
	s_waitcnt lgkmcnt(7)
	v_mfma_f32_16x16x32_bf16 v[42:45], v[200:203], v[154:157], v[42:45]
	v_mfma_f32_16x16x32_bf16 v[46:49], v[212:215], v[154:157], v[46:49]
	ds_read_b128 v[154:157], v216 offset:60416
	s_waitcnt lgkmcnt(7)
	v_mfma_f32_16x16x32_bf16 v[50:53], v[200:203], v[158:161], v[50:53]
	v_mfma_f32_16x16x32_bf16 v[54:57], v[212:215], v[158:161], v[54:57]
	ds_read_b128 v[158:161], v216 offset:62464
	s_waitcnt lgkmcnt(7)
	v_mfma_f32_16x16x32_bf16 v[58:61], v[200:203], v[162:165], v[58:61]
	v_mfma_f32_16x16x32_bf16 v[62:65], v[212:215], v[162:165], v[62:65]
	ds_read_b128 v[162:165], v216 offset:64512
	s_waitcnt vmcnt(4) lgkmcnt(0)
	s_barrier
	v_mfma_f32_16x16x32_bf16 v[66:69], v[200:203], v[134:137], v[66:69]
	s_add_u32 m0, s22, 0x8000
	v_mov_b32_e32 v223, v217
	global_load_lds_dwordx4 v223, s[6:7]
	v_mfma_f32_16x16x32_bf16 v[70:73], v[212:215], v[134:137], v[70:73]
	s_add_u32 m0, s22, 0x8400
	v_add_u32_e32 v224, 0x40, v217
	global_load_lds_dwordx4 v224, s[6:7]
	ds_read_b128 v[134:137], v216
	s_waitcnt lgkmcnt(7)
	v_mfma_f32_16x16x32_bf16 v[74:77], v[200:203], v[138:141], v[74:77]
	s_add_u32 m0, s22, 0x8800
	v_add_u32_e32 v223, 0x20000, v217
	global_load_lds_dwordx4 v223, s[6:7]
	v_mfma_f32_16x16x32_bf16 v[78:81], v[212:215], v[138:141], v[78:81]
	s_add_u32 m0, s22, 0x8c00
	v_add_u32_e32 v224, 0x20040, v217
	global_load_lds_dwordx4 v224, s[6:7]
	ds_read_b128 v[138:141], v216 offset:2048
	s_waitcnt lgkmcnt(7)
	v_mfma_f32_16x16x32_bf16 v[82:85], v[200:203], v[142:145], v[82:85]
	s_add_u32 m0, s22, 0x9000
	v_add_u32_e32 v223, 0x40000, v217
	global_load_lds_dwordx4 v223, s[6:7]
	v_mfma_f32_16x16x32_bf16 v[86:89], v[212:215], v[142:145], v[86:89]
	s_add_u32 m0, s22, 0x9400
	v_add_u32_e32 v224, 0x40040, v217
	global_load_lds_dwordx4 v224, s[6:7]
	ds_read_b128 v[142:145], v216 offset:4096
	s_waitcnt lgkmcnt(7)
	v_mfma_f32_16x16x32_bf16 v[90:93], v[200:203], v[146:149], v[90:93]
	s_add_u32 m0, s22, 0x9800
	v_add_u32_e32 v223, 0x60000, v217
	global_load_lds_dwordx4 v223, s[6:7]
	v_mfma_f32_16x16x32_bf16 v[94:97], v[212:215], v[146:149], v[94:97]
	s_add_u32 m0, s22, 0x9c00
	v_add_u32_e32 v224, 0x60040, v217
	global_load_lds_dwordx4 v224, s[6:7]
	ds_read_b128 v[146:149], v216 offset:6144
	s_waitcnt lgkmcnt(7)
	v_mfma_f32_16x16x32_bf16 v[98:101], v[200:203], v[150:153], v[98:101]
	v_mfma_f32_16x16x32_bf16 v[102:105], v[212:215], v[150:153], v[102:105]
	ds_read_b128 v[150:153], v216 offset:8192
	s_waitcnt lgkmcnt(7)
	v_mfma_f32_16x16x32_bf16 v[106:109], v[200:203], v[154:157], v[106:109]
	v_mfma_f32_16x16x32_bf16 v[110:113], v[212:215], v[154:157], v[110:113]
	ds_read_b128 v[154:157], v216 offset:10240
	s_waitcnt lgkmcnt(7)
	v_mfma_f32_16x16x32_bf16 v[114:117], v[200:203], v[158:161], v[114:117]
	v_mfma_f32_16x16x32_bf16 v[118:121], v[212:215], v[158:161], v[118:121]
	ds_read_b128 v[158:161], v216 offset:12288
	s_waitcnt lgkmcnt(7)
	v_mfma_f32_16x16x32_bf16 v[122:125], v[200:203], v[162:165], v[122:125]
	v_mfma_f32_16x16x32_bf16 v[126:129], v[212:215], v[162:165], v[126:129]
	v_add_u32_e32 v217, 0x80, v217
	v_add_u32_e32 v220, 0x800, v220
	v_add_u32_e32 v221, 0x800, v221
	s_mov_b32 s16, 30
.Lg256b_w2_loop:
	ds_read_b128 v[162:165], v216 offset:14336
	s_waitcnt vmcnt(8) lgkmcnt(7)
	v_mfma_f32_16x16x32_bf16 v[2:5], v[166:169], v[134:137], v[2:5]
	v_mfma_f32_16x16x32_bf16 v[6:9], v[174:177], v[134:137], v[6:9]
	ds_read_b128 v[134:137], v216 offset:16384
	s_waitcnt lgkmcnt(7)
	v_mfma_f32_16x16x32_bf16 v[10:13], v[166:169], v[138:141], v[10:13]
	v_mfma_f32_16x16x32_bf16 v[14:17], v[174:177], v[138:141], v[14:17]
	ds_read_b128 v[138:141], v216 offset:18432
	s_waitcnt lgkmcnt(7)
	v_mfma_f32_16x16x32_bf16 v[18:21], v[166:169], v[142:145], v[18:21]
	v_mfma_f32_16x16x32_bf16 v[22:25], v[174:177], v[142:145], v[22:25]
	ds_read_b128 v[142:145], v216 offset:20480
	s_waitcnt lgkmcnt(7)
	v_mfma_f32_16x16x32_bf16 v[26:29], v[166:169], v[146:149], v[26:29]
	v_mfma_f32_16x16x32_bf16 v[30:33], v[174:177], v[146:149], v[30:33]
	ds_read_b128 v[146:149], v216 offset:22528
	s_waitcnt lgkmcnt(7)
	v_mfma_f32_16x16x32_bf16 v[34:37], v[166:169], v[150:153], v[34:37]
	global_load_dwordx4 v[196:199], v220, s[8:9]
	v_mfma_f32_16x16x32_bf16 v[38:41], v[174:177], v[150:153], v[38:41]
	ds_read_b128 v[150:153], v216 offset:24576
	s_waitcnt lgkmcnt(7)
	v_mfma_f32_16x16x32_bf16 v[42:45], v[166:169], v[154:157], v[42:45]
	global_load_dwordx4 v[200:203], v220, s[8:9] offset:1024
	v_mfma_f32_16x16x32_bf16 v[46:49], v[174:177], v[154:157], v[46:49]
	ds_read_b128 v[154:157], v216 offset:26624
	s_waitcnt lgkmcnt(7)
	v_mfma_f32_16x16x32_bf16 v[50:53], v[166:169], v[158:161], v[50:53]
	global_load_dwordx4 v[204:207], v221, s[8:9]
	v_mfma_f32_16x16x32_bf16 v[54:57], v[174:177], v[158:161], v[54:57]
	ds_read_b128 v[158:161], v216 offset:28672
	s_waitcnt lgkmcnt(7)
	v_mfma_f32_16x16x32_bf16 v[58:61], v[166:169], v[162:165], v[58:61]
	global_load_dwordx4 v[212:215], v221, s[8:9] offset:1024
	v_mfma_f32_16x16x32_bf16 v[62:65], v[174:177], v[162:165], v[62:65]
	ds_read_b128 v[162:165], v216 offset:30720
	s_waitcnt lgkmcnt(7)
	v_mfma_f32_16x16x32_bf16 v[66:69], v[166:169], v[134:137], v[66:69]
	v_mfma_f32_16x16x32_bf16 v[70:73], v[174:177], v[134:137], v[70:73]
	ds_read_b128 v[134:137], v216 offset:1024
	s_waitcnt lgkmcnt(7)
	v_mfma_f32_16x16x32_bf16 v[74:77], v[166:169], v[138:141], v[74:77]
	v_mfma_f32_16x16x32_bf16 v[78:81], v[174:177], v[138:141], v[78:81]
	ds_read_b128 v[138:141], v216 offset:3072
	s_waitcnt lgkmcnt(7)
	v_mfma_f32_16x16x32_bf16 v[82:85], v[166:169], v[142:145], v[82:85]
	v_mfma_f32_16x16x32_bf16 v[86:89], v[174:177], v[142:145], v[86:89]
	ds_read_b128 v[142:145], v216 offset:5120
	s_waitcnt lgkmcnt(7)
	v_mfma_f32_16x16x32_bf16 v[90:93], v[166:169], v[146:149], v[90:93]
	v_mfma_f32_16x16x32_bf16 v[94:97], v[174:177], v[146:149], v[94:97]
	ds_read_b128 v[146:149], v216 offset:7168
	s_waitcnt lgkmcnt(7)
	v_mfma_f32_16x16x32_bf16 v[98:101], v[166:169], v[150:153], v[98:101]
	v_mfma_f32_16x16x32_bf16 v[102:105], v[174:177], v[150:153], v[102:105]
	ds_read_b128 v[150:153], v216 offset:9216
	s_waitcnt lgkmcnt(7)
	v_mfma_f32_16x16x32_bf16 v[106:109], v[166:169], v[154:157], v[106:109]
	v_mfma_f32_16x16x32_bf16 v[110:113], v[174:177], v[154:157], v[110:113]
	ds_read_b128 v[154:157], v216 offset:11264
	s_waitcnt lgkmcnt(7)
	v_mfma_f32_16x16x32_bf16 v[114:117], v[166:169], v[158:161], v[114:117]
	v_mfma_f32_16x16x32_bf16 v[118:121], v[174:177], v[158:161], v[118:121]
	ds_read_b128 v[158:161], v216 offset:13312
	s_waitcnt lgkmcnt(7)
	v_mfma_f32_16x16x32_bf16 v[122:125], v[166:169], v[162:165], v[122:125]
	v_mfma_f32_16x16x32_bf16 v[126:129], v[174:177], v[162:165], v[126:129]
	ds_read_b128 v[162:165], v216 offset:15360
	s_waitcnt lgkmcnt(7)
	v_mfma_f32_16x16x32_bf16 v[2:5], v[170:173], v[134:137], v[2:5]
	v_mfma_f32_16x16x32_bf16 v[6:9], v[178:181], v[134:137], v[6:9]
	ds_read_b128 v[134:137], v216 offset:17408
	s_waitcnt lgkmcnt(7)
	v_mfma_f32_16x16x32_bf16 v[10:13], v[170:173], v[138:141], v[10:13]
	v_mfma_f32_16x16x32_bf16 v[14:17], v[178:181], v[138:141], v[14:17]
	ds_read_b128 v[138:141], v216 offset:19456
	s_waitcnt lgkmcnt(7)
	v_mfma_f32_16x16x32_bf16 v[18:21], v[170:173], v[142:145], v[18:21]
	v_mfma_f32_16x16x32_bf16 v[22:25], v[178:181], v[142:145], v[22:25]
	ds_read_b128 v[142:145], v216 offset:21504
	s_waitcnt lgkmcnt(7)
	v_mfma_f32_16x16x32_bf16 v[26:29], v[170:173], v[146:149], v[26:29]
	v_mfma_f32_16x16x32_bf16 v[30:33], v[178:181], v[146:149], v[30:33]
	ds_read_b128 v[146:149], v216 offset:23552
	s_waitcnt lgkmcnt(7)
	v_mfma_f32_16x16x32_bf16 v[34:37], v[170:173], v[150:153], v[34:37]
	v_mfma_f32_16x16x32_bf16 v[38:41], v[178:181], v[150:153], v[38:41]
	ds_read_b128 v[150:153], v216 offset:25600
	s_waitcnt lgkmcnt(7)
	v_mfma_f32_16x16x32_bf16 v[42:45], v[170:173], v[154:157], v[42:45]
	v_mfma_f32_16x16x32_bf16 v[46:49], v[178:181], v[154:157], v[46:49]
	ds_read_b128 v[154:157], v216 offset:27648
	s_waitcnt lgkmcnt(7)
	v_mfma_f32_16x16x32_bf16 v[50:53], v[170:173], v[158:161], v[50:53]
	v_mfma_f32_16x16x32_bf16 v[54:57], v[178:181], v[158:161], v[54:57]
	ds_read_b128 v[158:161], v216 offset:29696
	s_waitcnt lgkmcnt(7)
	v_mfma_f32_16x16x32_bf16 v[58:61], v[170:173], v[162:165], v[58:61]
	v_mfma_f32_16x16x32_bf16 v[62:65], v[178:181], v[162:165], v[62:65]
	ds_read_b128 v[162:165], v216 offset:31744
	s_waitcnt vmcnt(4) lgkmcnt(0)
	s_barrier
	v_mfma_f32_16x16x32_bf16 v[66:69], v[170:173], v[134:137], v[66:69]
	s_add_u32 m0, s22, 0x0
	v_mov_b32_e32 v223, v217
	global_load_lds_dwordx4 v223, s[6:7]
	v_mfma_f32_16x16x32_bf16 v[70:73], v[178:181], v[134:137], v[70:73]
	s_add_u32 m0, s22, 0x400
	v_add_u32_e32 v224, 0x40, v217
	global_load_lds_dwordx4 v224, s[6:7]
	ds_read_b128 v[134:137], v216 offset:32768
	s_waitcnt lgkmcnt(7)
	v_mfma_f32_16x16x32_bf16 v[74:77], v[170:173], v[138:141], v[74:77]
	s_add_u32 m0, s22, 0x800
	v_add_u32_e32 v223, 0x20000, v217
	global_load_lds_dwordx4 v223, s[6:7]
	v_mfma_f32_16x16x32_bf16 v[78:81], v[178:181], v[138:141], v[78:81]
	s_add_u32 m0, s22, 0xc00
	v_add_u32_e32 v224, 0x20040, v217
	global_load_lds_dwordx4 v224, s[6:7]
	ds_read_b128 v[138:141], v216 offset:34816
	s_waitcnt lgkmcnt(7)
	v_mfma_f32_16x16x32_bf16 v[82:85], v[170:173], v[142:145], v[82:85]
	s_add_u32 m0, s22, 0x1000
	v_add_u32_e32 v223, 0x40000, v217
	global_load_lds_dwordx4 v223, s[6:7]
	v_mfma_f32_16x16x32_bf16 v[86:89], v[178:181], v[142:145], v[86:89]
	s_add_u32 m0, s22, 0x1400
	v_add_u32_e32 v224, 0x40040, v217
	global_load_lds_dwordx4 v224, s[6:7]
	ds_read_b128 v[142:145], v216 offset:36864
	s_waitcnt lgkmcnt(7)
	v_mfma_f32_16x16x32_bf16 v[90:93], v[170:173], v[146:149], v[90:93]
	s_add_u32 m0, s22, 0x1800
	v_add_u32_e32 v223, 0x60000, v217
	global_load_lds_dwordx4 v223, s[6:7]
	v_mfma_f32_16x16x32_bf16 v[94:97], v[178:181], v[146:149], v[94:97]
	s_add_u32 m0, s22, 0x1c00
	v_add_u32_e32 v224, 0x60040, v217
	global_load_lds_dwordx4 v224, s[6:7]
	ds_read_b128 v[146:149], v216 offset:38912
	s_waitcnt lgkmcnt(7)
	v_mfma_f32_16x16x32_bf16 v[98:101], v[170:173], v[150:153], v[98:101]
	v_mfma_f32_16x16x32_bf16 v[102:105], v[178:181], v[150:153], v[102:105]
	ds_read_b128 v[150:153], v216 offset:40960
	s_waitcnt lgkmcnt(7)
	v_mfma_f32_16x16x32_bf16 v[106:109], v[170:173], v[154:157], v[106:109]
	v_mfma_f32_16x16x32_bf16 v[110:113], v[178:181], v[154:157], v[110:113]
	ds_read_b128 v[154:157], v216 offset:43008
	s_waitcnt lgkmcnt(7)
	v_mfma_f32_16x16x32_bf16 v[114:117], v[170:173], v[158:161], v[114:117]
	v_mfma_f32_16x16x32_bf16 v[118:121], v[178:181], v[158:161], v[118:121]
	ds_read_b128 v[158:161], v216 offset:45056
	s_waitcnt lgkmcnt(7)
	v_mfma_f32_16x16x32_bf16 v[122:125], v[170:173], v[162:165], v[122:125]
	v_mfma_f32_16x16x32_bf16 v[126:129], v[178:181], v[162:165], v[126:129]
	v_add_u32_e32 v217, 0x80, v217
	v_add_u32_e32 v220, 0x800, v220
	v_add_u32_e32 v221, 0x800, v221
	ds_read_b128 v[162:165], v216 offset:47104
	s_waitcnt vmcnt(8) lgkmcnt(7)
	v_mfma_f32_16x16x32_bf16 v[2:5], v[196:199], v[134:137], v[2:5]
	v_mfma_f32_16x16x32_bf16 v[6:9], v[204:207], v[134:137], v[6:9]
	ds_read_b128 v[134:137], v216 offset:49152
	s_waitcnt lgkmcnt(7)
	v_mfma_f32_16x16x32_bf16 v[10:13], v[196:199], v[138:141], v[10:13]
	v_mfma_f32_16x16x32_bf16 v[14:17], v[204:207], v[138:141], v[14:17]
	ds_read_b128 v[138:141], v216 offset:51200
	s_waitcnt lgkmcnt(7)
	v_mfma_f32_16x16x32_bf16 v[18:21], v[196:199], v[142:145], v[18:21]
	v_mfma_f32_16x16x32_bf16 v[22:25], v[204:207], v[142:145], v[22:25]
	ds_read_b128 v[142:145], v216 offset:53248
	s_waitcnt lgkmcnt(7)
	v_mfma_f32_16x16x32_bf16 v[26:29], v[196:199], v[146:149], v[26:29]
	v_mfma_f32_16x16x32_bf16 v[30:33], v[204:207], v[146:149], v[30:33]
	ds_read_b128 v[146:149], v216 offset:55296
	s_waitcnt lgkmcnt(7)
	v_mfma_f32_16x16x32_bf16 v[34:37], v[196:199], v[150:153], v[34:37]
	global_load_dwordx4 v[166:169], v220, s[8:9]
	v_mfma_f32_16x16x32_bf16 v[38:41], v[204:207], v[150:153], v[38:41]
	ds_read_b128 v[150:153], v216 offset:57344
	s_waitcnt lgkmcnt(7)
	v_mfma_f32_16x16x32_bf16 v[42:45], v[196:199], v[154:157], v[42:45]
	global_load_dwordx4 v[170:173], v220, s[8:9] offset:1024
	v_mfma_f32_16x16x32_bf16 v[46:49], v[204:207], v[154:157], v[46:49]
	ds_read_b128 v[154:157], v216 offset:59392
	s_waitcnt lgkmcnt(7)
	v_mfma_f32_16x16x32_bf16 v[50:53], v[196:199], v[158:161], v[50:53]
	global_load_dwordx4 v[174:177], v221, s[8:9]
	v_mfma_f32_16x16x32_bf16 v[54:57], v[204:207], v[158:161], v[54:57]
	ds_read_b128 v[158:161], v216 offset:61440
	s_waitcnt lgkmcnt(7)
	v_mfma_f32_16x16x32_bf16 v[58:61], v[196:199], v[162:165], v[58:61]
	global_load_dwordx4 v[178:181], v221, s[8:9] offset:1024
	v_mfma_f32_16x16x32_bf16 v[62:65], v[204:207], v[162:165], v[62:65]
	ds_read_b128 v[162:165], v216 offset:63488
	s_waitcnt lgkmcnt(7)
	v_mfma_f32_16x16x32_bf16 v[66:69], v[196:199], v[134:137], v[66:69]
	v_mfma_f32_16x16x32_bf16 v[70:73], v[204:207], v[134:137], v[70:73]
	ds_read_b128 v[134:137], v216 offset:33792
	s_waitcnt lgkmcnt(7)
	v_mfma_f32_16x16x32_bf16 v[74:77], v[196:199], v[138:141], v[74:77]
	v_mfma_f32_16x16x32_bf16 v[78:81], v[204:207], v[138:141], v[78:81]
	ds_read_b128 v[138:141], v216 offset:35840
	s_waitcnt lgkmcnt(7)
	v_mfma_f32_16x16x32_bf16 v[82:85], v[196:199], v[142:145], v[82:85]
	v_mfma_f32_16x16x32_bf16 v[86:89], v[204:207], v[142:145], v[86:89]
	ds_read_b128 v[142:145], v216 offset:37888
	s_waitcnt lgkmcnt(7)
	v_mfma_f32_16x16x32_bf16 v[90:93], v[196:199], v[146:149], v[90:93]
	v_mfma_f32_16x16x32_bf16 v[94:97], v[204:207], v[146:149], v[94:97]
	ds_read_b128 v[146:149], v216 offset:39936
	s_waitcnt lgkmcnt(7)
	v_mfma_f32_16x16x32_bf16 v[98:101], v[196:199], v[150:153], v[98:101]
	v_mfma_f32_16x16x32_bf16 v[102:105], v[204:207], v[150:153], v[102:105]
	ds_read_b128 v[150:153], v216 offset:41984
	s_waitcnt lgkmcnt(7)
	v_mfma_f32_16x16x32_bf16 v[106:109], v[196:199], v[154:157], v[106:109]
	v_mfma_f32_16x16x32_bf16 v[110:113], v[204:207], v[154:157], v[110:113]
	ds_read_b128 v[154:157], v216 offset:44032
	s_waitcnt lgkmcnt(7)
	v_mfma_f32_16x16x32_bf16 v[114:117], v[196:199], v[158:161], v[114:117]
	v_mfma_f32_16x16x32_bf16 v[118:121], v[204:207], v[158:161], v[118:121]
	ds_read_b128 v[158:161], v216 offset:46080
	s_waitcnt lgkmcnt(7)
	v_mfma_f32_16x16x32_bf16 v[122:125], v[196:199], v[162:165], v[122:125]
	v_mfma_f32_16x16x32_bf16 v[126:129], v[204:207], v[162:165], v[126:129]
	ds_read_b128 v[162:165], v216 offset:48128
	s_waitcnt lgkmcnt(7)
	v_mfma_f32_16x16x32_bf16 v[2:5], v[200:203], v[134:137], v[2:5]
	v_mfma_f32_16x16x32_bf16 v[6:9], v[212:215], v[134:137], v[6:9]
	ds_read_b128 v[134:137], v216 offset:50176
	s_waitcnt lgkmcnt(7)
	v_mfma_f32_16x16x32_bf16 v[10:13], v[200:203], v[138:141], v[10:13]
	v_mfma_f32_16x16x32_bf16 v[14:17], v[212:215], v[138:141], v[14:17]
	ds_read_b128 v[138:141], v216 offset:52224
	s_waitcnt lgkmcnt(7)
	v_mfma_f32_16x16x32_bf16 v[18:21], v[200:203], v[142:145], v[18:21]
	v_mfma_f32_16x16x32_bf16 v[22:25], v[212:215], v[142:145], v[22:25]
	ds_read_b128 v[142:145], v216 offset:54272
	s_waitcnt lgkmcnt(7)
	v_mfma_f32_16x16x32_bf16 v[26:29], v[200:203], v[146:149], v[26:29]
	v_mfma_f32_16x16x32_bf16 v[30:33], v[212:215], v[146:149], v[30:33]
	ds_read_b128 v[146:149], v216 offset:56320
	s_waitcnt lgkmcnt(7)
	v_mfma_f32_16x16x32_bf16 v[34:37], v[200:203], v[150:153], v[34:37]
	v_mfma_f32_16x16x32_bf16 v[38:41], v[212:215], v[150:153], v[38:41]
	ds_read_b128 v[150:153], v216 offset:58368
	s_waitcnt lgkmcnt(7)
	v_mfma_f32_16x16x32_bf16 v[42:45], v[200:203], v[154:157], v[42:45]
	v_mfma_f32_16x16x32_bf16 v[46:49], v[212:215], v[154:157], v[46:49]
	ds_read_b128 v[154:157], v216 offset:60416
	s_waitcnt lgkmcnt(7)
	v_mfma_f32_16x16x32_bf16 v[50:53], v[200:203], v[158:161], v[50:53]
	v_mfma_f32_16x16x32_bf16 v[54:57], v[212:215], v[158:161], v[54:57]
	ds_read_b128 v[158:161], v216 offset:62464
	s_waitcnt lgkmcnt(7)
	v_mfma_f32_16x16x32_bf16 v[58:61], v[200:203], v[162:165], v[58:61]
	v_mfma_f32_16x16x32_bf16 v[62:65], v[212:215], v[162:165], v[62:65]
	ds_read_b128 v[162:165], v216 offset:64512
	s_waitcnt vmcnt(4) lgkmcnt(0)
	s_barrier
	v_mfma_f32_16x16x32_bf16 v[66:69], v[200:203], v[134:137], v[66:69]
	s_add_u32 m0, s22, 0x8000
	v_mov_b32_e32 v223, v217
	global_load_lds_dwordx4 v223, s[6:7]
	v_mfma_f32_16x16x32_bf16 v[70:73], v[212:215], v[134:137], v[70:73]
	s_add_u32 m0, s22, 0x8400
	v_add_u32_e32 v224, 0x40, v217
	global_load_lds_dwordx4 v224, s[6:7]
	ds_read_b128 v[134:137], v216
	s_waitcnt lgkmcnt(7)
	v_mfma_f32_16x16x32_bf16 v[74:77], v[200:203], v[138:141], v[74:77]
	s_add_u32 m0, s22, 0x8800
	v_add_u32_e32 v223, 0x20000, v217
	global_load_lds_dwordx4 v223, s[6:7]
	v_mfma_f32_16x16x32_bf16 v[78:81], v[212:215], v[138:141], v[78:81]
	s_add_u32 m0, s22, 0x8c00
	v_add_u32_e32 v224, 0x20040, v217
	global_load_lds_dwordx4 v224, s[6:7]
	ds_read_b128 v[138:141], v216 offset:2048
	s_waitcnt lgkmcnt(7)
	v_mfma_f32_16x16x32_bf16 v[82:85], v[200:203], v[142:145], v[82:85]
	s_add_u32 m0, s22, 0x9000
	v_add_u32_e32 v223, 0x40000, v217
	global_load_lds_dwordx4 v223, s[6:7]
	v_mfma_f32_16x16x32_bf16 v[86:89], v[212:215], v[142:145], v[86:89]
	s_add_u32 m0, s22, 0x9400
	v_add_u32_e32 v224, 0x40040, v217
	global_load_lds_dwordx4 v224, s[6:7]
	ds_read_b128 v[142:145], v216 offset:4096
	s_waitcnt lgkmcnt(7)
	v_mfma_f32_16x16x32_bf16 v[90:93], v[200:203], v[146:149], v[90:93]
	s_add_u32 m0, s22, 0x9800
	v_add_u32_e32 v223, 0x60000, v217
	global_load_lds_dwordx4 v223, s[6:7]
	v_mfma_f32_16x16x32_bf16 v[94:97], v[212:215], v[146:149], v[94:97]
	s_add_u32 m0, s22, 0x9c00
	v_add_u32_e32 v224, 0x60040, v217
	global_load_lds_dwordx4 v224, s[6:7]
	ds_read_b128 v[146:149], v216 offset:6144
	s_waitcnt lgkmcnt(7)
	v_mfma_f32_16x16x32_bf16 v[98:101], v[200:203], v[150:153], v[98:101]
	v_mfma_f32_16x16x32_bf16 v[102:105], v[212:215], v[150:153], v[102:105]
	ds_read_b128 v[150:153], v216 offset:8192
	s_waitcnt lgkmcnt(7)
	v_mfma_f32_16x16x32_bf16 v[106:109], v[200:203], v[154:157], v[106:109]
	v_mfma_f32_16x16x32_bf16 v[110:113], v[212:215], v[154:157], v[110:113]
	ds_read_b128 v[154:157], v216 offset:10240
	s_waitcnt lgkmcnt(7)
	v_mfma_f32_16x16x32_bf16 v[114:117], v[200:203], v[158:161], v[114:117]
	v_mfma_f32_16x16x32_bf16 v[118:121], v[212:215], v[158:161], v[118:121]
	ds_read_b128 v[158:161], v216 offset:12288
	s_waitcnt lgkmcnt(7)
	v_mfma_f32_16x16x32_bf16 v[122:125], v[200:203], v[162:165], v[122:125]
	v_mfma_f32_16x16x32_bf16 v[126:129], v[212:215], v[162:165], v[126:129]
	v_add_u32_e32 v217, 0x80, v217
	v_add_u32_e32 v220, 0x800, v220
	v_add_u32_e32 v221, 0x800, v221
	s_sub_u32 s16, s16, 1
	s_cmp_lg_u32 s16, 0
	s_cbranch_scc1 .Lg256b_w2_loop
	s_add_u32 s12, s12, s83
.Lg256b_w2_next_retry:
	s_cmp_ge_u32 s12, 64
	s_cbranch_scc1 .Lg256b_w2_nonext
	s_lshr_b32 s3, s12, 6
	s_lshl_b32 s3, s3, 3
	s_add_u32 s3, s3, s65
	s_mov_b32 s17, s3
	s_mov_b32 s3, 0
	s_lshl_b32 s17, s17, 3
	s_bfe_u32 s23, s12, 0x30003
	s_add_u32 s13, s17, s23
	s_lshl_b32 s3, s3, 3
	s_and_b32 s23, s12, 7
	s_add_u32 s14, s3, s23
	s_lshl_b32 s13, s13, 8
	s_lshl_b32 s14, s14, 7
	s_lshl_b32 s3, s15, 6
	s_add_u32 s17, s3, s13
	s_mul_i32 s17, s17, 0x2000
	s_add_u32 s6, s18, s17
	s_addc_u32 s7, s19, 0
	v_mov_b32_e32 v217, v218
	ds_read_b128 v[162:165], v216 offset:14336
	s_waitcnt vmcnt(8) lgkmcnt(7)
	v_mfma_f32_16x16x32_bf16 v[2:5], v[166:169], v[134:137], v[2:5]
	v_mfma_f32_16x16x32_bf16 v[6:9], v[174:177], v[134:137], v[6:9]
	ds_read_b128 v[134:137], v216 offset:16384
	s_waitcnt lgkmcnt(7)
	v_mfma_f32_16x16x32_bf16 v[10:13], v[166:169], v[138:141], v[10:13]
	v_mfma_f32_16x16x32_bf16 v[14:17], v[174:177], v[138:141], v[14:17]
	ds_read_b128 v[138:141], v216 offset:18432
	s_waitcnt lgkmcnt(7)
	v_mfma_f32_16x16x32_bf16 v[18:21], v[166:169], v[142:145], v[18:21]
	v_mfma_f32_16x16x32_bf16 v[22:25], v[174:177], v[142:145], v[22:25]
	ds_read_b128 v[142:145], v216 offset:20480
	s_waitcnt lgkmcnt(7)
	v_mfma_f32_16x16x32_bf16 v[26:29], v[166:169], v[146:149], v[26:29]
	v_mfma_f32_16x16x32_bf16 v[30:33], v[174:177], v[146:149], v[30:33]
	ds_read_b128 v[146:149], v216 offset:22528
	s_waitcnt lgkmcnt(7)
	v_mfma_f32_16x16x32_bf16 v[34:37], v[166:169], v[150:153], v[34:37]
	global_load_dwordx4 v[196:199], v220, s[8:9]
	v_mfma_f32_16x16x32_bf16 v[38:41], v[174:177], v[150:153], v[38:41]
	ds_read_b128 v[150:153], v216 offset:24576
	s_waitcnt lgkmcnt(7)
	v_mfma_f32_16x16x32_bf16 v[42:45], v[166:169], v[154:157], v[42:45]
	global_load_dwordx4 v[200:203], v220, s[8:9] offset:1024
	v_mfma_f32_16x16x32_bf16 v[46:49], v[174:177], v[154:157], v[46:49]
	ds_read_b128 v[154:157], v216 offset:26624
	s_waitcnt lgkmcnt(7)
	v_mfma_f32_16x16x32_bf16 v[50:53], v[166:169], v[158:161], v[50:53]
	global_load_dwordx4 v[204:207], v221, s[8:9]
	v_mfma_f32_16x16x32_bf16 v[54:57], v[174:177], v[158:161], v[54:57]
	ds_read_b128 v[158:161], v216 offset:28672
	s_waitcnt lgkmcnt(7)
	v_mfma_f32_16x16x32_bf16 v[58:61], v[166:169], v[162:165], v[58:61]
	global_load_dwordx4 v[212:215], v221, s[8:9] offset:1024
	v_mfma_f32_16x16x32_bf16 v[62:65], v[174:177], v[162:165], v[62:65]
	ds_read_b128 v[162:165], v216 offset:30720
	s_waitcnt lgkmcnt(7)
	v_mfma_f32_16x16x32_bf16 v[66:69], v[166:169], v[134:137], v[66:69]
	v_mfma_f32_16x16x32_bf16 v[70:73], v[174:177], v[134:137], v[70:73]
	ds_read_b128 v[134:137], v216 offset:1024
	s_waitcnt lgkmcnt(7)
	v_mfma_f32_16x16x32_bf16 v[74:77], v[166:169], v[138:141], v[74:77]
	v_mfma_f32_16x16x32_bf16 v[78:81], v[174:177], v[138:141], v[78:81]
	ds_read_b128 v[138:141], v216 offset:3072
	s_waitcnt lgkmcnt(7)
	v_mfma_f32_16x16x32_bf16 v[82:85], v[166:169], v[142:145], v[82:85]
	v_mfma_f32_16x16x32_bf16 v[86:89], v[174:177], v[142:145], v[86:89]
	ds_read_b128 v[142:145], v216 offset:5120
	s_waitcnt lgkmcnt(7)
	v_mfma_f32_16x16x32_bf16 v[90:93], v[166:169], v[146:149], v[90:93]
	v_mfma_f32_16x16x32_bf16 v[94:97], v[174:177], v[146:149], v[94:97]
	ds_read_b128 v[146:149], v216 offset:7168
	s_waitcnt lgkmcnt(7)
	v_mfma_f32_16x16x32_bf16 v[98:101], v[166:169], v[150:153], v[98:101]
	v_mfma_f32_16x16x32_bf16 v[102:105], v[174:177], v[150:153], v[102:105]
	ds_read_b128 v[150:153], v216 offset:9216
	s_waitcnt lgkmcnt(7)
	v_mfma_f32_16x16x32_bf16 v[106:109], v[166:169], v[154:157], v[106:109]
	v_mfma_f32_16x16x32_bf16 v[110:113], v[174:177], v[154:157], v[110:113]
	ds_read_b128 v[154:157], v216 offset:11264
	s_waitcnt lgkmcnt(7)
	v_mfma_f32_16x16x32_bf16 v[114:117], v[166:169], v[158:161], v[114:117]
	v_mfma_f32_16x16x32_bf16 v[118:121], v[174:177], v[158:161], v[118:121]
	ds_read_b128 v[158:161], v216 offset:13312
	s_waitcnt lgkmcnt(7)
	v_mfma_f32_16x16x32_bf16 v[122:125], v[166:169], v[162:165], v[122:125]
	v_mfma_f32_16x16x32_bf16 v[126:129], v[174:177], v[162:165], v[126:129]
	ds_read_b128 v[162:165], v216 offset:15360
	s_waitcnt lgkmcnt(7)
	v_mfma_f32_16x16x32_bf16 v[2:5], v[170:173], v[134:137], v[2:5]
	v_mfma_f32_16x16x32_bf16 v[6:9], v[178:181], v[134:137], v[6:9]
	ds_read_b128 v[134:137], v216 offset:17408
	s_waitcnt lgkmcnt(7)
	v_mfma_f32_16x16x32_bf16 v[10:13], v[170:173], v[138:141], v[10:13]
	v_mfma_f32_16x16x32_bf16 v[14:17], v[178:181], v[138:141], v[14:17]
	ds_read_b128 v[138:141], v216 offset:19456
	s_waitcnt lgkmcnt(7)
	v_mfma_f32_16x16x32_bf16 v[18:21], v[170:173], v[142:145], v[18:21]
	v_mfma_f32_16x16x32_bf16 v[22:25], v[178:181], v[142:145], v[22:25]
	ds_read_b128 v[142:145], v216 offset:21504
	s_waitcnt lgkmcnt(7)
	v_mfma_f32_16x16x32_bf16 v[26:29], v[170:173], v[146:149], v[26:29]
	v_mfma_f32_16x16x32_bf16 v[30:33], v[178:181], v[146:149], v[30:33]
	ds_read_b128 v[146:149], v216 offset:23552
	s_waitcnt lgkmcnt(7)
	v_mfma_f32_16x16x32_bf16 v[34:37], v[170:173], v[150:153], v[34:37]
	v_mfma_f32_16x16x32_bf16 v[38:41], v[178:181], v[150:153], v[38:41]
	ds_read_b128 v[150:153], v216 offset:25600
	s_waitcnt lgkmcnt(7)
	v_mfma_f32_16x16x32_bf16 v[42:45], v[170:173], v[154:157], v[42:45]
	v_mfma_f32_16x16x32_bf16 v[46:49], v[178:181], v[154:157], v[46:49]
	ds_read_b128 v[154:157], v216 offset:27648
	s_waitcnt lgkmcnt(7)
	v_mfma_f32_16x16x32_bf16 v[50:53], v[170:173], v[158:161], v[50:53]
	v_mfma_f32_16x16x32_bf16 v[54:57], v[178:181], v[158:161], v[54:57]
	ds_read_b128 v[158:161], v216 offset:29696
	s_waitcnt lgkmcnt(7)
	v_mfma_f32_16x16x32_bf16 v[58:61], v[170:173], v[162:165], v[58:61]
	v_mfma_f32_16x16x32_bf16 v[62:65], v[178:181], v[162:165], v[62:65]
	ds_read_b128 v[162:165], v216 offset:31744
	s_waitcnt vmcnt(4) lgkmcnt(0)
	s_barrier
	v_mfma_f32_16x16x32_bf16 v[66:69], v[170:173], v[134:137], v[66:69]
	s_add_u32 m0, s22, 0x0
	v_mov_b32_e32 v223, v217
	global_load_lds_dwordx4 v223, s[6:7]
	v_mfma_f32_16x16x32_bf16 v[70:73], v[178:181], v[134:137], v[70:73]
	s_add_u32 m0, s22, 0x400
	v_add_u32_e32 v224, 0x40, v217
	global_load_lds_dwordx4 v224, s[6:7]
	ds_read_b128 v[134:137], v216 offset:32768
	s_waitcnt lgkmcnt(7)
	v_mfma_f32_16x16x32_bf16 v[74:77], v[170:173], v[138:141], v[74:77]
	s_add_u32 m0, s22, 0x800
	v_add_u32_e32 v223, 0x20000, v217
	global_load_lds_dwordx4 v223, s[6:7]
	v_mfma_f32_16x16x32_bf16 v[78:81], v[178:181], v[138:141], v[78:81]
	s_add_u32 m0, s22, 0xc00
	v_add_u32_e32 v224, 0x20040, v217
	global_load_lds_dwordx4 v224, s[6:7]
	ds_read_b128 v[138:141], v216 offset:34816
	s_waitcnt lgkmcnt(7)
	v_mfma_f32_16x16x32_bf16 v[82:85], v[170:173], v[142:145], v[82:85]
	s_add_u32 m0, s22, 0x1000
	v_add_u32_e32 v223, 0x40000, v217
	global_load_lds_dwordx4 v223, s[6:7]
	v_mfma_f32_16x16x32_bf16 v[86:89], v[178:181], v[142:145], v[86:89]
	s_add_u32 m0, s22, 0x1400
	v_add_u32_e32 v224, 0x40040, v217
	global_load_lds_dwordx4 v224, s[6:7]
	ds_read_b128 v[142:145], v216 offset:36864
	s_waitcnt lgkmcnt(7)
	v_mfma_f32_16x16x32_bf16 v[90:93], v[170:173], v[146:149], v[90:93]
	s_add_u32 m0, s22, 0x1800
	v_add_u32_e32 v223, 0x60000, v217
	global_load_lds_dwordx4 v223, s[6:7]
	v_mfma_f32_16x16x32_bf16 v[94:97], v[178:181], v[146:149], v[94:97]
	s_add_u32 m0, s22, 0x1c00
	v_add_u32_e32 v224, 0x60040, v217
	global_load_lds_dwordx4 v224, s[6:7]
	ds_read_b128 v[146:149], v216 offset:38912
	s_waitcnt lgkmcnt(7)
	v_mfma_f32_16x16x32_bf16 v[98:101], v[170:173], v[150:153], v[98:101]
	v_mfma_f32_16x16x32_bf16 v[102:105], v[178:181], v[150:153], v[102:105]
	ds_read_b128 v[150:153], v216 offset:40960
	s_waitcnt lgkmcnt(7)
	v_mfma_f32_16x16x32_bf16 v[106:109], v[170:173], v[154:157], v[106:109]
	v_mfma_f32_16x16x32_bf16 v[110:113], v[178:181], v[154:157], v[110:113]
	ds_read_b128 v[154:157], v216 offset:43008
	s_waitcnt lgkmcnt(7)
	v_mfma_f32_16x16x32_bf16 v[114:117], v[170:173], v[158:161], v[114:117]
	v_mfma_f32_16x16x32_bf16 v[118:121], v[178:181], v[158:161], v[118:121]
	ds_read_b128 v[158:161], v216 offset:45056
	s_waitcnt lgkmcnt(7)
	v_mfma_f32_16x16x32_bf16 v[122:125], v[170:173], v[162:165], v[122:125]
	v_mfma_f32_16x16x32_bf16 v[126:129], v[178:181], v[162:165], v[126:129]
	v_add_u32_e32 v217, 0x80, v217
	v_add_u32_e32 v220, 0x800, v220
	v_add_u32_e32 v221, 0x800, v221
	s_lshr_b32 s3, s14, 4
	s_lshl_b32 s17, s15, 1
	s_add_u32 s3, s3, s17
	s_mul_i32 s17, s3, 0x20000
	s_add_u32 s8, s20, s17
	s_addc_u32 s9, s21, 0
	v_mov_b32_e32 v220, v222
	v_add_u32_e32 v221, 0x20000, v222
	ds_read_b128 v[162:165], v216 offset:47104
	s_waitcnt vmcnt(8) lgkmcnt(7)
	v_mfma_f32_16x16x32_bf16 v[2:5], v[196:199], v[134:137], v[2:5]
	v_mfma_f32_16x16x32_bf16 v[6:9], v[204:207], v[134:137], v[6:9]
	ds_read_b128 v[134:137], v216 offset:49152
	s_waitcnt lgkmcnt(7)
	v_mfma_f32_16x16x32_bf16 v[10:13], v[196:199], v[138:141], v[10:13]
	v_mfma_f32_16x16x32_bf16 v[14:17], v[204:207], v[138:141], v[14:17]
	ds_read_b128 v[138:141], v216 offset:51200
	s_waitcnt lgkmcnt(7)
	v_mfma_f32_16x16x32_bf16 v[18:21], v[196:199], v[142:145], v[18:21]
	v_mfma_f32_16x16x32_bf16 v[22:25], v[204:207], v[142:145], v[22:25]
	ds_read_b128 v[142:145], v216 offset:53248
	s_waitcnt lgkmcnt(7)
	v_mfma_f32_16x16x32_bf16 v[26:29], v[196:199], v[146:149], v[26:29]
	v_mfma_f32_16x16x32_bf16 v[30:33], v[204:207], v[146:149], v[30:33]
	ds_read_b128 v[146:149], v216 offset:55296
	s_waitcnt lgkmcnt(7)
	v_mfma_f32_16x16x32_bf16 v[34:37], v[196:199], v[150:153], v[34:37]
	global_load_dwordx4 v[166:169], v220, s[8:9]
	v_mfma_f32_16x16x32_bf16 v[38:41], v[204:207], v[150:153], v[38:41]
	ds_read_b128 v[150:153], v216 offset:57344
	s_waitcnt lgkmcnt(7)
	v_mfma_f32_16x16x32_bf16 v[42:45], v[196:199], v[154:157], v[42:45]
	global_load_dwordx4 v[170:173], v220, s[8:9] offset:1024
	v_mfma_f32_16x16x32_bf16 v[46:49], v[204:207], v[154:157], v[46:49]
	ds_read_b128 v[154:157], v216 offset:59392
	s_waitcnt lgkmcnt(7)
	v_mfma_f32_16x16x32_bf16 v[50:53], v[196:199], v[158:161], v[50:53]
	global_load_dwordx4 v[174:177], v221, s[8:9]
	v_mfma_f32_16x16x32_bf16 v[54:57], v[204:207], v[158:161], v[54:57]
	ds_read_b128 v[158:161], v216 offset:61440
	s_waitcnt lgkmcnt(7)
	v_mfma_f32_16x16x32_bf16 v[58:61], v[196:199], v[162:165], v[58:61]
	global_load_dwordx4 v[178:181], v221, s[8:9] offset:1024
	v_mfma_f32_16x16x32_bf16 v[62:65], v[204:207], v[162:165], v[62:65]
	ds_read_b128 v[162:165], v216 offset:63488
	s_waitcnt lgkmcnt(7)
	v_mfma_f32_16x16x32_bf16 v[66:69], v[196:199], v[134:137], v[66:69]
	v_mfma_f32_16x16x32_bf16 v[70:73], v[204:207], v[134:137], v[70:73]
	ds_read_b128 v[134:137], v216 offset:33792
	s_waitcnt lgkmcnt(7)
	v_mfma_f32_16x16x32_bf16 v[74:77], v[196:199], v[138:141], v[74:77]
	v_mfma_f32_16x16x32_bf16 v[78:81], v[204:207], v[138:141], v[78:81]
	ds_read_b128 v[138:141], v216 offset:35840
	s_waitcnt lgkmcnt(7)
	v_mfma_f32_16x16x32_bf16 v[82:85], v[196:199], v[142:145], v[82:85]
	v_mfma_f32_16x16x32_bf16 v[86:89], v[204:207], v[142:145], v[86:89]
	ds_read_b128 v[142:145], v216 offset:37888
	s_waitcnt lgkmcnt(7)
	v_mfma_f32_16x16x32_bf16 v[90:93], v[196:199], v[146:149], v[90:93]
	v_mfma_f32_16x16x32_bf16 v[94:97], v[204:207], v[146:149], v[94:97]
	ds_read_b128 v[146:149], v216 offset:39936
	s_waitcnt lgkmcnt(7)
	v_mfma_f32_16x16x32_bf16 v[98:101], v[196:199], v[150:153], v[98:101]
	v_mfma_f32_16x16x32_bf16 v[102:105], v[204:207], v[150:153], v[102:105]
	ds_read_b128 v[150:153], v216 offset:41984
	s_waitcnt lgkmcnt(7)
	v_mfma_f32_16x16x32_bf16 v[106:109], v[196:199], v[154:157], v[106:109]
	v_mfma_f32_16x16x32_bf16 v[110:113], v[204:207], v[154:157], v[110:113]
	ds_read_b128 v[154:157], v216 offset:44032
	s_waitcnt lgkmcnt(7)
	v_mfma_f32_16x16x32_bf16 v[114:117], v[196:199], v[158:161], v[114:117]
	v_mfma_f32_16x16x32_bf16 v[118:121], v[204:207], v[158:161], v[118:121]
	ds_read_b128 v[158:161], v216 offset:46080
	s_waitcnt lgkmcnt(7)
	v_mfma_f32_16x16x32_bf16 v[122:125], v[196:199], v[162:165], v[122:125]
	v_mfma_f32_16x16x32_bf16 v[126:129], v[204:207], v[162:165], v[126:129]
	ds_read_b128 v[162:165], v216 offset:48128
	s_waitcnt lgkmcnt(7)
	v_mfma_f32_16x16x32_bf16 v[2:5], v[200:203], v[134:137], v[2:5]
	v_mfma_f32_16x16x32_bf16 v[6:9], v[212:215], v[134:137], v[6:9]
	ds_read_b128 v[134:137], v216 offset:50176
	s_waitcnt lgkmcnt(7)
	v_mfma_f32_16x16x32_bf16 v[10:13], v[200:203], v[138:141], v[10:13]
	v_mfma_f32_16x16x32_bf16 v[14:17], v[212:215], v[138:141], v[14:17]
	ds_read_b128 v[138:141], v216 offset:52224
	s_waitcnt lgkmcnt(7)
	v_mfma_f32_16x16x32_bf16 v[18:21], v[200:203], v[142:145], v[18:21]
	v_mfma_f32_16x16x32_bf16 v[22:25], v[212:215], v[142:145], v[22:25]
	ds_read_b128 v[142:145], v216 offset:54272
	s_waitcnt lgkmcnt(7)
	v_mfma_f32_16x16x32_bf16 v[26:29], v[200:203], v[146:149], v[26:29]
	v_mfma_f32_16x16x32_bf16 v[30:33], v[212:215], v[146:149], v[30:33]
	ds_read_b128 v[146:149], v216 offset:56320
	s_waitcnt lgkmcnt(7)
	v_mfma_f32_16x16x32_bf16 v[34:37], v[200:203], v[150:153], v[34:37]
	v_mfma_f32_16x16x32_bf16 v[38:41], v[212:215], v[150:153], v[38:41]
	ds_read_b128 v[150:153], v216 offset:58368
	s_waitcnt lgkmcnt(7)
	v_mfma_f32_16x16x32_bf16 v[42:45], v[200:203], v[154:157], v[42:45]
	v_mfma_f32_16x16x32_bf16 v[46:49], v[212:215], v[154:157], v[46:49]
	ds_read_b128 v[154:157], v216 offset:60416
	s_waitcnt lgkmcnt(7)
	v_mfma_f32_16x16x32_bf16 v[50:53], v[200:203], v[158:161], v[50:53]
	v_mfma_f32_16x16x32_bf16 v[54:57], v[212:215], v[158:161], v[54:57]
	ds_read_b128 v[158:161], v216 offset:62464
	s_waitcnt lgkmcnt(7)
	v_mfma_f32_16x16x32_bf16 v[58:61], v[200:203], v[162:165], v[58:61]
	v_mfma_f32_16x16x32_bf16 v[62:65], v[212:215], v[162:165], v[62:65]
	ds_read_b128 v[162:165], v216 offset:64512
	s_waitcnt vmcnt(4) lgkmcnt(0)
	s_barrier
	v_mfma_f32_16x16x32_bf16 v[66:69], v[200:203], v[134:137], v[66:69]
	s_add_u32 m0, s22, 0x8000
	v_mov_b32_e32 v223, v217
	global_load_lds_dwordx4 v223, s[6:7]
	v_mfma_f32_16x16x32_bf16 v[70:73], v[212:215], v[134:137], v[70:73]
	s_add_u32 m0, s22, 0x8400
	v_add_u32_e32 v224, 0x40, v217
	global_load_lds_dwordx4 v224, s[6:7]
	ds_read_b128 v[134:137], v216
	s_waitcnt lgkmcnt(7)
	v_mfma_f32_16x16x32_bf16 v[74:77], v[200:203], v[138:141], v[74:77]
	s_add_u32 m0, s22, 0x8800
	v_add_u32_e32 v223, 0x20000, v217
	global_load_lds_dwordx4 v223, s[6:7]
	v_mfma_f32_16x16x32_bf16 v[78:81], v[212:215], v[138:141], v[78:81]
	s_add_u32 m0, s22, 0x8c00
	v_add_u32_e32 v224, 0x20040, v217
	global_load_lds_dwordx4 v224, s[6:7]
	ds_read_b128 v[138:141], v216 offset:2048
	s_waitcnt lgkmcnt(7)
	v_mfma_f32_16x16x32_bf16 v[82:85], v[200:203], v[142:145], v[82:85]
	s_add_u32 m0, s22, 0x9000
	v_add_u32_e32 v223, 0x40000, v217
	global_load_lds_dwordx4 v223, s[6:7]
	v_mfma_f32_16x16x32_bf16 v[86:89], v[212:215], v[142:145], v[86:89]
	s_add_u32 m0, s22, 0x9400
	v_add_u32_e32 v224, 0x40040, v217
	global_load_lds_dwordx4 v224, s[6:7]
	ds_read_b128 v[142:145], v216 offset:4096
	s_waitcnt lgkmcnt(7)
	v_mfma_f32_16x16x32_bf16 v[90:93], v[200:203], v[146:149], v[90:93]
	s_add_u32 m0, s22, 0x9800
	v_add_u32_e32 v223, 0x60000, v217
	global_load_lds_dwordx4 v223, s[6:7]
	v_mfma_f32_16x16x32_bf16 v[94:97], v[212:215], v[146:149], v[94:97]
	s_add_u32 m0, s22, 0x9c00
	v_add_u32_e32 v224, 0x60040, v217
	global_load_lds_dwordx4 v224, s[6:7]
	ds_read_b128 v[146:149], v216 offset:6144
	s_waitcnt lgkmcnt(7)
	v_mfma_f32_16x16x32_bf16 v[98:101], v[200:203], v[150:153], v[98:101]
	v_mfma_f32_16x16x32_bf16 v[102:105], v[212:215], v[150:153], v[102:105]
	ds_read_b128 v[150:153], v216 offset:8192
	s_waitcnt lgkmcnt(7)
	v_mfma_f32_16x16x32_bf16 v[106:109], v[200:203], v[154:157], v[106:109]
	v_mfma_f32_16x16x32_bf16 v[110:113], v[212:215], v[154:157], v[110:113]
	ds_read_b128 v[154:157], v216 offset:10240
	s_waitcnt lgkmcnt(7)
	v_mfma_f32_16x16x32_bf16 v[114:117], v[200:203], v[158:161], v[114:117]
	v_mfma_f32_16x16x32_bf16 v[118:121], v[212:215], v[158:161], v[118:121]
	ds_read_b128 v[158:161], v216 offset:12288
	s_waitcnt lgkmcnt(7)
	v_mfma_f32_16x16x32_bf16 v[122:125], v[200:203], v[162:165], v[122:125]
	v_mfma_f32_16x16x32_bf16 v[126:129], v[212:215], v[162:165], v[126:129]
	v_add_u32_e32 v217, 0x80, v217
	v_add_u32_e32 v220, 0x800, v220
	v_add_u32_e32 v221, 0x800, v221
	s_mov_b32 s16, 1
	s_branch .Lg256b_w2_epi
.Lg256b_w2_nonext:
	ds_read_b128 v[162:165], v216 offset:14336
	s_waitcnt vmcnt(8) lgkmcnt(7)
	v_mfma_f32_16x16x32_bf16 v[2:5], v[166:169], v[134:137], v[2:5]
	v_mfma_f32_16x16x32_bf16 v[6:9], v[174:177], v[134:137], v[6:9]
	ds_read_b128 v[134:137], v216 offset:16384
	s_waitcnt lgkmcnt(7)
	v_mfma_f32_16x16x32_bf16 v[10:13], v[166:169], v[138:141], v[10:13]
	v_mfma_f32_16x16x32_bf16 v[14:17], v[174:177], v[138:141], v[14:17]
	ds_read_b128 v[138:141], v216 offset:18432
	s_waitcnt lgkmcnt(7)
	v_mfma_f32_16x16x32_bf16 v[18:21], v[166:169], v[142:145], v[18:21]
	v_mfma_f32_16x16x32_bf16 v[22:25], v[174:177], v[142:145], v[22:25]
	ds_read_b128 v[142:145], v216 offset:20480
	s_waitcnt lgkmcnt(7)
	v_mfma_f32_16x16x32_bf16 v[26:29], v[166:169], v[146:149], v[26:29]
	v_mfma_f32_16x16x32_bf16 v[30:33], v[174:177], v[146:149], v[30:33]
	ds_read_b128 v[146:149], v216 offset:22528
	s_waitcnt lgkmcnt(7)
	v_mfma_f32_16x16x32_bf16 v[34:37], v[166:169], v[150:153], v[34:37]
	global_load_dwordx4 v[196:199], v220, s[8:9]
	v_mfma_f32_16x16x32_bf16 v[38:41], v[174:177], v[150:153], v[38:41]
	ds_read_b128 v[150:153], v216 offset:24576
	s_waitcnt lgkmcnt(7)
	v_mfma_f32_16x16x32_bf16 v[42:45], v[166:169], v[154:157], v[42:45]
	global_load_dwordx4 v[200:203], v220, s[8:9] offset:1024
	v_mfma_f32_16x16x32_bf16 v[46:49], v[174:177], v[154:157], v[46:49]
	ds_read_b128 v[154:157], v216 offset:26624
	s_waitcnt lgkmcnt(7)
	v_mfma_f32_16x16x32_bf16 v[50:53], v[166:169], v[158:161], v[50:53]
	global_load_dwordx4 v[204:207], v221, s[8:9]
	v_mfma_f32_16x16x32_bf16 v[54:57], v[174:177], v[158:161], v[54:57]
	ds_read_b128 v[158:161], v216 offset:28672
	s_waitcnt lgkmcnt(7)
	v_mfma_f32_16x16x32_bf16 v[58:61], v[166:169], v[162:165], v[58:61]
	global_load_dwordx4 v[212:215], v221, s[8:9] offset:1024
	v_mfma_f32_16x16x32_bf16 v[62:65], v[174:177], v[162:165], v[62:65]
	ds_read_b128 v[162:165], v216 offset:30720
	s_waitcnt lgkmcnt(7)
	v_mfma_f32_16x16x32_bf16 v[66:69], v[166:169], v[134:137], v[66:69]
	v_mfma_f32_16x16x32_bf16 v[70:73], v[174:177], v[134:137], v[70:73]
	ds_read_b128 v[134:137], v216 offset:1024
	s_waitcnt lgkmcnt(7)
	v_mfma_f32_16x16x32_bf16 v[74:77], v[166:169], v[138:141], v[74:77]
	v_mfma_f32_16x16x32_bf16 v[78:81], v[174:177], v[138:141], v[78:81]
	ds_read_b128 v[138:141], v216 offset:3072
	s_waitcnt lgkmcnt(7)
	v_mfma_f32_16x16x32_bf16 v[82:85], v[166:169], v[142:145], v[82:85]
	v_mfma_f32_16x16x32_bf16 v[86:89], v[174:177], v[142:145], v[86:89]
	ds_read_b128 v[142:145], v216 offset:5120
	s_waitcnt lgkmcnt(7)
	v_mfma_f32_16x16x32_bf16 v[90:93], v[166:169], v[146:149], v[90:93]
	v_mfma_f32_16x16x32_bf16 v[94:97], v[174:177], v[146:149], v[94:97]
	ds_read_b128 v[146:149], v216 offset:7168
	s_waitcnt lgkmcnt(7)
	v_mfma_f32_16x16x32_bf16 v[98:101], v[166:169], v[150:153], v[98:101]
	v_mfma_f32_16x16x32_bf16 v[102:105], v[174:177], v[150:153], v[102:105]
	ds_read_b128 v[150:153], v216 offset:9216
	s_waitcnt lgkmcnt(7)
	v_mfma_f32_16x16x32_bf16 v[106:109], v[166:169], v[154:157], v[106:109]
	v_mfma_f32_16x16x32_bf16 v[110:113], v[174:177], v[154:157], v[110:113]
	ds_read_b128 v[154:157], v216 offset:11264
	s_waitcnt lgkmcnt(7)
	v_mfma_f32_16x16x32_bf16 v[114:117], v[166:169], v[158:161], v[114:117]
	v_mfma_f32_16x16x32_bf16 v[118:121], v[174:177], v[158:161], v[118:121]
	ds_read_b128 v[158:161], v216 offset:13312
	s_waitcnt lgkmcnt(7)
	v_mfma_f32_16x16x32_bf16 v[122:125], v[166:169], v[162:165], v[122:125]
	v_mfma_f32_16x16x32_bf16 v[126:129], v[174:177], v[162:165], v[126:129]
	ds_read_b128 v[162:165], v216 offset:15360
	s_waitcnt lgkmcnt(7)
	v_mfma_f32_16x16x32_bf16 v[2:5], v[170:173], v[134:137], v[2:5]
	v_mfma_f32_16x16x32_bf16 v[6:9], v[178:181], v[134:137], v[6:9]
	ds_read_b128 v[134:137], v216 offset:17408
	s_waitcnt lgkmcnt(7)
	v_mfma_f32_16x16x32_bf16 v[10:13], v[170:173], v[138:141], v[10:13]
	v_mfma_f32_16x16x32_bf16 v[14:17], v[178:181], v[138:141], v[14:17]
	ds_read_b128 v[138:141], v216 offset:19456
	s_waitcnt lgkmcnt(7)
	v_mfma_f32_16x16x32_bf16 v[18:21], v[170:173], v[142:145], v[18:21]
	v_mfma_f32_16x16x32_bf16 v[22:25], v[178:181], v[142:145], v[22:25]
	ds_read_b128 v[142:145], v216 offset:21504
	s_waitcnt lgkmcnt(7)
	v_mfma_f32_16x16x32_bf16 v[26:29], v[170:173], v[146:149], v[26:29]
	v_mfma_f32_16x16x32_bf16 v[30:33], v[178:181], v[146:149], v[30:33]
	ds_read_b128 v[146:149], v216 offset:23552
	s_waitcnt lgkmcnt(7)
	v_mfma_f32_16x16x32_bf16 v[34:37], v[170:173], v[150:153], v[34:37]
	v_mfma_f32_16x16x32_bf16 v[38:41], v[178:181], v[150:153], v[38:41]
	ds_read_b128 v[150:153], v216 offset:25600
	s_waitcnt lgkmcnt(7)
	v_mfma_f32_16x16x32_bf16 v[42:45], v[170:173], v[154:157], v[42:45]
	v_mfma_f32_16x16x32_bf16 v[46:49], v[178:181], v[154:157], v[46:49]
	ds_read_b128 v[154:157], v216 offset:27648
	s_waitcnt lgkmcnt(7)
	v_mfma_f32_16x16x32_bf16 v[50:53], v[170:173], v[158:161], v[50:53]
	v_mfma_f32_16x16x32_bf16 v[54:57], v[178:181], v[158:161], v[54:57]
	ds_read_b128 v[158:161], v216 offset:29696
	s_waitcnt lgkmcnt(7)
	v_mfma_f32_16x16x32_bf16 v[58:61], v[170:173], v[162:165], v[58:61]
	v_mfma_f32_16x16x32_bf16 v[62:65], v[178:181], v[162:165], v[62:65]
	ds_read_b128 v[162:165], v216 offset:31744
	s_waitcnt vmcnt(4) lgkmcnt(0)
	s_barrier
	v_mfma_f32_16x16x32_bf16 v[66:69], v[170:173], v[134:137], v[66:69]
	v_mfma_f32_16x16x32_bf16 v[70:73], v[178:181], v[134:137], v[70:73]
	ds_read_b128 v[134:137], v216 offset:32768
	s_waitcnt lgkmcnt(7)
	v_mfma_f32_16x16x32_bf16 v[74:77], v[170:173], v[138:141], v[74:77]
	v_mfma_f32_16x16x32_bf16 v[78:81], v[178:181], v[138:141], v[78:81]
	ds_read_b128 v[138:141], v216 offset:34816
	s_waitcnt lgkmcnt(7)
	v_mfma_f32_16x16x32_bf16 v[82:85], v[170:173], v[142:145], v[82:85]
	v_mfma_f32_16x16x32_bf16 v[86:89], v[178:181], v[142:145], v[86:89]
	ds_read_b128 v[142:145], v216 offset:36864
	s_waitcnt lgkmcnt(7)
	v_mfma_f32_16x16x32_bf16 v[90:93], v[170:173], v[146:149], v[90:93]
	v_mfma_f32_16x16x32_bf16 v[94:97], v[178:181], v[146:149], v[94:97]
	ds_read_b128 v[146:149], v216 offset:38912
	s_waitcnt lgkmcnt(7)
	v_mfma_f32_16x16x32_bf16 v[98:101], v[170:173], v[150:153], v[98:101]
	v_mfma_f32_16x16x32_bf16 v[102:105], v[178:181], v[150:153], v[102:105]
	ds_read_b128 v[150:153], v216 offset:40960
	s_waitcnt lgkmcnt(7)
	v_mfma_f32_16x16x32_bf16 v[106:109], v[170:173], v[154:157], v[106:109]
	v_mfma_f32_16x16x32_bf16 v[110:113], v[178:181], v[154:157], v[110:113]
	ds_read_b128 v[154:157], v216 offset:43008
	s_waitcnt lgkmcnt(7)
	v_mfma_f32_16x16x32_bf16 v[114:117], v[170:173], v[158:161], v[114:117]
	v_mfma_f32_16x16x32_bf16 v[118:121], v[178:181], v[158:161], v[118:121]
	ds_read_b128 v[158:161], v216 offset:45056
	s_waitcnt lgkmcnt(7)
	v_mfma_f32_16x16x32_bf16 v[122:125], v[170:173], v[162:165], v[122:125]
	v_mfma_f32_16x16x32_bf16 v[126:129], v[178:181], v[162:165], v[126:129]
	v_add_u32_e32 v220, 0x800, v220
	v_add_u32_e32 v221, 0x800, v221
	ds_read_b128 v[162:165], v216 offset:47104
	s_waitcnt vmcnt(0) lgkmcnt(7)
	v_mfma_f32_16x16x32_bf16 v[2:5], v[196:199], v[134:137], v[2:5]
	v_mfma_f32_16x16x32_bf16 v[6:9], v[204:207], v[134:137], v[6:9]
	ds_read_b128 v[134:137], v216 offset:49152
	s_waitcnt lgkmcnt(7)
	v_mfma_f32_16x16x32_bf16 v[10:13], v[196:199], v[138:141], v[10:13]
	v_mfma_f32_16x16x32_bf16 v[14:17], v[204:207], v[138:141], v[14:17]
	ds_read_b128 v[138:141], v216 offset:51200
	s_waitcnt lgkmcnt(7)
	v_mfma_f32_16x16x32_bf16 v[18:21], v[196:199], v[142:145], v[18:21]
	v_mfma_f32_16x16x32_bf16 v[22:25], v[204:207], v[142:145], v[22:25]
	ds_read_b128 v[142:145], v216 offset:53248
	s_waitcnt lgkmcnt(7)
	v_mfma_f32_16x16x32_bf16 v[26:29], v[196:199], v[146:149], v[26:29]
	v_mfma_f32_16x16x32_bf16 v[30:33], v[204:207], v[146:149], v[30:33]
	ds_read_b128 v[146:149], v216 offset:55296
	s_waitcnt lgkmcnt(7)
	v_mfma_f32_16x16x32_bf16 v[34:37], v[196:199], v[150:153], v[34:37]
	v_mfma_f32_16x16x32_bf16 v[38:41], v[204:207], v[150:153], v[38:41]
	ds_read_b128 v[150:153], v216 offset:57344
	s_waitcnt lgkmcnt(7)
	v_mfma_f32_16x16x32_bf16 v[42:45], v[196:199], v[154:157], v[42:45]
	v_mfma_f32_16x16x32_bf16 v[46:49], v[204:207], v[154:157], v[46:49]
	ds_read_b128 v[154:157], v216 offset:59392
	s_waitcnt lgkmcnt(7)
	v_mfma_f32_16x16x32_bf16 v[50:53], v[196:199], v[158:161], v[50:53]
	v_mfma_f32_16x16x32_bf16 v[54:57], v[204:207], v[158:161], v[54:57]
	ds_read_b128 v[158:161], v216 offset:61440
	s_waitcnt lgkmcnt(7)
	v_mfma_f32_16x16x32_bf16 v[58:61], v[196:199], v[162:165], v[58:61]
	v_mfma_f32_16x16x32_bf16 v[62:65], v[204:207], v[162:165], v[62:65]
	ds_read_b128 v[162:165], v216 offset:63488
	s_waitcnt lgkmcnt(7)
	v_mfma_f32_16x16x32_bf16 v[66:69], v[196:199], v[134:137], v[66:69]
	v_mfma_f32_16x16x32_bf16 v[70:73], v[204:207], v[134:137], v[70:73]
	ds_read_b128 v[134:137], v216 offset:33792
	s_waitcnt lgkmcnt(7)
	v_mfma_f32_16x16x32_bf16 v[74:77], v[196:199], v[138:141], v[74:77]
	v_mfma_f32_16x16x32_bf16 v[78:81], v[204:207], v[138:141], v[78:81]
	ds_read_b128 v[138:141], v216 offset:35840
	s_waitcnt lgkmcnt(7)
	v_mfma_f32_16x16x32_bf16 v[82:85], v[196:199], v[142:145], v[82:85]
	v_mfma_f32_16x16x32_bf16 v[86:89], v[204:207], v[142:145], v[86:89]
	ds_read_b128 v[142:145], v216 offset:37888
	s_waitcnt lgkmcnt(7)
	v_mfma_f32_16x16x32_bf16 v[90:93], v[196:199], v[146:149], v[90:93]
	v_mfma_f32_16x16x32_bf16 v[94:97], v[204:207], v[146:149], v[94:97]
	ds_read_b128 v[146:149], v216 offset:39936
	s_waitcnt lgkmcnt(7)
	v_mfma_f32_16x16x32_bf16 v[98:101], v[196:199], v[150:153], v[98:101]
	v_mfma_f32_16x16x32_bf16 v[102:105], v[204:207], v[150:153], v[102:105]
	ds_read_b128 v[150:153], v216 offset:41984
	s_waitcnt lgkmcnt(7)
	v_mfma_f32_16x16x32_bf16 v[106:109], v[196:199], v[154:157], v[106:109]
	v_mfma_f32_16x16x32_bf16 v[110:113], v[204:207], v[154:157], v[110:113]
	ds_read_b128 v[154:157], v216 offset:44032
	s_waitcnt lgkmcnt(7)
	v_mfma_f32_16x16x32_bf16 v[114:117], v[196:199], v[158:161], v[114:117]
	v_mfma_f32_16x16x32_bf16 v[118:121], v[204:207], v[158:161], v[118:121]
	ds_read_b128 v[158:161], v216 offset:46080
	s_waitcnt lgkmcnt(7)
	v_mfma_f32_16x16x32_bf16 v[122:125], v[196:199], v[162:165], v[122:125]
	v_mfma_f32_16x16x32_bf16 v[126:129], v[204:207], v[162:165], v[126:129]
	ds_read_b128 v[162:165], v216 offset:48128
	s_waitcnt lgkmcnt(7)
	v_mfma_f32_16x16x32_bf16 v[2:5], v[200:203], v[134:137], v[2:5]
	v_mfma_f32_16x16x32_bf16 v[6:9], v[212:215], v[134:137], v[6:9]
	ds_read_b128 v[134:137], v216 offset:50176
	s_waitcnt lgkmcnt(7)
	v_mfma_f32_16x16x32_bf16 v[10:13], v[200:203], v[138:141], v[10:13]
	v_mfma_f32_16x16x32_bf16 v[14:17], v[212:215], v[138:141], v[14:17]
	ds_read_b128 v[138:141], v216 offset:52224
	s_waitcnt lgkmcnt(7)
	v_mfma_f32_16x16x32_bf16 v[18:21], v[200:203], v[142:145], v[18:21]
	v_mfma_f32_16x16x32_bf16 v[22:25], v[212:215], v[142:145], v[22:25]
	ds_read_b128 v[142:145], v216 offset:54272
	s_waitcnt lgkmcnt(7)
	v_mfma_f32_16x16x32_bf16 v[26:29], v[200:203], v[146:149], v[26:29]
	v_mfma_f32_16x16x32_bf16 v[30:33], v[212:215], v[146:149], v[30:33]
	ds_read_b128 v[146:149], v216 offset:56320
	s_waitcnt lgkmcnt(7)
	v_mfma_f32_16x16x32_bf16 v[34:37], v[200:203], v[150:153], v[34:37]
	v_mfma_f32_16x16x32_bf16 v[38:41], v[212:215], v[150:153], v[38:41]
	ds_read_b128 v[150:153], v216 offset:58368
	s_waitcnt lgkmcnt(7)
	v_mfma_f32_16x16x32_bf16 v[42:45], v[200:203], v[154:157], v[42:45]
	v_mfma_f32_16x16x32_bf16 v[46:49], v[212:215], v[154:157], v[46:49]
	ds_read_b128 v[154:157], v216 offset:60416
	s_waitcnt lgkmcnt(7)
	v_mfma_f32_16x16x32_bf16 v[50:53], v[200:203], v[158:161], v[50:53]
	v_mfma_f32_16x16x32_bf16 v[54:57], v[212:215], v[158:161], v[54:57]
	ds_read_b128 v[158:161], v216 offset:62464
	s_waitcnt lgkmcnt(7)
	v_mfma_f32_16x16x32_bf16 v[58:61], v[200:203], v[162:165], v[58:61]
	v_mfma_f32_16x16x32_bf16 v[62:65], v[212:215], v[162:165], v[62:65]
	ds_read_b128 v[162:165], v216 offset:64512
	s_waitcnt vmcnt(0) lgkmcnt(0)
	s_barrier
	v_mfma_f32_16x16x32_bf16 v[66:69], v[200:203], v[134:137], v[66:69]
	v_mfma_f32_16x16x32_bf16 v[70:73], v[212:215], v[134:137], v[70:73]
	s_waitcnt lgkmcnt(7)
	v_mfma_f32_16x16x32_bf16 v[74:77], v[200:203], v[138:141], v[74:77]
	v_mfma_f32_16x16x32_bf16 v[78:81], v[212:215], v[138:141], v[78:81]
	s_waitcnt lgkmcnt(7)
	v_mfma_f32_16x16x32_bf16 v[82:85], v[200:203], v[142:145], v[82:85]
	v_mfma_f32_16x16x32_bf16 v[86:89], v[212:215], v[142:145], v[86:89]
	s_waitcnt lgkmcnt(7)
	v_mfma_f32_16x16x32_bf16 v[90:93], v[200:203], v[146:149], v[90:93]
	v_mfma_f32_16x16x32_bf16 v[94:97], v[212:215], v[146:149], v[94:97]
	s_waitcnt lgkmcnt(7)
	v_mfma_f32_16x16x32_bf16 v[98:101], v[200:203], v[150:153], v[98:101]
	v_mfma_f32_16x16x32_bf16 v[102:105], v[212:215], v[150:153], v[102:105]
	s_waitcnt lgkmcnt(7)
	v_mfma_f32_16x16x32_bf16 v[106:109], v[200:203], v[154:157], v[106:109]
	v_mfma_f32_16x16x32_bf16 v[110:113], v[212:215], v[154:157], v[110:113]
	s_waitcnt lgkmcnt(7)
	v_mfma_f32_16x16x32_bf16 v[114:117], v[200:203], v[158:161], v[114:117]
	v_mfma_f32_16x16x32_bf16 v[118:121], v[212:215], v[158:161], v[118:121]
	s_waitcnt lgkmcnt(7)
	v_mfma_f32_16x16x32_bf16 v[122:125], v[200:203], v[162:165], v[122:125]
	v_mfma_f32_16x16x32_bf16 v[126:129], v[212:215], v[162:165], v[126:129]
	s_mov_b32 s16, 0

.Lg256b_w1_tile:
	s_mul_i32 s17, s13, 0x2000
	s_lshl_b32 s3, s15, 5
	s_add_u32 s3, s3, s14
	s_mul_i32 s3, s3, 2
	s_add_u32 s17, s17, s3
	s_add_u32 s10, s24, s17
	s_addc_u32 s11, s25, 0
	ds_read_b128 v[162:165], v216 offset:14336
	s_waitcnt vmcnt(40) lgkmcnt(7)
	v_mfma_f32_16x16x32_bf16 v[2:5], v[166:169], v[134:137], 0
	v_mfma_f32_16x16x32_bf16 v[6:9], v[174:177], v[134:137], 0
	ds_read_b128 v[134:137], v216 offset:16384
	s_waitcnt lgkmcnt(7)
	v_mfma_f32_16x16x32_bf16 v[10:13], v[166:169], v[138:141], 0
	v_mfma_f32_16x16x32_bf16 v[14:17], v[174:177], v[138:141], 0
	ds_read_b128 v[138:141], v216 offset:18432
	s_waitcnt lgkmcnt(7)
	v_mfma_f32_16x16x32_bf16 v[18:21], v[166:169], v[142:145], 0
	v_mfma_f32_16x16x32_bf16 v[22:25], v[174:177], v[142:145], 0
	ds_read_b128 v[142:145], v216 offset:20480
	s_waitcnt lgkmcnt(7)
	v_mfma_f32_16x16x32_bf16 v[26:29], v[166:169], v[146:149], 0
	v_mfma_f32_16x16x32_bf16 v[30:33], v[174:177], v[146:149], 0
	ds_read_b128 v[146:149], v216 offset:22528
	s_waitcnt lgkmcnt(7)
	v_mfma_f32_16x16x32_bf16 v[34:37], v[166:169], v[150:153], 0
	global_load_dwordx4 v[196:199], v220, s[8:9]
	v_mfma_f32_16x16x32_bf16 v[38:41], v[174:177], v[150:153], 0
	ds_read_b128 v[150:153], v216 offset:24576
	s_waitcnt lgkmcnt(7)
	v_mfma_f32_16x16x32_bf16 v[42:45], v[166:169], v[154:157], 0
	global_load_dwordx4 v[200:203], v220, s[8:9] offset:1024
	v_mfma_f32_16x16x32_bf16 v[46:49], v[174:177], v[154:157], 0
	ds_read_b128 v[154:157], v216 offset:26624
	s_waitcnt lgkmcnt(7)
	v_mfma_f32_16x16x32_bf16 v[50:53], v[166:169], v[158:161], 0
	global_load_dwordx4 v[204:207], v221, s[8:9]
	v_mfma_f32_16x16x32_bf16 v[54:57], v[174:177], v[158:161], 0
	ds_read_b128 v[158:161], v216 offset:28672
	s_waitcnt lgkmcnt(7)
	v_mfma_f32_16x16x32_bf16 v[58:61], v[166:169], v[162:165], 0
	global_load_dwordx4 v[212:215], v221, s[8:9] offset:1024
	v_mfma_f32_16x16x32_bf16 v[62:65], v[174:177], v[162:165], 0
	ds_read_b128 v[162:165], v216 offset:30720
	s_waitcnt lgkmcnt(7)
	v_mfma_f32_16x16x32_bf16 v[66:69], v[166:169], v[134:137], 0
	v_mfma_f32_16x16x32_bf16 v[70:73], v[174:177], v[134:137], 0
	ds_read_b128 v[134:137], v216 offset:1024
	s_waitcnt lgkmcnt(7)
	v_mfma_f32_16x16x32_bf16 v[74:77], v[166:169], v[138:141], 0
	v_mfma_f32_16x16x32_bf16 v[78:81], v[174:177], v[138:141], 0
	ds_read_b128 v[138:141], v216 offset:3072
	s_waitcnt lgkmcnt(7)
	v_mfma_f32_16x16x32_bf16 v[82:85], v[166:169], v[142:145], 0
	v_mfma_f32_16x16x32_bf16 v[86:89], v[174:177], v[142:145], 0
	ds_read_b128 v[142:145], v216 offset:5120
	s_waitcnt lgkmcnt(7)
	v_mfma_f32_16x16x32_bf16 v[90:93], v[166:169], v[146:149], 0
	v_mfma_f32_16x16x32_bf16 v[94:97], v[174:177], v[146:149], 0
	ds_read_b128 v[146:149], v216 offset:7168
	s_waitcnt lgkmcnt(7)
	v_mfma_f32_16x16x32_bf16 v[98:101], v[166:169], v[150:153], 0
	v_mfma_f32_16x16x32_bf16 v[102:105], v[174:177], v[150:153], 0
	ds_read_b128 v[150:153], v216 offset:9216
	s_waitcnt lgkmcnt(7)
	v_mfma_f32_16x16x32_bf16 v[106:109], v[166:169], v[154:157], 0
	v_mfma_f32_16x16x32_bf16 v[110:113], v[174:177], v[154:157], 0
	ds_read_b128 v[154:157], v216 offset:11264
	s_waitcnt lgkmcnt(7)
	v_mfma_f32_16x16x32_bf16 v[114:117], v[166:169], v[158:161], 0
	v_mfma_f32_16x16x32_bf16 v[118:121], v[174:177], v[158:161], 0
	ds_read_b128 v[158:161], v216 offset:13312
	s_waitcnt lgkmcnt(7)
	v_mfma_f32_16x16x32_bf16 v[122:125], v[166:169], v[162:165], 0
	v_mfma_f32_16x16x32_bf16 v[126:129], v[174:177], v[162:165], 0
	ds_read_b128 v[162:165], v216 offset:15360
	s_waitcnt lgkmcnt(7)
	v_mfma_f32_16x16x32_bf16 v[2:5], v[170:173], v[134:137], v[2:5]
	v_mfma_f32_16x16x32_bf16 v[6:9], v[178:181], v[134:137], v[6:9]
	ds_read_b128 v[134:137], v216 offset:17408
	s_waitcnt lgkmcnt(7)
	v_mfma_f32_16x16x32_bf16 v[10:13], v[170:173], v[138:141], v[10:13]
	v_mfma_f32_16x16x32_bf16 v[14:17], v[178:181], v[138:141], v[14:17]
	ds_read_b128 v[138:141], v216 offset:19456
	s_waitcnt lgkmcnt(7)
	v_mfma_f32_16x16x32_bf16 v[18:21], v[170:173], v[142:145], v[18:21]
	v_mfma_f32_16x16x32_bf16 v[22:25], v[178:181], v[142:145], v[22:25]
	ds_read_b128 v[142:145], v216 offset:21504
	s_waitcnt lgkmcnt(7)
	v_mfma_f32_16x16x32_bf16 v[26:29], v[170:173], v[146:149], v[26:29]
	v_mfma_f32_16x16x32_bf16 v[30:33], v[178:181], v[146:149], v[30:33]
	ds_read_b128 v[146:149], v216 offset:23552
	s_waitcnt lgkmcnt(7)
	v_mfma_f32_16x16x32_bf16 v[34:37], v[170:173], v[150:153], v[34:37]
	v_mfma_f32_16x16x32_bf16 v[38:41], v[178:181], v[150:153], v[38:41]
	ds_read_b128 v[150:153], v216 offset:25600
	s_waitcnt lgkmcnt(7)
	v_mfma_f32_16x16x32_bf16 v[42:45], v[170:173], v[154:157], v[42:45]
	v_mfma_f32_16x16x32_bf16 v[46:49], v[178:181], v[154:157], v[46:49]
	ds_read_b128 v[154:157], v216 offset:27648
	s_waitcnt lgkmcnt(7)
	v_mfma_f32_16x16x32_bf16 v[50:53], v[170:173], v[158:161], v[50:53]
	v_mfma_f32_16x16x32_bf16 v[54:57], v[178:181], v[158:161], v[54:57]
	ds_read_b128 v[158:161], v216 offset:29696
	s_waitcnt lgkmcnt(7)
	v_mfma_f32_16x16x32_bf16 v[58:61], v[170:173], v[162:165], v[58:61]
	v_mfma_f32_16x16x32_bf16 v[62:65], v[178:181], v[162:165], v[62:65]
	ds_read_b128 v[162:165], v216 offset:31744
	s_waitcnt vmcnt(36) lgkmcnt(0)
	s_barrier
	v_mfma_f32_16x16x32_bf16 v[66:69], v[170:173], v[134:137], v[66:69]
	s_add_u32 m0, s22, 0x0
	v_mov_b32_e32 v223, v217
	global_load_lds_dwordx4 v223, s[6:7]
	v_mfma_f32_16x16x32_bf16 v[70:73], v[178:181], v[134:137], v[70:73]
	s_add_u32 m0, s22, 0x400
	v_add_u32_e32 v224, 0x40, v217
	global_load_lds_dwordx4 v224, s[6:7]
	ds_read_b128 v[134:137], v216 offset:32768
	s_waitcnt lgkmcnt(7)
	v_mfma_f32_16x16x32_bf16 v[74:77], v[170:173], v[138:141], v[74:77]
	s_add_u32 m0, s22, 0x800
	v_add_u32_e32 v223, 0x8000, v217
	global_load_lds_dwordx4 v223, s[6:7]
	v_mfma_f32_16x16x32_bf16 v[78:81], v[178:181], v[138:141], v[78:81]
	s_add_u32 m0, s22, 0xc00
	v_add_u32_e32 v224, 0x8040, v217
	global_load_lds_dwordx4 v224, s[6:7]
	ds_read_b128 v[138:141], v216 offset:34816
	s_waitcnt lgkmcnt(7)
	v_mfma_f32_16x16x32_bf16 v[82:85], v[170:173], v[142:145], v[82:85]
	s_add_u32 m0, s22, 0x1000
	v_add_u32_e32 v223, 0x10000, v217
	global_load_lds_dwordx4 v223, s[6:7]
	v_mfma_f32_16x16x32_bf16 v[86:89], v[178:181], v[142:145], v[86:89]
	s_add_u32 m0, s22, 0x1400
	v_add_u32_e32 v224, 0x10040, v217
	global_load_lds_dwordx4 v224, s[6:7]
	ds_read_b128 v[142:145], v216 offset:36864
	s_waitcnt lgkmcnt(7)
	v_mfma_f32_16x16x32_bf16 v[90:93], v[170:173], v[146:149], v[90:93]
	s_add_u32 m0, s22, 0x1800
	v_add_u32_e32 v223, 0x18000, v217
	global_load_lds_dwordx4 v223, s[6:7]
	v_mfma_f32_16x16x32_bf16 v[94:97], v[178:181], v[146:149], v[94:97]
	s_add_u32 m0, s22, 0x1c00
	v_add_u32_e32 v224, 0x18040, v217
	global_load_lds_dwordx4 v224, s[6:7]
	ds_read_b128 v[146:149], v216 offset:38912
	s_waitcnt lgkmcnt(7)
	v_mfma_f32_16x16x32_bf16 v[98:101], v[170:173], v[150:153], v[98:101]
	v_mfma_f32_16x16x32_bf16 v[102:105], v[178:181], v[150:153], v[102:105]
	ds_read_b128 v[150:153], v216 offset:40960
	s_waitcnt lgkmcnt(7)
	v_mfma_f32_16x16x32_bf16 v[106:109], v[170:173], v[154:157], v[106:109]
	v_mfma_f32_16x16x32_bf16 v[110:113], v[178:181], v[154:157], v[110:113]
	ds_read_b128 v[154:157], v216 offset:43008
	s_waitcnt lgkmcnt(7)
	v_mfma_f32_16x16x32_bf16 v[114:117], v[170:173], v[158:161], v[114:117]
	v_mfma_f32_16x16x32_bf16 v[118:121], v[178:181], v[158:161], v[118:121]
	ds_read_b128 v[158:161], v216 offset:45056
	s_waitcnt lgkmcnt(7)
	v_mfma_f32_16x16x32_bf16 v[122:125], v[170:173], v[162:165], v[122:125]
	v_mfma_f32_16x16x32_bf16 v[126:129], v[178:181], v[162:165], v[126:129]
	v_add_u32_e32 v217, 0x80, v217
	v_add_u32_e32 v220, 0x800, v220
	v_add_u32_e32 v221, 0x800, v221
	ds_read_b128 v[162:165], v216 offset:47104
	s_waitcnt vmcnt(8) lgkmcnt(7)
	v_mfma_f32_16x16x32_bf16 v[2:5], v[196:199], v[134:137], v[2:5]
	v_mfma_f32_16x16x32_bf16 v[6:9], v[204:207], v[134:137], v[6:9]
	ds_read_b128 v[134:137], v216 offset:49152
	s_waitcnt lgkmcnt(7)
	v_mfma_f32_16x16x32_bf16 v[10:13], v[196:199], v[138:141], v[10:13]
	v_mfma_f32_16x16x32_bf16 v[14:17], v[204:207], v[138:141], v[14:17]
	ds_read_b128 v[138:141], v216 offset:51200
	s_waitcnt lgkmcnt(7)
	v_mfma_f32_16x16x32_bf16 v[18:21], v[196:199], v[142:145], v[18:21]
	v_mfma_f32_16x16x32_bf16 v[22:25], v[204:207], v[142:145], v[22:25]
	ds_read_b128 v[142:145], v216 offset:53248
	s_waitcnt lgkmcnt(7)
	v_mfma_f32_16x16x32_bf16 v[26:29], v[196:199], v[146:149], v[26:29]
	v_mfma_f32_16x16x32_bf16 v[30:33], v[204:207], v[146:149], v[30:33]
	ds_read_b128 v[146:149], v216 offset:55296
	s_waitcnt lgkmcnt(7)
	v_mfma_f32_16x16x32_bf16 v[34:37], v[196:199], v[150:153], v[34:37]
	global_load_dwordx4 v[166:169], v220, s[8:9]
	v_mfma_f32_16x16x32_bf16 v[38:41], v[204:207], v[150:153], v[38:41]
	ds_read_b128 v[150:153], v216 offset:57344
	s_waitcnt lgkmcnt(7)
	v_mfma_f32_16x16x32_bf16 v[42:45], v[196:199], v[154:157], v[42:45]
	global_load_dwordx4 v[170:173], v220, s[8:9] offset:1024
	v_mfma_f32_16x16x32_bf16 v[46:49], v[204:207], v[154:157], v[46:49]
	ds_read_b128 v[154:157], v216 offset:59392
	s_waitcnt lgkmcnt(7)
	v_mfma_f32_16x16x32_bf16 v[50:53], v[196:199], v[158:161], v[50:53]
	global_load_dwordx4 v[174:177], v221, s[8:9]
	v_mfma_f32_16x16x32_bf16 v[54:57], v[204:207], v[158:161], v[54:57]
	ds_read_b128 v[158:161], v216 offset:61440
	s_waitcnt lgkmcnt(7)
	v_mfma_f32_16x16x32_bf16 v[58:61], v[196:199], v[162:165], v[58:61]
	global_load_dwordx4 v[178:181], v221, s[8:9] offset:1024
	v_mfma_f32_16x16x32_bf16 v[62:65], v[204:207], v[162:165], v[62:65]
	ds_read_b128 v[162:165], v216 offset:63488
	s_waitcnt lgkmcnt(7)
	v_mfma_f32_16x16x32_bf16 v[66:69], v[196:199], v[134:137], v[66:69]
	v_mfma_f32_16x16x32_bf16 v[70:73], v[204:207], v[134:137], v[70:73]
	ds_read_b128 v[134:137], v216 offset:33792
	s_waitcnt lgkmcnt(7)
	v_mfma_f32_16x16x32_bf16 v[74:77], v[196:199], v[138:141], v[74:77]
	v_mfma_f32_16x16x32_bf16 v[78:81], v[204:207], v[138:141], v[78:81]
	ds_read_b128 v[138:141], v216 offset:35840
	s_waitcnt lgkmcnt(7)
	v_mfma_f32_16x16x32_bf16 v[82:85], v[196:199], v[142:145], v[82:85]
	v_mfma_f32_16x16x32_bf16 v[86:89], v[204:207], v[142:145], v[86:89]
	ds_read_b128 v[142:145], v216 offset:37888
	s_waitcnt lgkmcnt(7)
	v_mfma_f32_16x16x32_bf16 v[90:93], v[196:199], v[146:149], v[90:93]
	v_mfma_f32_16x16x32_bf16 v[94:97], v[204:207], v[146:149], v[94:97]
	ds_read_b128 v[146:149], v216 offset:39936
	s_waitcnt lgkmcnt(7)
	v_mfma_f32_16x16x32_bf16 v[98:101], v[196:199], v[150:153], v[98:101]
	v_mfma_f32_16x16x32_bf16 v[102:105], v[204:207], v[150:153], v[102:105]
	ds_read_b128 v[150:153], v216 offset:41984
	s_waitcnt lgkmcnt(7)
	v_mfma_f32_16x16x32_bf16 v[106:109], v[196:199], v[154:157], v[106:109]
	v_mfma_f32_16x16x32_bf16 v[110:113], v[204:207], v[154:157], v[110:113]
	ds_read_b128 v[154:157], v216 offset:44032
	s_waitcnt lgkmcnt(7)
	v_mfma_f32_16x16x32_bf16 v[114:117], v[196:199], v[158:161], v[114:117]
	v_mfma_f32_16x16x32_bf16 v[118:121], v[204:207], v[158:161], v[118:121]
	ds_read_b128 v[158:161], v216 offset:46080
	s_waitcnt lgkmcnt(7)
	v_mfma_f32_16x16x32_bf16 v[122:125], v[196:199], v[162:165], v[122:125]
	v_mfma_f32_16x16x32_bf16 v[126:129], v[204:207], v[162:165], v[126:129]
	ds_read_b128 v[162:165], v216 offset:48128
	s_waitcnt lgkmcnt(7)
	v_mfma_f32_16x16x32_bf16 v[2:5], v[200:203], v[134:137], v[2:5]
	v_mfma_f32_16x16x32_bf16 v[6:9], v[212:215], v[134:137], v[6:9]
	ds_read_b128 v[134:137], v216 offset:50176
	s_waitcnt lgkmcnt(7)
	v_mfma_f32_16x16x32_bf16 v[10:13], v[200:203], v[138:141], v[10:13]
	v_mfma_f32_16x16x32_bf16 v[14:17], v[212:215], v[138:141], v[14:17]
	ds_read_b128 v[138:141], v216 offset:52224
	s_waitcnt lgkmcnt(7)
	v_mfma_f32_16x16x32_bf16 v[18:21], v[200:203], v[142:145], v[18:21]
	v_mfma_f32_16x16x32_bf16 v[22:25], v[212:215], v[142:145], v[22:25]
	ds_read_b128 v[142:145], v216 offset:54272
	s_waitcnt lgkmcnt(7)
	v_mfma_f32_16x16x32_bf16 v[26:29], v[200:203], v[146:149], v[26:29]
	v_mfma_f32_16x16x32_bf16 v[30:33], v[212:215], v[146:149], v[30:33]
	ds_read_b128 v[146:149], v216 offset:56320
	s_waitcnt lgkmcnt(7)
	v_mfma_f32_16x16x32_bf16 v[34:37], v[200:203], v[150:153], v[34:37]
	v_mfma_f32_16x16x32_bf16 v[38:41], v[212:215], v[150:153], v[38:41]
	ds_read_b128 v[150:153], v216 offset:58368
	s_waitcnt lgkmcnt(7)
	v_mfma_f32_16x16x32_bf16 v[42:45], v[200:203], v[154:157], v[42:45]
	v_mfma_f32_16x16x32_bf16 v[46:49], v[212:215], v[154:157], v[46:49]
	ds_read_b128 v[154:157], v216 offset:60416
	s_waitcnt lgkmcnt(7)
	v_mfma_f32_16x16x32_bf16 v[50:53], v[200:203], v[158:161], v[50:53]
	v_mfma_f32_16x16x32_bf16 v[54:57], v[212:215], v[158:161], v[54:57]
	ds_read_b128 v[158:161], v216 offset:62464
	s_waitcnt lgkmcnt(7)
	v_mfma_f32_16x16x32_bf16 v[58:61], v[200:203], v[162:165], v[58:61]
	v_mfma_f32_16x16x32_bf16 v[62:65], v[212:215], v[162:165], v[62:65]
	ds_read_b128 v[162:165], v216 offset:64512
	s_waitcnt vmcnt(4) lgkmcnt(0)
	s_barrier
	v_mfma_f32_16x16x32_bf16 v[66:69], v[200:203], v[134:137], v[66:69]
	s_add_u32 m0, s22, 0x8000
	v_mov_b32_e32 v223, v217
	global_load_lds_dwordx4 v223, s[6:7]
	v_mfma_f32_16x16x32_bf16 v[70:73], v[212:215], v[134:137], v[70:73]
	s_add_u32 m0, s22, 0x8400
	v_add_u32_e32 v224, 0x40, v217
	global_load_lds_dwordx4 v224, s[6:7]
	ds_read_b128 v[134:137], v216
	s_waitcnt lgkmcnt(7)
	v_mfma_f32_16x16x32_bf16 v[74:77], v[200:203], v[138:141], v[74:77]
	s_add_u32 m0, s22, 0x8800
	v_add_u32_e32 v223, 0x8000, v217
	global_load_lds_dwordx4 v223, s[6:7]
	v_mfma_f32_16x16x32_bf16 v[78:81], v[212:215], v[138:141], v[78:81]
	s_add_u32 m0, s22, 0x8c00
	v_add_u32_e32 v224, 0x8040, v217
	global_load_lds_dwordx4 v224, s[6:7]
	ds_read_b128 v[138:141], v216 offset:2048
	s_waitcnt lgkmcnt(7)
	v_mfma_f32_16x16x32_bf16 v[82:85], v[200:203], v[142:145], v[82:85]
	s_add_u32 m0, s22, 0x9000
	v_add_u32_e32 v223, 0x10000, v217
	global_load_lds_dwordx4 v223, s[6:7]
	v_mfma_f32_16x16x32_bf16 v[86:89], v[212:215], v[142:145], v[86:89]
	s_add_u32 m0, s22, 0x9400
	v_add_u32_e32 v224, 0x10040, v217
	global_load_lds_dwordx4 v224, s[6:7]
	ds_read_b128 v[142:145], v216 offset:4096
	s_waitcnt lgkmcnt(7)
	v_mfma_f32_16x16x32_bf16 v[90:93], v[200:203], v[146:149], v[90:93]
	s_add_u32 m0, s22, 0x9800
	v_add_u32_e32 v223, 0x18000, v217
	global_load_lds_dwordx4 v223, s[6:7]
	v_mfma_f32_16x16x32_bf16 v[94:97], v[212:215], v[146:149], v[94:97]
	s_add_u32 m0, s22, 0x9c00
	v_add_u32_e32 v224, 0x18040, v217
	global_load_lds_dwordx4 v224, s[6:7]
	ds_read_b128 v[146:149], v216 offset:6144
	s_waitcnt lgkmcnt(7)
	v_mfma_f32_16x16x32_bf16 v[98:101], v[200:203], v[150:153], v[98:101]
	v_mfma_f32_16x16x32_bf16 v[102:105], v[212:215], v[150:153], v[102:105]
	ds_read_b128 v[150:153], v216 offset:8192
	s_waitcnt lgkmcnt(7)
	v_mfma_f32_16x16x32_bf16 v[106:109], v[200:203], v[154:157], v[106:109]
	v_mfma_f32_16x16x32_bf16 v[110:113], v[212:215], v[154:157], v[110:113]
	ds_read_b128 v[154:157], v216 offset:10240
	s_waitcnt lgkmcnt(7)
	v_mfma_f32_16x16x32_bf16 v[114:117], v[200:203], v[158:161], v[114:117]
	v_mfma_f32_16x16x32_bf16 v[118:121], v[212:215], v[158:161], v[118:121]
	ds_read_b128 v[158:161], v216 offset:12288
	s_waitcnt lgkmcnt(7)
	v_mfma_f32_16x16x32_bf16 v[122:125], v[200:203], v[162:165], v[122:125]
	v_mfma_f32_16x16x32_bf16 v[126:129], v[212:215], v[162:165], v[126:129]
	v_add_u32_e32 v217, 0x80, v217
	v_add_u32_e32 v220, 0x800, v220
	v_add_u32_e32 v221, 0x800, v221
	s_mov_b32 s16, 6
.Lg256b_w1_loop:
	ds_read_b128 v[162:165], v216 offset:14336
	s_waitcnt vmcnt(8) lgkmcnt(7)
	v_mfma_f32_16x16x32_bf16 v[2:5], v[166:169], v[134:137], v[2:5]
	v_mfma_f32_16x16x32_bf16 v[6:9], v[174:177], v[134:137], v[6:9]
	ds_read_b128 v[134:137], v216 offset:16384
	s_waitcnt lgkmcnt(7)
	v_mfma_f32_16x16x32_bf16 v[10:13], v[166:169], v[138:141], v[10:13]
	v_mfma_f32_16x16x32_bf16 v[14:17], v[174:177], v[138:141], v[14:17]
	ds_read_b128 v[138:141], v216 offset:18432
	s_waitcnt lgkmcnt(7)
	v_mfma_f32_16x16x32_bf16 v[18:21], v[166:169], v[142:145], v[18:21]
	v_mfma_f32_16x16x32_bf16 v[22:25], v[174:177], v[142:145], v[22:25]
	ds_read_b128 v[142:145], v216 offset:20480
	s_waitcnt lgkmcnt(7)
	v_mfma_f32_16x16x32_bf16 v[26:29], v[166:169], v[146:149], v[26:29]
	v_mfma_f32_16x16x32_bf16 v[30:33], v[174:177], v[146:149], v[30:33]
	ds_read_b128 v[146:149], v216 offset:22528
	s_waitcnt lgkmcnt(7)
	v_mfma_f32_16x16x32_bf16 v[34:37], v[166:169], v[150:153], v[34:37]
	global_load_dwordx4 v[196:199], v220, s[8:9]
	v_mfma_f32_16x16x32_bf16 v[38:41], v[174:177], v[150:153], v[38:41]
	ds_read_b128 v[150:153], v216 offset:24576
	s_waitcnt lgkmcnt(7)
	v_mfma_f32_16x16x32_bf16 v[42:45], v[166:169], v[154:157], v[42:45]
	global_load_dwordx4 v[200:203], v220, s[8:9] offset:1024
	v_mfma_f32_16x16x32_bf16 v[46:49], v[174:177], v[154:157], v[46:49]
	ds_read_b128 v[154:157], v216 offset:26624
	s_waitcnt lgkmcnt(7)
	v_mfma_f32_16x16x32_bf16 v[50:53], v[166:169], v[158:161], v[50:53]
	global_load_dwordx4 v[204:207], v221, s[8:9]
	v_mfma_f32_16x16x32_bf16 v[54:57], v[174:177], v[158:161], v[54:57]
	ds_read_b128 v[158:161], v216 offset:28672
	s_waitcnt lgkmcnt(7)
	v_mfma_f32_16x16x32_bf16 v[58:61], v[166:169], v[162:165], v[58:61]
	global_load_dwordx4 v[212:215], v221, s[8:9] offset:1024
	v_mfma_f32_16x16x32_bf16 v[62:65], v[174:177], v[162:165], v[62:65]
	ds_read_b128 v[162:165], v216 offset:30720
	s_waitcnt lgkmcnt(7)
	v_mfma_f32_16x16x32_bf16 v[66:69], v[166:169], v[134:137], v[66:69]
	v_mfma_f32_16x16x32_bf16 v[70:73], v[174:177], v[134:137], v[70:73]
	ds_read_b128 v[134:137], v216 offset:1024
	s_waitcnt lgkmcnt(7)
	v_mfma_f32_16x16x32_bf16 v[74:77], v[166:169], v[138:141], v[74:77]
	v_mfma_f32_16x16x32_bf16 v[78:81], v[174:177], v[138:141], v[78:81]
	ds_read_b128 v[138:141], v216 offset:3072
	s_waitcnt lgkmcnt(7)
	v_mfma_f32_16x16x32_bf16 v[82:85], v[166:169], v[142:145], v[82:85]
	v_mfma_f32_16x16x32_bf16 v[86:89], v[174:177], v[142:145], v[86:89]
	ds_read_b128 v[142:145], v216 offset:5120
	s_waitcnt lgkmcnt(7)
	v_mfma_f32_16x16x32_bf16 v[90:93], v[166:169], v[146:149], v[90:93]
	v_mfma_f32_16x16x32_bf16 v[94:97], v[174:177], v[146:149], v[94:97]
	ds_read_b128 v[146:149], v216 offset:7168
	s_waitcnt lgkmcnt(7)
	v_mfma_f32_16x16x32_bf16 v[98:101], v[166:169], v[150:153], v[98:101]
	v_mfma_f32_16x16x32_bf16 v[102:105], v[174:177], v[150:153], v[102:105]
	ds_read_b128 v[150:153], v216 offset:9216
	s_waitcnt lgkmcnt(7)
	v_mfma_f32_16x16x32_bf16 v[106:109], v[166:169], v[154:157], v[106:109]
	v_mfma_f32_16x16x32_bf16 v[110:113], v[174:177], v[154:157], v[110:113]
	ds_read_b128 v[154:157], v216 offset:11264
	s_waitcnt lgkmcnt(7)
	v_mfma_f32_16x16x32_bf16 v[114:117], v[166:169], v[158:161], v[114:117]
	v_mfma_f32_16x16x32_bf16 v[118:121], v[174:177], v[158:161], v[118:121]
	ds_read_b128 v[158:161], v216 offset:13312
	s_waitcnt lgkmcnt(7)
	v_mfma_f32_16x16x32_bf16 v[122:125], v[166:169], v[162:165], v[122:125]
	v_mfma_f32_16x16x32_bf16 v[126:129], v[174:177], v[162:165], v[126:129]
	ds_read_b128 v[162:165], v216 offset:15360
	s_waitcnt lgkmcnt(7)
	v_mfma_f32_16x16x32_bf16 v[2:5], v[170:173], v[134:137], v[2:5]
	v_mfma_f32_16x16x32_bf16 v[6:9], v[178:181], v[134:137], v[6:9]
	ds_read_b128 v[134:137], v216 offset:17408
	s_waitcnt lgkmcnt(7)
	v_mfma_f32_16x16x32_bf16 v[10:13], v[170:173], v[138:141], v[10:13]
	v_mfma_f32_16x16x32_bf16 v[14:17], v[178:181], v[138:141], v[14:17]
	ds_read_b128 v[138:141], v216 offset:19456
	s_waitcnt lgkmcnt(7)
	v_mfma_f32_16x16x32_bf16 v[18:21], v[170:173], v[142:145], v[18:21]
	v_mfma_f32_16x16x32_bf16 v[22:25], v[178:181], v[142:145], v[22:25]
	ds_read_b128 v[142:145], v216 offset:21504
	s_waitcnt lgkmcnt(7)
	v_mfma_f32_16x16x32_bf16 v[26:29], v[170:173], v[146:149], v[26:29]
	v_mfma_f32_16x16x32_bf16 v[30:33], v[178:181], v[146:149], v[30:33]
	ds_read_b128 v[146:149], v216 offset:23552
	s_waitcnt lgkmcnt(7)
	v_mfma_f32_16x16x32_bf16 v[34:37], v[170:173], v[150:153], v[34:37]
	v_mfma_f32_16x16x32_bf16 v[38:41], v[178:181], v[150:153], v[38:41]
	ds_read_b128 v[150:153], v216 offset:25600
	s_waitcnt lgkmcnt(7)
	v_mfma_f32_16x16x32_bf16 v[42:45], v[170:173], v[154:157], v[42:45]
	v_mfma_f32_16x16x32_bf16 v[46:49], v[178:181], v[154:157], v[46:49]
	ds_read_b128 v[154:157], v216 offset:27648
	s_waitcnt lgkmcnt(7)
	v_mfma_f32_16x16x32_bf16 v[50:53], v[170:173], v[158:161], v[50:53]
	v_mfma_f32_16x16x32_bf16 v[54:57], v[178:181], v[158:161], v[54:57]
	ds_read_b128 v[158:161], v216 offset:29696
	s_waitcnt lgkmcnt(7)
	v_mfma_f32_16x16x32_bf16 v[58:61], v[170:173], v[162:165], v[58:61]
	v_mfma_f32_16x16x32_bf16 v[62:65], v[178:181], v[162:165], v[62:65]
	ds_read_b128 v[162:165], v216 offset:31744
	s_waitcnt vmcnt(4) lgkmcnt(0)
	s_barrier
	v_mfma_f32_16x16x32_bf16 v[66:69], v[170:173], v[134:137], v[66:69]
	s_add_u32 m0, s22, 0x0
	v_mov_b32_e32 v223, v217
	global_load_lds_dwordx4 v223, s[6:7]
	v_mfma_f32_16x16x32_bf16 v[70:73], v[178:181], v[134:137], v[70:73]
	s_add_u32 m0, s22, 0x400
	v_add_u32_e32 v224, 0x40, v217
	global_load_lds_dwordx4 v224, s[6:7]
	ds_read_b128 v[134:137], v216 offset:32768
	s_waitcnt lgkmcnt(7)
	v_mfma_f32_16x16x32_bf16 v[74:77], v[170:173], v[138:141], v[74:77]
	s_add_u32 m0, s22, 0x800
	v_add_u32_e32 v223, 0x8000, v217
	global_load_lds_dwordx4 v223, s[6:7]
	v_mfma_f32_16x16x32_bf16 v[78:81], v[178:181], v[138:141], v[78:81]
	s_add_u32 m0, s22, 0xc00
	v_add_u32_e32 v224, 0x8040, v217
	global_load_lds_dwordx4 v224, s[6:7]
	ds_read_b128 v[138:141], v216 offset:34816
	s_waitcnt lgkmcnt(7)
	v_mfma_f32_16x16x32_bf16 v[82:85], v[170:173], v[142:145], v[82:85]
	s_add_u32 m0, s22, 0x1000
	v_add_u32_e32 v223, 0x10000, v217
	global_load_lds_dwordx4 v223, s[6:7]
	v_mfma_f32_16x16x32_bf16 v[86:89], v[178:181], v[142:145], v[86:89]
	s_add_u32 m0, s22, 0x1400
	v_add_u32_e32 v224, 0x10040, v217
	global_load_lds_dwordx4 v224, s[6:7]
	ds_read_b128 v[142:145], v216 offset:36864
	s_waitcnt lgkmcnt(7)
	v_mfma_f32_16x16x32_bf16 v[90:93], v[170:173], v[146:149], v[90:93]
	s_add_u32 m0, s22, 0x1800
	v_add_u32_e32 v223, 0x18000, v217
	global_load_lds_dwordx4 v223, s[6:7]
	v_mfma_f32_16x16x32_bf16 v[94:97], v[178:181], v[146:149], v[94:97]
	s_add_u32 m0, s22, 0x1c00
	v_add_u32_e32 v224, 0x18040, v217
	global_load_lds_dwordx4 v224, s[6:7]
	ds_read_b128 v[146:149], v216 offset:38912
	s_waitcnt lgkmcnt(7)
	v_mfma_f32_16x16x32_bf16 v[98:101], v[170:173], v[150:153], v[98:101]
	v_mfma_f32_16x16x32_bf16 v[102:105], v[178:181], v[150:153], v[102:105]
	ds_read_b128 v[150:153], v216 offset:40960
	s_waitcnt lgkmcnt(7)
	v_mfma_f32_16x16x32_bf16 v[106:109], v[170:173], v[154:157], v[106:109]
	v_mfma_f32_16x16x32_bf16 v[110:113], v[178:181], v[154:157], v[110:113]
	ds_read_b128 v[154:157], v216 offset:43008
	s_waitcnt lgkmcnt(7)
	v_mfma_f32_16x16x32_bf16 v[114:117], v[170:173], v[158:161], v[114:117]
	v_mfma_f32_16x16x32_bf16 v[118:121], v[178:181], v[158:161], v[118:121]
	ds_read_b128 v[158:161], v216 offset:45056
	s_waitcnt lgkmcnt(7)
	v_mfma_f32_16x16x32_bf16 v[122:125], v[170:173], v[162:165], v[122:125]
	v_mfma_f32_16x16x32_bf16 v[126:129], v[178:181], v[162:165], v[126:129]
	v_add_u32_e32 v217, 0x80, v217
	v_add_u32_e32 v220, 0x800, v220
	v_add_u32_e32 v221, 0x800, v221
	ds_read_b128 v[162:165], v216 offset:47104
	s_waitcnt vmcnt(8) lgkmcnt(7)
	v_mfma_f32_16x16x32_bf16 v[2:5], v[196:199], v[134:137], v[2:5]
	v_mfma_f32_16x16x32_bf16 v[6:9], v[204:207], v[134:137], v[6:9]
	ds_read_b128 v[134:137], v216 offset:49152
	s_waitcnt lgkmcnt(7)
	v_mfma_f32_16x16x32_bf16 v[10:13], v[196:199], v[138:141], v[10:13]
	v_mfma_f32_16x16x32_bf16 v[14:17], v[204:207], v[138:141], v[14:17]
	ds_read_b128 v[138:141], v216 offset:51200
	s_waitcnt lgkmcnt(7)
	v_mfma_f32_16x16x32_bf16 v[18:21], v[196:199], v[142:145], v[18:21]
	v_mfma_f32_16x16x32_bf16 v[22:25], v[204:207], v[142:145], v[22:25]
	ds_read_b128 v[142:145], v216 offset:53248
	s_waitcnt lgkmcnt(7)
	v_mfma_f32_16x16x32_bf16 v[26:29], v[196:199], v[146:149], v[26:29]
	v_mfma_f32_16x16x32_bf16 v[30:33], v[204:207], v[146:149], v[30:33]
	ds_read_b128 v[146:149], v216 offset:55296
	s_waitcnt lgkmcnt(7)
	v_mfma_f32_16x16x32_bf16 v[34:37], v[196:199], v[150:153], v[34:37]
	global_load_dwordx4 v[166:169], v220, s[8:9]
	v_mfma_f32_16x16x32_bf16 v[38:41], v[204:207], v[150:153], v[38:41]
	ds_read_b128 v[150:153], v216 offset:57344
	s_waitcnt lgkmcnt(7)
	v_mfma_f32_16x16x32_bf16 v[42:45], v[196:199], v[154:157], v[42:45]
	global_load_dwordx4 v[170:173], v220, s[8:9] offset:1024
	v_mfma_f32_16x16x32_bf16 v[46:49], v[204:207], v[154:157], v[46:49]
	ds_read_b128 v[154:157], v216 offset:59392
	s_waitcnt lgkmcnt(7)
	v_mfma_f32_16x16x32_bf16 v[50:53], v[196:199], v[158:161], v[50:53]
	global_load_dwordx4 v[174:177], v221, s[8:9]
	v_mfma_f32_16x16x32_bf16 v[54:57], v[204:207], v[158:161], v[54:57]
	ds_read_b128 v[158:161], v216 offset:61440
	s_waitcnt lgkmcnt(7)
	v_mfma_f32_16x16x32_bf16 v[58:61], v[196:199], v[162:165], v[58:61]
	global_load_dwordx4 v[178:181], v221, s[8:9] offset:1024
	v_mfma_f32_16x16x32_bf16 v[62:65], v[204:207], v[162:165], v[62:65]
	ds_read_b128 v[162:165], v216 offset:63488
	s_waitcnt lgkmcnt(7)
	v_mfma_f32_16x16x32_bf16 v[66:69], v[196:199], v[134:137], v[66:69]
	v_mfma_f32_16x16x32_bf16 v[70:73], v[204:207], v[134:137], v[70:73]
	ds_read_b128 v[134:137], v216 offset:33792
	s_waitcnt lgkmcnt(7)
	v_mfma_f32_16x16x32_bf16 v[74:77], v[196:199], v[138:141], v[74:77]
	v_mfma_f32_16x16x32_bf16 v[78:81], v[204:207], v[138:141], v[78:81]
	ds_read_b128 v[138:141], v216 offset:35840
	s_waitcnt lgkmcnt(7)
	v_mfma_f32_16x16x32_bf16 v[82:85], v[196:199], v[142:145], v[82:85]
	v_mfma_f32_16x16x32_bf16 v[86:89], v[204:207], v[142:145], v[86:89]
	ds_read_b128 v[142:145], v216 offset:37888
	s_waitcnt lgkmcnt(7)
	v_mfma_f32_16x16x32_bf16 v[90:93], v[196:199], v[146:149], v[90:93]
	v_mfma_f32_16x16x32_bf16 v[94:97], v[204:207], v[146:149], v[94:97]
	ds_read_b128 v[146:149], v216 offset:39936
	s_waitcnt lgkmcnt(7)
	v_mfma_f32_16x16x32_bf16 v[98:101], v[196:199], v[150:153], v[98:101]
	v_mfma_f32_16x16x32_bf16 v[102:105], v[204:207], v[150:153], v[102:105]
	ds_read_b128 v[150:153], v216 offset:41984
	s_waitcnt lgkmcnt(7)
	v_mfma_f32_16x16x32_bf16 v[106:109], v[196:199], v[154:157], v[106:109]
	v_mfma_f32_16x16x32_bf16 v[110:113], v[204:207], v[154:157], v[110:113]
	ds_read_b128 v[154:157], v216 offset:44032
	s_waitcnt lgkmcnt(7)
	v_mfma_f32_16x16x32_bf16 v[114:117], v[196:199], v[158:161], v[114:117]
	v_mfma_f32_16x16x32_bf16 v[118:121], v[204:207], v[158:161], v[118:121]
	ds_read_b128 v[158:161], v216 offset:46080
	s_waitcnt lgkmcnt(7)
	v_mfma_f32_16x16x32_bf16 v[122:125], v[196:199], v[162:165], v[122:125]
	v_mfma_f32_16x16x32_bf16 v[126:129], v[204:207], v[162:165], v[126:129]
	ds_read_b128 v[162:165], v216 offset:48128
	s_waitcnt lgkmcnt(7)
	v_mfma_f32_16x16x32_bf16 v[2:5], v[200:203], v[134:137], v[2:5]
	v_mfma_f32_16x16x32_bf16 v[6:9], v[212:215], v[134:137], v[6:9]
	ds_read_b128 v[134:137], v216 offset:50176
	s_waitcnt lgkmcnt(7)
	v_mfma_f32_16x16x32_bf16 v[10:13], v[200:203], v[138:141], v[10:13]
	v_mfma_f32_16x16x32_bf16 v[14:17], v[212:215], v[138:141], v[14:17]
	ds_read_b128 v[138:141], v216 offset:52224
	s_waitcnt lgkmcnt(7)
	v_mfma_f32_16x16x32_bf16 v[18:21], v[200:203], v[142:145], v[18:21]
	v_mfma_f32_16x16x32_bf16 v[22:25], v[212:215], v[142:145], v[22:25]
	ds_read_b128 v[142:145], v216 offset:54272
	s_waitcnt lgkmcnt(7)
	v_mfma_f32_16x16x32_bf16 v[26:29], v[200:203], v[146:149], v[26:29]
	v_mfma_f32_16x16x32_bf16 v[30:33], v[212:215], v[146:149], v[30:33]
	ds_read_b128 v[146:149], v216 offset:56320
	s_waitcnt lgkmcnt(7)
	v_mfma_f32_16x16x32_bf16 v[34:37], v[200:203], v[150:153], v[34:37]
	v_mfma_f32_16x16x32_bf16 v[38:41], v[212:215], v[150:153], v[38:41]
	ds_read_b128 v[150:153], v216 offset:58368
	s_waitcnt lgkmcnt(7)
	v_mfma_f32_16x16x32_bf16 v[42:45], v[200:203], v[154:157], v[42:45]
	v_mfma_f32_16x16x32_bf16 v[46:49], v[212:215], v[154:157], v[46:49]
	ds_read_b128 v[154:157], v216 offset:60416
	s_waitcnt lgkmcnt(7)
	v_mfma_f32_16x16x32_bf16 v[50:53], v[200:203], v[158:161], v[50:53]
	v_mfma_f32_16x16x32_bf16 v[54:57], v[212:215], v[158:161], v[54:57]
	ds_read_b128 v[158:161], v216 offset:62464
	s_waitcnt lgkmcnt(7)
	v_mfma_f32_16x16x32_bf16 v[58:61], v[200:203], v[162:165], v[58:61]
	v_mfma_f32_16x16x32_bf16 v[62:65], v[212:215], v[162:165], v[62:65]
	ds_read_b128 v[162:165], v216 offset:64512
	s_waitcnt vmcnt(4) lgkmcnt(0)
	s_barrier
	v_mfma_f32_16x16x32_bf16 v[66:69], v[200:203], v[134:137], v[66:69]
	s_add_u32 m0, s22, 0x8000
	v_mov_b32_e32 v223, v217
	global_load_lds_dwordx4 v223, s[6:7]
	v_mfma_f32_16x16x32_bf16 v[70:73], v[212:215], v[134:137], v[70:73]
	s_add_u32 m0, s22, 0x8400
	v_add_u32_e32 v224, 0x40, v217
	global_load_lds_dwordx4 v224, s[6:7]
	ds_read_b128 v[134:137], v216
	s_waitcnt lgkmcnt(7)
	v_mfma_f32_16x16x32_bf16 v[74:77], v[200:203], v[138:141], v[74:77]
	s_add_u32 m0, s22, 0x8800
	v_add_u32_e32 v223, 0x8000, v217
	global_load_lds_dwordx4 v223, s[6:7]
	v_mfma_f32_16x16x32_bf16 v[78:81], v[212:215], v[138:141], v[78:81]
	s_add_u32 m0, s22, 0x8c00
	v_add_u32_e32 v224, 0x8040, v217
	global_load_lds_dwordx4 v224, s[6:7]
	ds_read_b128 v[138:141], v216 offset:2048
	s_waitcnt lgkmcnt(7)
	v_mfma_f32_16x16x32_bf16 v[82:85], v[200:203], v[142:145], v[82:85]
	s_add_u32 m0, s22, 0x9000
	v_add_u32_e32 v223, 0x10000, v217
	global_load_lds_dwordx4 v223, s[6:7]
	v_mfma_f32_16x16x32_bf16 v[86:89], v[212:215], v[142:145], v[86:89]
	s_add_u32 m0, s22, 0x9400
	v_add_u32_e32 v224, 0x10040, v217
	global_load_lds_dwordx4 v224, s[6:7]
	ds_read_b128 v[142:145], v216 offset:4096
	s_waitcnt lgkmcnt(7)
	v_mfma_f32_16x16x32_bf16 v[90:93], v[200:203], v[146:149], v[90:93]
	s_add_u32 m0, s22, 0x9800
	v_add_u32_e32 v223, 0x18000, v217
	global_load_lds_dwordx4 v223, s[6:7]
	v_mfma_f32_16x16x32_bf16 v[94:97], v[212:215], v[146:149], v[94:97]
	s_add_u32 m0, s22, 0x9c00
	v_add_u32_e32 v224, 0x18040, v217
	global_load_lds_dwordx4 v224, s[6:7]
	ds_read_b128 v[146:149], v216 offset:6144
	s_waitcnt lgkmcnt(7)
	v_mfma_f32_16x16x32_bf16 v[98:101], v[200:203], v[150:153], v[98:101]
	v_mfma_f32_16x16x32_bf16 v[102:105], v[212:215], v[150:153], v[102:105]
	ds_read_b128 v[150:153], v216 offset:8192
	s_waitcnt lgkmcnt(7)
	v_mfma_f32_16x16x32_bf16 v[106:109], v[200:203], v[154:157], v[106:109]
	v_mfma_f32_16x16x32_bf16 v[110:113], v[212:215], v[154:157], v[110:113]
	ds_read_b128 v[154:157], v216 offset:10240
	s_waitcnt lgkmcnt(7)
	v_mfma_f32_16x16x32_bf16 v[114:117], v[200:203], v[158:161], v[114:117]
	v_mfma_f32_16x16x32_bf16 v[118:121], v[212:215], v[158:161], v[118:121]
	ds_read_b128 v[158:161], v216 offset:12288
	s_waitcnt lgkmcnt(7)
	v_mfma_f32_16x16x32_bf16 v[122:125], v[200:203], v[162:165], v[122:125]
	v_mfma_f32_16x16x32_bf16 v[126:129], v[212:215], v[162:165], v[126:129]
	v_add_u32_e32 v217, 0x80, v217
	v_add_u32_e32 v220, 0x800, v220
	v_add_u32_e32 v221, 0x800, v221
	s_sub_u32 s16, s16, 1
	s_cmp_lg_u32 s16, 0
	s_cbranch_scc1 .Lg256b_w1_loop
	s_add_u32 s12, s12, s83
.Lg256b_w1_next_retry:
	s_cmp_ge_u32 s12, 256
	s_cbranch_scc1 .Lg256b_w1_nonext
	s_lshr_b32 s3, s12, 6
	s_lshl_b32 s3, s3, 3
	s_add_u32 s3, s3, s65
	s_lshr_b32 s17, s3, 2
	s_and_b32 s3, s3, 3
	s_lshl_b32 s17, s17, 3
	s_bfe_u32 s23, s12, 0x30003
	s_add_u32 s13, s17, s23
	s_lshl_b32 s3, s3, 3
	s_and_b32 s23, s12, 7
	s_add_u32 s14, s3, s23
	s_lshl_b32 s13, s13, 8
	s_lshl_b32 s14, s14, 7
	s_lshl_b32 s3, s15, 6
	s_add_u32 s17, s3, s13
	s_mul_i32 s17, s17, 0x800
	s_add_u32 s6, s18, s17
	s_addc_u32 s7, s19, 0
	v_mov_b32_e32 v217, v218
	ds_read_b128 v[162:165], v216 offset:14336
	s_waitcnt vmcnt(8) lgkmcnt(7)
	v_mfma_f32_16x16x32_bf16 v[2:5], v[166:169], v[134:137], v[2:5]
	v_mfma_f32_16x16x32_bf16 v[6:9], v[174:177], v[134:137], v[6:9]
	ds_read_b128 v[134:137], v216 offset:16384
	s_waitcnt lgkmcnt(7)
	v_mfma_f32_16x16x32_bf16 v[10:13], v[166:169], v[138:141], v[10:13]
	v_mfma_f32_16x16x32_bf16 v[14:17], v[174:177], v[138:141], v[14:17]
	ds_read_b128 v[138:141], v216 offset:18432
	s_waitcnt lgkmcnt(7)
	v_mfma_f32_16x16x32_bf16 v[18:21], v[166:169], v[142:145], v[18:21]
	v_mfma_f32_16x16x32_bf16 v[22:25], v[174:177], v[142:145], v[22:25]
	ds_read_b128 v[142:145], v216 offset:20480
	s_waitcnt lgkmcnt(7)
	v_mfma_f32_16x16x32_bf16 v[26:29], v[166:169], v[146:149], v[26:29]
	v_mfma_f32_16x16x32_bf16 v[30:33], v[174:177], v[146:149], v[30:33]
	ds_read_b128 v[146:149], v216 offset:22528
	s_waitcnt lgkmcnt(7)
	v_mfma_f32_16x16x32_bf16 v[34:37], v[166:169], v[150:153], v[34:37]
	global_load_dwordx4 v[196:199], v220, s[8:9]
	v_mfma_f32_16x16x32_bf16 v[38:41], v[174:177], v[150:153], v[38:41]
	ds_read_b128 v[150:153], v216 offset:24576
	s_waitcnt lgkmcnt(7)
	v_mfma_f32_16x16x32_bf16 v[42:45], v[166:169], v[154:157], v[42:45]
	global_load_dwordx4 v[200:203], v220, s[8:9] offset:1024
	v_mfma_f32_16x16x32_bf16 v[46:49], v[174:177], v[154:157], v[46:49]
	ds_read_b128 v[154:157], v216 offset:26624
	s_waitcnt lgkmcnt(7)
	v_mfma_f32_16x16x32_bf16 v[50:53], v[166:169], v[158:161], v[50:53]
	global_load_dwordx4 v[204:207], v221, s[8:9]
	v_mfma_f32_16x16x32_bf16 v[54:57], v[174:177], v[158:161], v[54:57]
	ds_read_b128 v[158:161], v216 offset:28672
	s_waitcnt lgkmcnt(7)
	v_mfma_f32_16x16x32_bf16 v[58:61], v[166:169], v[162:165], v[58:61]
	global_load_dwordx4 v[212:215], v221, s[8:9] offset:1024
	v_mfma_f32_16x16x32_bf16 v[62:65], v[174:177], v[162:165], v[62:65]
	ds_read_b128 v[162:165], v216 offset:30720
	s_waitcnt lgkmcnt(7)
	v_mfma_f32_16x16x32_bf16 v[66:69], v[166:169], v[134:137], v[66:69]
	v_mfma_f32_16x16x32_bf16 v[70:73], v[174:177], v[134:137], v[70:73]
	ds_read_b128 v[134:137], v216 offset:1024
	s_waitcnt lgkmcnt(7)
	v_mfma_f32_16x16x32_bf16 v[74:77], v[166:169], v[138:141], v[74:77]
	v_mfma_f32_16x16x32_bf16 v[78:81], v[174:177], v[138:141], v[78:81]
	ds_read_b128 v[138:141], v216 offset:3072
	s_waitcnt lgkmcnt(7)
	v_mfma_f32_16x16x32_bf16 v[82:85], v[166:169], v[142:145], v[82:85]
	v_mfma_f32_16x16x32_bf16 v[86:89], v[174:177], v[142:145], v[86:89]
	ds_read_b128 v[142:145], v216 offset:5120
	s_waitcnt lgkmcnt(7)
	v_mfma_f32_16x16x32_bf16 v[90:93], v[166:169], v[146:149], v[90:93]
	v_mfma_f32_16x16x32_bf16 v[94:97], v[174:177], v[146:149], v[94:97]
	ds_read_b128 v[146:149], v216 offset:7168
	s_waitcnt lgkmcnt(7)
	v_mfma_f32_16x16x32_bf16 v[98:101], v[166:169], v[150:153], v[98:101]
	v_mfma_f32_16x16x32_bf16 v[102:105], v[174:177], v[150:153], v[102:105]
	ds_read_b128 v[150:153], v216 offset:9216
	s_waitcnt lgkmcnt(7)
	v_mfma_f32_16x16x32_bf16 v[106:109], v[166:169], v[154:157], v[106:109]
	v_mfma_f32_16x16x32_bf16 v[110:113], v[174:177], v[154:157], v[110:113]
	ds_read_b128 v[154:157], v216 offset:11264
	s_waitcnt lgkmcnt(7)
	v_mfma_f32_16x16x32_bf16 v[114:117], v[166:169], v[158:161], v[114:117]
	v_mfma_f32_16x16x32_bf16 v[118:121], v[174:177], v[158:161], v[118:121]
	ds_read_b128 v[158:161], v216 offset:13312
	s_waitcnt lgkmcnt(7)
	v_mfma_f32_16x16x32_bf16 v[122:125], v[166:169], v[162:165], v[122:125]
	v_mfma_f32_16x16x32_bf16 v[126:129], v[174:177], v[162:165], v[126:129]
	ds_read_b128 v[162:165], v216 offset:15360
	s_waitcnt lgkmcnt(7)
	v_mfma_f32_16x16x32_bf16 v[2:5], v[170:173], v[134:137], v[2:5]
	v_mfma_f32_16x16x32_bf16 v[6:9], v[178:181], v[134:137], v[6:9]
	ds_read_b128 v[134:137], v216 offset:17408
	s_waitcnt lgkmcnt(7)
	v_mfma_f32_16x16x32_bf16 v[10:13], v[170:173], v[138:141], v[10:13]
	v_mfma_f32_16x16x32_bf16 v[14:17], v[178:181], v[138:141], v[14:17]
	ds_read_b128 v[138:141], v216 offset:19456
	s_waitcnt lgkmcnt(7)
	v_mfma_f32_16x16x32_bf16 v[18:21], v[170:173], v[142:145], v[18:21]
	v_mfma_f32_16x16x32_bf16 v[22:25], v[178:181], v[142:145], v[22:25]
	ds_read_b128 v[142:145], v216 offset:21504
	s_waitcnt lgkmcnt(7)
	v_mfma_f32_16x16x32_bf16 v[26:29], v[170:173], v[146:149], v[26:29]
	v_mfma_f32_16x16x32_bf16 v[30:33], v[178:181], v[146:149], v[30:33]
	ds_read_b128 v[146:149], v216 offset:23552
	s_waitcnt lgkmcnt(7)
	v_mfma_f32_16x16x32_bf16 v[34:37], v[170:173], v[150:153], v[34:37]
	v_mfma_f32_16x16x32_bf16 v[38:41], v[178:181], v[150:153], v[38:41]
	ds_read_b128 v[150:153], v216 offset:25600
	s_waitcnt lgkmcnt(7)
	v_mfma_f32_16x16x32_bf16 v[42:45], v[170:173], v[154:157], v[42:45]
	v_mfma_f32_16x16x32_bf16 v[46:49], v[178:181], v[154:157], v[46:49]
	ds_read_b128 v[154:157], v216 offset:27648
	s_waitcnt lgkmcnt(7)
	v_mfma_f32_16x16x32_bf16 v[50:53], v[170:173], v[158:161], v[50:53]
	v_mfma_f32_16x16x32_bf16 v[54:57], v[178:181], v[158:161], v[54:57]
	ds_read_b128 v[158:161], v216 offset:29696
	s_waitcnt lgkmcnt(7)
	v_mfma_f32_16x16x32_bf16 v[58:61], v[170:173], v[162:165], v[58:61]
	v_mfma_f32_16x16x32_bf16 v[62:65], v[178:181], v[162:165], v[62:65]
	ds_read_b128 v[162:165], v216 offset:31744
	s_waitcnt vmcnt(4) lgkmcnt(0)
	s_barrier
	v_mfma_f32_16x16x32_bf16 v[66:69], v[170:173], v[134:137], v[66:69]
	s_add_u32 m0, s22, 0x0
	v_mov_b32_e32 v223, v217
	global_load_lds_dwordx4 v223, s[6:7]
	v_mfma_f32_16x16x32_bf16 v[70:73], v[178:181], v[134:137], v[70:73]
	s_add_u32 m0, s22, 0x400
	v_add_u32_e32 v224, 0x40, v217
	global_load_lds_dwordx4 v224, s[6:7]
	ds_read_b128 v[134:137], v216 offset:32768
	s_waitcnt lgkmcnt(7)
	v_mfma_f32_16x16x32_bf16 v[74:77], v[170:173], v[138:141], v[74:77]
	s_add_u32 m0, s22, 0x800
	v_add_u32_e32 v223, 0x8000, v217
	global_load_lds_dwordx4 v223, s[6:7]
	v_mfma_f32_16x16x32_bf16 v[78:81], v[178:181], v[138:141], v[78:81]
	s_add_u32 m0, s22, 0xc00
	v_add_u32_e32 v224, 0x8040, v217
	global_load_lds_dwordx4 v224, s[6:7]
	ds_read_b128 v[138:141], v216 offset:34816
	s_waitcnt lgkmcnt(7)
	v_mfma_f32_16x16x32_bf16 v[82:85], v[170:173], v[142:145], v[82:85]
	s_add_u32 m0, s22, 0x1000
	v_add_u32_e32 v223, 0x10000, v217
	global_load_lds_dwordx4 v223, s[6:7]
	v_mfma_f32_16x16x32_bf16 v[86:89], v[178:181], v[142:145], v[86:89]
	s_add_u32 m0, s22, 0x1400
	v_add_u32_e32 v224, 0x10040, v217
	global_load_lds_dwordx4 v224, s[6:7]
	ds_read_b128 v[142:145], v216 offset:36864
	s_waitcnt lgkmcnt(7)
	v_mfma_f32_16x16x32_bf16 v[90:93], v[170:173], v[146:149], v[90:93]
	s_add_u32 m0, s22, 0x1800
	v_add_u32_e32 v223, 0x18000, v217
	global_load_lds_dwordx4 v223, s[6:7]
	v_mfma_f32_16x16x32_bf16 v[94:97], v[178:181], v[146:149], v[94:97]
	s_add_u32 m0, s22, 0x1c00
	v_add_u32_e32 v224, 0x18040, v217
	global_load_lds_dwordx4 v224, s[6:7]
	ds_read_b128 v[146:149], v216 offset:38912
	s_waitcnt lgkmcnt(7)
	v_mfma_f32_16x16x32_bf16 v[98:101], v[170:173], v[150:153], v[98:101]
	v_mfma_f32_16x16x32_bf16 v[102:105], v[178:181], v[150:153], v[102:105]
	ds_read_b128 v[150:153], v216 offset:40960
	s_waitcnt lgkmcnt(7)
	v_mfma_f32_16x16x32_bf16 v[106:109], v[170:173], v[154:157], v[106:109]
	v_mfma_f32_16x16x32_bf16 v[110:113], v[178:181], v[154:157], v[110:113]
	ds_read_b128 v[154:157], v216 offset:43008
	s_waitcnt lgkmcnt(7)
	v_mfma_f32_16x16x32_bf16 v[114:117], v[170:173], v[158:161], v[114:117]
	v_mfma_f32_16x16x32_bf16 v[118:121], v[178:181], v[158:161], v[118:121]
	ds_read_b128 v[158:161], v216 offset:45056
	s_waitcnt lgkmcnt(7)
	v_mfma_f32_16x16x32_bf16 v[122:125], v[170:173], v[162:165], v[122:125]
	v_mfma_f32_16x16x32_bf16 v[126:129], v[178:181], v[162:165], v[126:129]
	v_add_u32_e32 v217, 0x80, v217
	v_add_u32_e32 v220, 0x800, v220
	v_add_u32_e32 v221, 0x800, v221
	s_lshr_b32 s3, s14, 4
	s_lshl_b32 s17, s15, 1
	s_add_u32 s3, s3, s17
	s_mul_i32 s17, s3, 0x8000
	s_add_u32 s8, s20, s17
	s_addc_u32 s9, s21, 0
	v_mov_b32_e32 v220, v222
	v_add_u32_e32 v221, 0x8000, v222
	ds_read_b128 v[162:165], v216 offset:47104
	s_waitcnt vmcnt(8) lgkmcnt(7)
	v_mfma_f32_16x16x32_bf16 v[2:5], v[196:199], v[134:137], v[2:5]
	v_mfma_f32_16x16x32_bf16 v[6:9], v[204:207], v[134:137], v[6:9]
	ds_read_b128 v[134:137], v216 offset:49152
	s_waitcnt lgkmcnt(7)
	v_mfma_f32_16x16x32_bf16 v[10:13], v[196:199], v[138:141], v[10:13]
	v_mfma_f32_16x16x32_bf16 v[14:17], v[204:207], v[138:141], v[14:17]
	ds_read_b128 v[138:141], v216 offset:51200
	s_waitcnt lgkmcnt(7)
	v_mfma_f32_16x16x32_bf16 v[18:21], v[196:199], v[142:145], v[18:21]
	v_mfma_f32_16x16x32_bf16 v[22:25], v[204:207], v[142:145], v[22:25]
	ds_read_b128 v[142:145], v216 offset:53248
	s_waitcnt lgkmcnt(7)
	v_mfma_f32_16x16x32_bf16 v[26:29], v[196:199], v[146:149], v[26:29]
	v_mfma_f32_16x16x32_bf16 v[30:33], v[204:207], v[146:149], v[30:33]
	ds_read_b128 v[146:149], v216 offset:55296
	s_waitcnt lgkmcnt(7)
	v_mfma_f32_16x16x32_bf16 v[34:37], v[196:199], v[150:153], v[34:37]
	global_load_dwordx4 v[166:169], v220, s[8:9]
	v_mfma_f32_16x16x32_bf16 v[38:41], v[204:207], v[150:153], v[38:41]
	ds_read_b128 v[150:153], v216 offset:57344
	s_waitcnt lgkmcnt(7)
	v_mfma_f32_16x16x32_bf16 v[42:45], v[196:199], v[154:157], v[42:45]
	global_load_dwordx4 v[170:173], v220, s[8:9] offset:1024
	v_mfma_f32_16x16x32_bf16 v[46:49], v[204:207], v[154:157], v[46:49]
	ds_read_b128 v[154:157], v216 offset:59392
	s_waitcnt lgkmcnt(7)
	v_mfma_f32_16x16x32_bf16 v[50:53], v[196:199], v[158:161], v[50:53]
	global_load_dwordx4 v[174:177], v221, s[8:9]
	v_mfma_f32_16x16x32_bf16 v[54:57], v[204:207], v[158:161], v[54:57]
	ds_read_b128 v[158:161], v216 offset:61440
	s_waitcnt lgkmcnt(7)
	v_mfma_f32_16x16x32_bf16 v[58:61], v[196:199], v[162:165], v[58:61]
	global_load_dwordx4 v[178:181], v221, s[8:9] offset:1024
	v_mfma_f32_16x16x32_bf16 v[62:65], v[204:207], v[162:165], v[62:65]
	ds_read_b128 v[162:165], v216 offset:63488
	s_waitcnt lgkmcnt(7)
	v_mfma_f32_16x16x32_bf16 v[66:69], v[196:199], v[134:137], v[66:69]
	v_mfma_f32_16x16x32_bf16 v[70:73], v[204:207], v[134:137], v[70:73]
	ds_read_b128 v[134:137], v216 offset:33792
	s_waitcnt lgkmcnt(7)
	v_mfma_f32_16x16x32_bf16 v[74:77], v[196:199], v[138:141], v[74:77]
	v_mfma_f32_16x16x32_bf16 v[78:81], v[204:207], v[138:141], v[78:81]
	ds_read_b128 v[138:141], v216 offset:35840
	s_waitcnt lgkmcnt(7)
	v_mfma_f32_16x16x32_bf16 v[82:85], v[196:199], v[142:145], v[82:85]
	v_mfma_f32_16x16x32_bf16 v[86:89], v[204:207], v[142:145], v[86:89]
	ds_read_b128 v[142:145], v216 offset:37888
	s_waitcnt lgkmcnt(7)
	v_mfma_f32_16x16x32_bf16 v[90:93], v[196:199], v[146:149], v[90:93]
	v_mfma_f32_16x16x32_bf16 v[94:97], v[204:207], v[146:149], v[94:97]
	ds_read_b128 v[146:149], v216 offset:39936
	s_waitcnt lgkmcnt(7)
	v_mfma_f32_16x16x32_bf16 v[98:101], v[196:199], v[150:153], v[98:101]
	v_mfma_f32_16x16x32_bf16 v[102:105], v[204:207], v[150:153], v[102:105]
	ds_read_b128 v[150:153], v216 offset:41984
	s_waitcnt lgkmcnt(7)
	v_mfma_f32_16x16x32_bf16 v[106:109], v[196:199], v[154:157], v[106:109]
	v_mfma_f32_16x16x32_bf16 v[110:113], v[204:207], v[154:157], v[110:113]
	ds_read_b128 v[154:157], v216 offset:44032
	s_waitcnt lgkmcnt(7)
	v_mfma_f32_16x16x32_bf16 v[114:117], v[196:199], v[158:161], v[114:117]
	v_mfma_f32_16x16x32_bf16 v[118:121], v[204:207], v[158:161], v[118:121]
	ds_read_b128 v[158:161], v216 offset:46080
	s_waitcnt lgkmcnt(7)
	v_mfma_f32_16x16x32_bf16 v[122:125], v[196:199], v[162:165], v[122:125]
	v_mfma_f32_16x16x32_bf16 v[126:129], v[204:207], v[162:165], v[126:129]
	ds_read_b128 v[162:165], v216 offset:48128
	s_waitcnt lgkmcnt(7)
	v_mfma_f32_16x16x32_bf16 v[2:5], v[200:203], v[134:137], v[2:5]
	v_mfma_f32_16x16x32_bf16 v[6:9], v[212:215], v[134:137], v[6:9]
	ds_read_b128 v[134:137], v216 offset:50176
	s_waitcnt lgkmcnt(7)
	v_mfma_f32_16x16x32_bf16 v[10:13], v[200:203], v[138:141], v[10:13]
	v_mfma_f32_16x16x32_bf16 v[14:17], v[212:215], v[138:141], v[14:17]
	ds_read_b128 v[138:141], v216 offset:52224
	s_waitcnt lgkmcnt(7)
	v_mfma_f32_16x16x32_bf16 v[18:21], v[200:203], v[142:145], v[18:21]
	v_mfma_f32_16x16x32_bf16 v[22:25], v[212:215], v[142:145], v[22:25]
	ds_read_b128 v[142:145], v216 offset:54272
	s_waitcnt lgkmcnt(7)
	v_mfma_f32_16x16x32_bf16 v[26:29], v[200:203], v[146:149], v[26:29]
	v_mfma_f32_16x16x32_bf16 v[30:33], v[212:215], v[146:149], v[30:33]
	ds_read_b128 v[146:149], v216 offset:56320
	s_waitcnt lgkmcnt(7)
	v_mfma_f32_16x16x32_bf16 v[34:37], v[200:203], v[150:153], v[34:37]
	v_mfma_f32_16x16x32_bf16 v[38:41], v[212:215], v[150:153], v[38:41]
	ds_read_b128 v[150:153], v216 offset:58368
	s_waitcnt lgkmcnt(7)
	v_mfma_f32_16x16x32_bf16 v[42:45], v[200:203], v[154:157], v[42:45]
	v_mfma_f32_16x16x32_bf16 v[46:49], v[212:215], v[154:157], v[46:49]
	ds_read_b128 v[154:157], v216 offset:60416
	s_waitcnt lgkmcnt(7)
	v_mfma_f32_16x16x32_bf16 v[50:53], v[200:203], v[158:161], v[50:53]
	v_mfma_f32_16x16x32_bf16 v[54:57], v[212:215], v[158:161], v[54:57]
	ds_read_b128 v[158:161], v216 offset:62464
	s_waitcnt lgkmcnt(7)
	v_mfma_f32_16x16x32_bf16 v[58:61], v[200:203], v[162:165], v[58:61]
	v_mfma_f32_16x16x32_bf16 v[62:65], v[212:215], v[162:165], v[62:65]
	ds_read_b128 v[162:165], v216 offset:64512
	s_waitcnt vmcnt(4) lgkmcnt(0)
	s_barrier
	v_mfma_f32_16x16x32_bf16 v[66:69], v[200:203], v[134:137], v[66:69]
	s_add_u32 m0, s22, 0x8000
	v_mov_b32_e32 v223, v217
	global_load_lds_dwordx4 v223, s[6:7]
	v_mfma_f32_16x16x32_bf16 v[70:73], v[212:215], v[134:137], v[70:73]
	s_add_u32 m0, s22, 0x8400
	v_add_u32_e32 v224, 0x40, v217
	global_load_lds_dwordx4 v224, s[6:7]
	ds_read_b128 v[134:137], v216
	s_waitcnt lgkmcnt(7)
	v_mfma_f32_16x16x32_bf16 v[74:77], v[200:203], v[138:141], v[74:77]
	s_add_u32 m0, s22, 0x8800
	v_add_u32_e32 v223, 0x8000, v217
	global_load_lds_dwordx4 v223, s[6:7]
	v_mfma_f32_16x16x32_bf16 v[78:81], v[212:215], v[138:141], v[78:81]
	s_add_u32 m0, s22, 0x8c00
	v_add_u32_e32 v224, 0x8040, v217
	global_load_lds_dwordx4 v224, s[6:7]
	ds_read_b128 v[138:141], v216 offset:2048
	s_waitcnt lgkmcnt(7)
	v_mfma_f32_16x16x32_bf16 v[82:85], v[200:203], v[142:145], v[82:85]
	s_add_u32 m0, s22, 0x9000
	v_add_u32_e32 v223, 0x10000, v217
	global_load_lds_dwordx4 v223, s[6:7]
	v_mfma_f32_16x16x32_bf16 v[86:89], v[212:215], v[142:145], v[86:89]
	s_add_u32 m0, s22, 0x9400
	v_add_u32_e32 v224, 0x10040, v217
	global_load_lds_dwordx4 v224, s[6:7]
	ds_read_b128 v[142:145], v216 offset:4096
	s_waitcnt lgkmcnt(7)
	v_mfma_f32_16x16x32_bf16 v[90:93], v[200:203], v[146:149], v[90:93]
	s_add_u32 m0, s22, 0x9800
	v_add_u32_e32 v223, 0x18000, v217
	global_load_lds_dwordx4 v223, s[6:7]
	v_mfma_f32_16x16x32_bf16 v[94:97], v[212:215], v[146:149], v[94:97]
	s_add_u32 m0, s22, 0x9c00
	v_add_u32_e32 v224, 0x18040, v217
	global_load_lds_dwordx4 v224, s[6:7]
	ds_read_b128 v[146:149], v216 offset:6144
	s_waitcnt lgkmcnt(7)
	v_mfma_f32_16x16x32_bf16 v[98:101], v[200:203], v[150:153], v[98:101]
	v_mfma_f32_16x16x32_bf16 v[102:105], v[212:215], v[150:153], v[102:105]
	ds_read_b128 v[150:153], v216 offset:8192
	s_waitcnt lgkmcnt(7)
	v_mfma_f32_16x16x32_bf16 v[106:109], v[200:203], v[154:157], v[106:109]
	v_mfma_f32_16x16x32_bf16 v[110:113], v[212:215], v[154:157], v[110:113]
	ds_read_b128 v[154:157], v216 offset:10240
	s_waitcnt lgkmcnt(7)
	v_mfma_f32_16x16x32_bf16 v[114:117], v[200:203], v[158:161], v[114:117]
	v_mfma_f32_16x16x32_bf16 v[118:121], v[212:215], v[158:161], v[118:121]
	ds_read_b128 v[158:161], v216 offset:12288
	s_waitcnt lgkmcnt(7)
	v_mfma_f32_16x16x32_bf16 v[122:125], v[200:203], v[162:165], v[122:125]
	v_mfma_f32_16x16x32_bf16 v[126:129], v[212:215], v[162:165], v[126:129]
	v_add_u32_e32 v217, 0x80, v217
	v_add_u32_e32 v220, 0x800, v220
	v_add_u32_e32 v221, 0x800, v221
	s_mov_b32 s16, 1
	s_branch .Lg256b_w1_epi

.Lg256b_wo_x_go:
	ds_read_b128 v[162:165], v216 offset:14336
	s_waitcnt vmcnt(16) lgkmcnt(7)
	v_mfma_f32_16x16x32_bf16 v[2:5], v[166:169], v[134:137], 0
	v_mfma_f32_16x16x32_bf16 v[6:9], v[174:177], v[134:137], 0
	ds_read_b128 v[134:137], v216 offset:16384
	s_waitcnt lgkmcnt(7)
	v_mfma_f32_16x16x32_bf16 v[10:13], v[166:169], v[138:141], 0
	v_mfma_f32_16x16x32_bf16 v[14:17], v[174:177], v[138:141], 0
	ds_read_b128 v[138:141], v216 offset:18432
	s_waitcnt lgkmcnt(7)
	v_mfma_f32_16x16x32_bf16 v[18:21], v[166:169], v[142:145], 0
	v_mfma_f32_16x16x32_bf16 v[22:25], v[174:177], v[142:145], 0
	ds_read_b128 v[142:145], v216 offset:20480
	s_waitcnt lgkmcnt(7)
	v_mfma_f32_16x16x32_bf16 v[26:29], v[166:169], v[146:149], 0
	v_mfma_f32_16x16x32_bf16 v[30:33], v[174:177], v[146:149], 0
	ds_read_b128 v[146:149], v216 offset:22528
	s_waitcnt lgkmcnt(7)
	v_mfma_f32_16x16x32_bf16 v[34:37], v[166:169], v[150:153], 0
	global_load_dwordx4 v[196:199], v220, s[8:9]
	v_mfma_f32_16x16x32_bf16 v[38:41], v[174:177], v[150:153], 0
	ds_read_b128 v[150:153], v216 offset:24576
	s_waitcnt lgkmcnt(7)
	v_mfma_f32_16x16x32_bf16 v[42:45], v[166:169], v[154:157], 0
	global_load_dwordx4 v[200:203], v220, s[8:9] offset:1024
	v_mfma_f32_16x16x32_bf16 v[46:49], v[174:177], v[154:157], 0
	ds_read_b128 v[154:157], v216 offset:26624
	s_waitcnt lgkmcnt(7)
	v_mfma_f32_16x16x32_bf16 v[50:53], v[166:169], v[158:161], 0
	global_load_dwordx4 v[204:207], v221, s[8:9]
	v_mfma_f32_16x16x32_bf16 v[54:57], v[174:177], v[158:161], 0
	ds_read_b128 v[158:161], v216 offset:28672
	s_waitcnt lgkmcnt(7)
	v_mfma_f32_16x16x32_bf16 v[58:61], v[166:169], v[162:165], 0
	global_load_dwordx4 v[212:215], v221, s[8:9] offset:1024
	v_mfma_f32_16x16x32_bf16 v[62:65], v[174:177], v[162:165], 0
	ds_read_b128 v[162:165], v216 offset:30720
	s_waitcnt lgkmcnt(7)
	v_mfma_f32_16x16x32_bf16 v[66:69], v[166:169], v[134:137], 0
	v_mfma_f32_16x16x32_bf16 v[70:73], v[174:177], v[134:137], 0
	ds_read_b128 v[134:137], v216 offset:1024
	s_waitcnt lgkmcnt(7)
	v_mfma_f32_16x16x32_bf16 v[74:77], v[166:169], v[138:141], 0
	v_mfma_f32_16x16x32_bf16 v[78:81], v[174:177], v[138:141], 0
	ds_read_b128 v[138:141], v216 offset:3072
	s_waitcnt lgkmcnt(7)
	v_mfma_f32_16x16x32_bf16 v[82:85], v[166:169], v[142:145], 0
	v_mfma_f32_16x16x32_bf16 v[86:89], v[174:177], v[142:145], 0
	ds_read_b128 v[142:145], v216 offset:5120
	s_waitcnt lgkmcnt(7)
	v_mfma_f32_16x16x32_bf16 v[90:93], v[166:169], v[146:149], 0
	v_mfma_f32_16x16x32_bf16 v[94:97], v[174:177], v[146:149], 0
	ds_read_b128 v[146:149], v216 offset:7168
	s_waitcnt lgkmcnt(7)
	v_mfma_f32_16x16x32_bf16 v[98:101], v[166:169], v[150:153], 0
	v_mfma_f32_16x16x32_bf16 v[102:105], v[174:177], v[150:153], 0
	ds_read_b128 v[150:153], v216 offset:9216
	s_waitcnt lgkmcnt(7)
	v_mfma_f32_16x16x32_bf16 v[106:109], v[166:169], v[154:157], 0
	v_mfma_f32_16x16x32_bf16 v[110:113], v[174:177], v[154:157], 0
	ds_read_b128 v[154:157], v216 offset:11264
	s_waitcnt lgkmcnt(7)
	v_mfma_f32_16x16x32_bf16 v[114:117], v[166:169], v[158:161], 0
	v_mfma_f32_16x16x32_bf16 v[118:121], v[174:177], v[158:161], 0
	ds_read_b128 v[158:161], v216 offset:13312
	s_waitcnt lgkmcnt(7)
	v_mfma_f32_16x16x32_bf16 v[122:125], v[166:169], v[162:165], 0
	v_mfma_f32_16x16x32_bf16 v[126:129], v[174:177], v[162:165], 0
	ds_read_b128 v[162:165], v216 offset:15360
	s_waitcnt lgkmcnt(7)
	v_mfma_f32_16x16x32_bf16 v[2:5], v[170:173], v[134:137], v[2:5]
	v_mfma_f32_16x16x32_bf16 v[6:9], v[178:181], v[134:137], v[6:9]
	ds_read_b128 v[134:137], v216 offset:17408
	s_waitcnt lgkmcnt(7)
	v_mfma_f32_16x16x32_bf16 v[10:13], v[170:173], v[138:141], v[10:13]
	v_mfma_f32_16x16x32_bf16 v[14:17], v[178:181], v[138:141], v[14:17]
	ds_read_b128 v[138:141], v216 offset:19456
	s_waitcnt lgkmcnt(7)
	v_mfma_f32_16x16x32_bf16 v[18:21], v[170:173], v[142:145], v[18:21]
	v_mfma_f32_16x16x32_bf16 v[22:25], v[178:181], v[142:145], v[22:25]
	ds_read_b128 v[142:145], v216 offset:21504
	s_waitcnt lgkmcnt(7)
	v_mfma_f32_16x16x32_bf16 v[26:29], v[170:173], v[146:149], v[26:29]
	v_mfma_f32_16x16x32_bf16 v[30:33], v[178:181], v[146:149], v[30:33]
	ds_read_b128 v[146:149], v216 offset:23552
	s_waitcnt lgkmcnt(7)
	v_mfma_f32_16x16x32_bf16 v[34:37], v[170:173], v[150:153], v[34:37]
	v_mfma_f32_16x16x32_bf16 v[38:41], v[178:181], v[150:153], v[38:41]
	ds_read_b128 v[150:153], v216 offset:25600
	s_waitcnt lgkmcnt(7)
	v_mfma_f32_16x16x32_bf16 v[42:45], v[170:173], v[154:157], v[42:45]
	v_mfma_f32_16x16x32_bf16 v[46:49], v[178:181], v[154:157], v[46:49]
	ds_read_b128 v[154:157], v216 offset:27648
	s_waitcnt lgkmcnt(7)
	v_mfma_f32_16x16x32_bf16 v[50:53], v[170:173], v[158:161], v[50:53]
	v_mfma_f32_16x16x32_bf16 v[54:57], v[178:181], v[158:161], v[54:57]
	ds_read_b128 v[158:161], v216 offset:29696
	s_waitcnt lgkmcnt(7)
	v_mfma_f32_16x16x32_bf16 v[58:61], v[170:173], v[162:165], v[58:61]
	v_mfma_f32_16x16x32_bf16 v[62:65], v[178:181], v[162:165], v[62:65]
	ds_read_b128 v[162:165], v216 offset:31744
	s_waitcnt vmcnt(12) lgkmcnt(0)
	s_barrier
	v_mfma_f32_16x16x32_bf16 v[66:69], v[170:173], v[134:137], v[66:69]
	s_add_u32 m0, s22, 0x0
	v_mov_b32_e32 v223, v217
	global_load_lds_dwordx4 v223, s[6:7]
	v_mfma_f32_16x16x32_bf16 v[70:73], v[178:181], v[134:137], v[70:73]
	s_add_u32 m0, s22, 0x400
	v_add_u32_e32 v224, 0x40, v217
	global_load_lds_dwordx4 v224, s[6:7]
	ds_read_b128 v[134:137], v216 offset:32768
	s_waitcnt lgkmcnt(7)
	v_mfma_f32_16x16x32_bf16 v[74:77], v[170:173], v[138:141], v[74:77]
	s_add_u32 m0, s22, 0x800
	v_add_u32_e32 v223, 0x8000, v217
	global_load_lds_dwordx4 v223, s[6:7]
	v_mfma_f32_16x16x32_bf16 v[78:81], v[178:181], v[138:141], v[78:81]
	s_add_u32 m0, s22, 0xc00
	v_add_u32_e32 v224, 0x8040, v217
	global_load_lds_dwordx4 v224, s[6:7]
	ds_read_b128 v[138:141], v216 offset:34816
	s_waitcnt lgkmcnt(7)
	v_mfma_f32_16x16x32_bf16 v[82:85], v[170:173], v[142:145], v[82:85]
	s_add_u32 m0, s22, 0x1000
	v_add_u32_e32 v223, 0x10000, v217
	global_load_lds_dwordx4 v223, s[6:7]
	v_mfma_f32_16x16x32_bf16 v[86:89], v[178:181], v[142:145], v[86:89]
	s_add_u32 m0, s22, 0x1400
	v_add_u32_e32 v224, 0x10040, v217
	global_load_lds_dwordx4 v224, s[6:7]
	ds_read_b128 v[142:145], v216 offset:36864
	s_waitcnt lgkmcnt(7)
	v_mfma_f32_16x16x32_bf16 v[90:93], v[170:173], v[146:149], v[90:93]
	s_add_u32 m0, s22, 0x1800
	v_add_u32_e32 v223, 0x18000, v217
	global_load_lds_dwordx4 v223, s[6:7]
	v_mfma_f32_16x16x32_bf16 v[94:97], v[178:181], v[146:149], v[94:97]
	s_add_u32 m0, s22, 0x1c00
	v_add_u32_e32 v224, 0x18040, v217
	global_load_lds_dwordx4 v224, s[6:7]
	ds_read_b128 v[146:149], v216 offset:38912
	s_waitcnt lgkmcnt(7)
	v_mfma_f32_16x16x32_bf16 v[98:101], v[170:173], v[150:153], v[98:101]
	v_mfma_f32_16x16x32_bf16 v[102:105], v[178:181], v[150:153], v[102:105]
	ds_read_b128 v[150:153], v216 offset:40960
	s_waitcnt lgkmcnt(7)
	v_mfma_f32_16x16x32_bf16 v[106:109], v[170:173], v[154:157], v[106:109]
	v_mfma_f32_16x16x32_bf16 v[110:113], v[178:181], v[154:157], v[110:113]
	ds_read_b128 v[154:157], v216 offset:43008
	s_waitcnt lgkmcnt(7)
	v_mfma_f32_16x16x32_bf16 v[114:117], v[170:173], v[158:161], v[114:117]
	v_mfma_f32_16x16x32_bf16 v[118:121], v[178:181], v[158:161], v[118:121]
	ds_read_b128 v[158:161], v216 offset:45056
	s_waitcnt lgkmcnt(7)
	v_mfma_f32_16x16x32_bf16 v[122:125], v[170:173], v[162:165], v[122:125]
	v_mfma_f32_16x16x32_bf16 v[126:129], v[178:181], v[162:165], v[126:129]
	v_add_u32_e32 v217, 0x80, v217
	v_add_u32_e32 v220, 0x800, v220
	v_add_u32_e32 v221, 0x800, v221
	ds_read_b128 v[162:165], v216 offset:47104
	s_waitcnt vmcnt(8) lgkmcnt(7)
	v_mfma_f32_16x16x32_bf16 v[2:5], v[196:199], v[134:137], v[2:5]
	v_mfma_f32_16x16x32_bf16 v[6:9], v[204:207], v[134:137], v[6:9]
	ds_read_b128 v[134:137], v216 offset:49152
	s_waitcnt lgkmcnt(7)
	v_mfma_f32_16x16x32_bf16 v[10:13], v[196:199], v[138:141], v[10:13]
	v_mfma_f32_16x16x32_bf16 v[14:17], v[204:207], v[138:141], v[14:17]
	ds_read_b128 v[138:141], v216 offset:51200
	s_waitcnt lgkmcnt(7)
	v_mfma_f32_16x16x32_bf16 v[18:21], v[196:199], v[142:145], v[18:21]
	v_mfma_f32_16x16x32_bf16 v[22:25], v[204:207], v[142:145], v[22:25]
	ds_read_b128 v[142:145], v216 offset:53248
	s_waitcnt lgkmcnt(7)
	v_mfma_f32_16x16x32_bf16 v[26:29], v[196:199], v[146:149], v[26:29]
	v_mfma_f32_16x16x32_bf16 v[30:33], v[204:207], v[146:149], v[30:33]
	ds_read_b128 v[146:149], v216 offset:55296
	s_waitcnt lgkmcnt(7)
	v_mfma_f32_16x16x32_bf16 v[34:37], v[196:199], v[150:153], v[34:37]
	global_load_dwordx4 v[166:169], v220, s[8:9]
	v_mfma_f32_16x16x32_bf16 v[38:41], v[204:207], v[150:153], v[38:41]
	ds_read_b128 v[150:153], v216 offset:57344
	s_waitcnt lgkmcnt(7)
	v_mfma_f32_16x16x32_bf16 v[42:45], v[196:199], v[154:157], v[42:45]
	global_load_dwordx4 v[170:173], v220, s[8:9] offset:1024
	v_mfma_f32_16x16x32_bf16 v[46:49], v[204:207], v[154:157], v[46:49]
	ds_read_b128 v[154:157], v216 offset:59392
	s_waitcnt lgkmcnt(7)
	v_mfma_f32_16x16x32_bf16 v[50:53], v[196:199], v[158:161], v[50:53]
	global_load_dwordx4 v[174:177], v221, s[8:9]
	v_mfma_f32_16x16x32_bf16 v[54:57], v[204:207], v[158:161], v[54:57]
	ds_read_b128 v[158:161], v216 offset:61440
	s_waitcnt lgkmcnt(7)
	v_mfma_f32_16x16x32_bf16 v[58:61], v[196:199], v[162:165], v[58:61]
	global_load_dwordx4 v[178:181], v221, s[8:9] offset:1024
	v_mfma_f32_16x16x32_bf16 v[62:65], v[204:207], v[162:165], v[62:65]
	ds_read_b128 v[162:165], v216 offset:63488
	s_waitcnt lgkmcnt(7)
	v_mfma_f32_16x16x32_bf16 v[66:69], v[196:199], v[134:137], v[66:69]
	v_mfma_f32_16x16x32_bf16 v[70:73], v[204:207], v[134:137], v[70:73]
	ds_read_b128 v[134:137], v216 offset:33792
	s_waitcnt lgkmcnt(7)
	v_mfma_f32_16x16x32_bf16 v[74:77], v[196:199], v[138:141], v[74:77]
	v_mfma_f32_16x16x32_bf16 v[78:81], v[204:207], v[138:141], v[78:81]
	ds_read_b128 v[138:141], v216 offset:35840
	s_waitcnt lgkmcnt(7)
	v_mfma_f32_16x16x32_bf16 v[82:85], v[196:199], v[142:145], v[82:85]
	v_mfma_f32_16x16x32_bf16 v[86:89], v[204:207], v[142:145], v[86:89]
	ds_read_b128 v[142:145], v216 offset:37888
	s_waitcnt lgkmcnt(7)
	v_mfma_f32_16x16x32_bf16 v[90:93], v[196:199], v[146:149], v[90:93]
	v_mfma_f32_16x16x32_bf16 v[94:97], v[204:207], v[146:149], v[94:97]
	ds_read_b128 v[146:149], v216 offset:39936
	s_waitcnt lgkmcnt(7)
	v_mfma_f32_16x16x32_bf16 v[98:101], v[196:199], v[150:153], v[98:101]
	v_mfma_f32_16x16x32_bf16 v[102:105], v[204:207], v[150:153], v[102:105]
	ds_read_b128 v[150:153], v216 offset:41984
	s_waitcnt lgkmcnt(7)
	v_mfma_f32_16x16x32_bf16 v[106:109], v[196:199], v[154:157], v[106:109]
	v_mfma_f32_16x16x32_bf16 v[110:113], v[204:207], v[154:157], v[110:113]
	ds_read_b128 v[154:157], v216 offset:44032
	s_waitcnt lgkmcnt(7)
	v_mfma_f32_16x16x32_bf16 v[114:117], v[196:199], v[158:161], v[114:117]
	v_mfma_f32_16x16x32_bf16 v[118:121], v[204:207], v[158:161], v[118:121]
	ds_read_b128 v[158:161], v216 offset:46080
	s_waitcnt lgkmcnt(7)
	v_mfma_f32_16x16x32_bf16 v[122:125], v[196:199], v[162:165], v[122:125]
	v_mfma_f32_16x16x32_bf16 v[126:129], v[204:207], v[162:165], v[126:129]
	ds_read_b128 v[162:165], v216 offset:48128
	s_waitcnt lgkmcnt(7)
	v_mfma_f32_16x16x32_bf16 v[2:5], v[200:203], v[134:137], v[2:5]
	v_mfma_f32_16x16x32_bf16 v[6:9], v[212:215], v[134:137], v[6:9]
	ds_read_b128 v[134:137], v216 offset:50176
	s_waitcnt lgkmcnt(7)
	v_mfma_f32_16x16x32_bf16 v[10:13], v[200:203], v[138:141], v[10:13]
	v_mfma_f32_16x16x32_bf16 v[14:17], v[212:215], v[138:141], v[14:17]
	ds_read_b128 v[138:141], v216 offset:52224
	s_waitcnt lgkmcnt(7)
	v_mfma_f32_16x16x32_bf16 v[18:21], v[200:203], v[142:145], v[18:21]
	v_mfma_f32_16x16x32_bf16 v[22:25], v[212:215], v[142:145], v[22:25]
	ds_read_b128 v[142:145], v216 offset:54272
	s_waitcnt lgkmcnt(7)
	v_mfma_f32_16x16x32_bf16 v[26:29], v[200:203], v[146:149], v[26:29]
	v_mfma_f32_16x16x32_bf16 v[30:33], v[212:215], v[146:149], v[30:33]
	ds_read_b128 v[146:149], v216 offset:56320
	s_waitcnt lgkmcnt(7)
	v_mfma_f32_16x16x32_bf16 v[34:37], v[200:203], v[150:153], v[34:37]
	v_mfma_f32_16x16x32_bf16 v[38:41], v[212:215], v[150:153], v[38:41]
	ds_read_b128 v[150:153], v216 offset:58368
	s_waitcnt lgkmcnt(7)
	v_mfma_f32_16x16x32_bf16 v[42:45], v[200:203], v[154:157], v[42:45]
	v_mfma_f32_16x16x32_bf16 v[46:49], v[212:215], v[154:157], v[46:49]
	ds_read_b128 v[154:157], v216 offset:60416
	s_waitcnt lgkmcnt(7)
	v_mfma_f32_16x16x32_bf16 v[50:53], v[200:203], v[158:161], v[50:53]
	v_mfma_f32_16x16x32_bf16 v[54:57], v[212:215], v[158:161], v[54:57]
	ds_read_b128 v[158:161], v216 offset:62464
	s_waitcnt lgkmcnt(7)
	v_mfma_f32_16x16x32_bf16 v[58:61], v[200:203], v[162:165], v[58:61]
	v_mfma_f32_16x16x32_bf16 v[62:65], v[212:215], v[162:165], v[62:65]
	ds_read_b128 v[162:165], v216 offset:64512
	s_waitcnt vmcnt(4) lgkmcnt(0)
	s_barrier
	v_mfma_f32_16x16x32_bf16 v[66:69], v[200:203], v[134:137], v[66:69]
	s_add_u32 m0, s22, 0x8000
	v_mov_b32_e32 v223, v217
	global_load_lds_dwordx4 v223, s[6:7]
	v_mfma_f32_16x16x32_bf16 v[70:73], v[212:215], v[134:137], v[70:73]
	s_add_u32 m0, s22, 0x8400
	v_add_u32_e32 v224, 0x40, v217
	global_load_lds_dwordx4 v224, s[6:7]
	ds_read_b128 v[134:137], v216
	s_waitcnt lgkmcnt(7)
	v_mfma_f32_16x16x32_bf16 v[74:77], v[200:203], v[138:141], v[74:77]
	s_add_u32 m0, s22, 0x8800
	v_add_u32_e32 v223, 0x8000, v217
	global_load_lds_dwordx4 v223, s[6:7]
	v_mfma_f32_16x16x32_bf16 v[78:81], v[212:215], v[138:141], v[78:81]
	s_add_u32 m0, s22, 0x8c00
	v_add_u32_e32 v224, 0x8040, v217
	global_load_lds_dwordx4 v224, s[6:7]
	ds_read_b128 v[138:141], v216 offset:2048
	s_waitcnt lgkmcnt(7)
	v_mfma_f32_16x16x32_bf16 v[82:85], v[200:203], v[142:145], v[82:85]
	s_add_u32 m0, s22, 0x9000
	v_add_u32_e32 v223, 0x10000, v217
	global_load_lds_dwordx4 v223, s[6:7]
	v_mfma_f32_16x16x32_bf16 v[86:89], v[212:215], v[142:145], v[86:89]
	s_add_u32 m0, s22, 0x9400
	v_add_u32_e32 v224, 0x10040, v217
	global_load_lds_dwordx4 v224, s[6:7]
	ds_read_b128 v[142:145], v216 offset:4096
	s_waitcnt lgkmcnt(7)
	v_mfma_f32_16x16x32_bf16 v[90:93], v[200:203], v[146:149], v[90:93]
	s_add_u32 m0, s22, 0x9800
	v_add_u32_e32 v223, 0x18000, v217
	global_load_lds_dwordx4 v223, s[6:7]
	v_mfma_f32_16x16x32_bf16 v[94:97], v[212:215], v[146:149], v[94:97]
	s_add_u32 m0, s22, 0x9c00
	v_add_u32_e32 v224, 0x18040, v217
	global_load_lds_dwordx4 v224, s[6:7]
	ds_read_b128 v[146:149], v216 offset:6144
	s_waitcnt lgkmcnt(7)
	v_mfma_f32_16x16x32_bf16 v[98:101], v[200:203], v[150:153], v[98:101]
	v_mfma_f32_16x16x32_bf16 v[102:105], v[212:215], v[150:153], v[102:105]
	ds_read_b128 v[150:153], v216 offset:8192
	s_waitcnt lgkmcnt(7)
	v_mfma_f32_16x16x32_bf16 v[106:109], v[200:203], v[154:157], v[106:109]
	v_mfma_f32_16x16x32_bf16 v[110:113], v[212:215], v[154:157], v[110:113]
	ds_read_b128 v[154:157], v216 offset:10240
	s_waitcnt lgkmcnt(7)
	v_mfma_f32_16x16x32_bf16 v[114:117], v[200:203], v[158:161], v[114:117]
	v_mfma_f32_16x16x32_bf16 v[118:121], v[212:215], v[158:161], v[118:121]
	ds_read_b128 v[158:161], v216 offset:12288
	s_waitcnt lgkmcnt(7)
	v_mfma_f32_16x16x32_bf16 v[122:125], v[200:203], v[162:165], v[122:125]
	v_mfma_f32_16x16x32_bf16 v[126:129], v[212:215], v[162:165], v[126:129]
	v_add_u32_e32 v217, 0x80, v217
	v_add_u32_e32 v220, 0x800, v220
	v_add_u32_e32 v221, 0x800, v221
	s_mov_b32 s16, 6

.Lg256b_wo_next_retry:
	s_cmp_ge_u32 s12, 64
	s_cbranch_scc1 .Lg256b_wo_nonext
	s_lshr_b32 s3, s12, 6
	s_lshl_b32 s3, s3, 3
	s_add_u32 s3, s3, s65
	s_mov_b32 s17, s3
	s_mov_b32 s3, 0
	s_lshl_b32 s17, s17, 3
	s_bfe_u32 s23, s12, 0x30003
	s_add_u32 s13, s17, s23
	s_lshl_b32 s3, s3, 3
	s_and_b32 s23, s12, 7
	s_add_u32 s14, s3, s23
	s_lshl_b32 s13, s13, 8
	s_lshl_b32 s14, s14, 7
	s_lshl_b32 s3, s15, 6
	s_add_u32 s17, s3, s13
	s_mul_i32 s17, s17, 0x800
	s_add_u32 s6, s18, s17
	s_addc_u32 s7, s19, 0
	v_mov_b32_e32 v217, v218
	ds_read_b128 v[162:165], v216 offset:14336
	s_waitcnt vmcnt(8) lgkmcnt(7)
	v_mfma_f32_16x16x32_bf16 v[2:5], v[166:169], v[134:137], v[2:5]
	v_mfma_f32_16x16x32_bf16 v[6:9], v[174:177], v[134:137], v[6:9]
	ds_read_b128 v[134:137], v216 offset:16384
	s_waitcnt lgkmcnt(7)
	v_mfma_f32_16x16x32_bf16 v[10:13], v[166:169], v[138:141], v[10:13]
	v_mfma_f32_16x16x32_bf16 v[14:17], v[174:177], v[138:141], v[14:17]
	ds_read_b128 v[138:141], v216 offset:18432
	s_waitcnt lgkmcnt(7)
	v_mfma_f32_16x16x32_bf16 v[18:21], v[166:169], v[142:145], v[18:21]
	v_mfma_f32_16x16x32_bf16 v[22:25], v[174:177], v[142:145], v[22:25]
	ds_read_b128 v[142:145], v216 offset:20480
	s_waitcnt lgkmcnt(7)
	v_mfma_f32_16x16x32_bf16 v[26:29], v[166:169], v[146:149], v[26:29]
	v_mfma_f32_16x16x32_bf16 v[30:33], v[174:177], v[146:149], v[30:33]
	ds_read_b128 v[146:149], v216 offset:22528
	s_waitcnt lgkmcnt(7)
	v_mfma_f32_16x16x32_bf16 v[34:37], v[166:169], v[150:153], v[34:37]
	global_load_dwordx4 v[196:199], v220, s[8:9]
	v_mfma_f32_16x16x32_bf16 v[38:41], v[174:177], v[150:153], v[38:41]
	ds_read_b128 v[150:153], v216 offset:24576
	s_waitcnt lgkmcnt(7)
	v_mfma_f32_16x16x32_bf16 v[42:45], v[166:169], v[154:157], v[42:45]
	global_load_dwordx4 v[200:203], v220, s[8:9] offset:1024
	v_mfma_f32_16x16x32_bf16 v[46:49], v[174:177], v[154:157], v[46:49]
	ds_read_b128 v[154:157], v216 offset:26624
	s_waitcnt lgkmcnt(7)
	v_mfma_f32_16x16x32_bf16 v[50:53], v[166:169], v[158:161], v[50:53]
	global_load_dwordx4 v[204:207], v221, s[8:9]
	v_mfma_f32_16x16x32_bf16 v[54:57], v[174:177], v[158:161], v[54:57]
	ds_read_b128 v[158:161], v216 offset:28672
	s_waitcnt lgkmcnt(7)
	v_mfma_f32_16x16x32_bf16 v[58:61], v[166:169], v[162:165], v[58:61]
	global_load_dwordx4 v[212:215], v221, s[8:9] offset:1024
	v_mfma_f32_16x16x32_bf16 v[62:65], v[174:177], v[162:165], v[62:65]
	ds_read_b128 v[162:165], v216 offset:30720
	s_waitcnt lgkmcnt(7)
	v_mfma_f32_16x16x32_bf16 v[66:69], v[166:169], v[134:137], v[66:69]
	v_mfma_f32_16x16x32_bf16 v[70:73], v[174:177], v[134:137], v[70:73]
	ds_read_b128 v[134:137], v216 offset:1024
	s_waitcnt lgkmcnt(7)
	v_mfma_f32_16x16x32_bf16 v[74:77], v[166:169], v[138:141], v[74:77]
	v_mfma_f32_16x16x32_bf16 v[78:81], v[174:177], v[138:141], v[78:81]
	ds_read_b128 v[138:141], v216 offset:3072
	s_waitcnt lgkmcnt(7)
	v_mfma_f32_16x16x32_bf16 v[82:85], v[166:169], v[142:145], v[82:85]
	v_mfma_f32_16x16x32_bf16 v[86:89], v[174:177], v[142:145], v[86:89]
	ds_read_b128 v[142:145], v216 offset:5120
	s_waitcnt lgkmcnt(7)
	v_mfma_f32_16x16x32_bf16 v[90:93], v[166:169], v[146:149], v[90:93]
	v_mfma_f32_16x16x32_bf16 v[94:97], v[174:177], v[146:149], v[94:97]
	ds_read_b128 v[146:149], v216 offset:7168
	s_waitcnt lgkmcnt(7)
	v_mfma_f32_16x16x32_bf16 v[98:101], v[166:169], v[150:153], v[98:101]
	v_mfma_f32_16x16x32_bf16 v[102:105], v[174:177], v[150:153], v[102:105]
	ds_read_b128 v[150:153], v216 offset:9216
	s_waitcnt lgkmcnt(7)
	v_mfma_f32_16x16x32_bf16 v[106:109], v[166:169], v[154:157], v[106:109]
	v_mfma_f32_16x16x32_bf16 v[110:113], v[174:177], v[154:157], v[110:113]
	ds_read_b128 v[154:157], v216 offset:11264
	s_waitcnt lgkmcnt(7)
	v_mfma_f32_16x16x32_bf16 v[114:117], v[166:169], v[158:161], v[114:117]
	v_mfma_f32_16x16x32_bf16 v[118:121], v[174:177], v[158:161], v[118:121]
	ds_read_b128 v[158:161], v216 offset:13312
	s_waitcnt lgkmcnt(7)
	v_mfma_f32_16x16x32_bf16 v[122:125], v[166:169], v[162:165], v[122:125]
	v_mfma_f32_16x16x32_bf16 v[126:129], v[174:177], v[162:165], v[126:129]
	ds_read_b128 v[162:165], v216 offset:15360
	s_waitcnt lgkmcnt(7)
	v_mfma_f32_16x16x32_bf16 v[2:5], v[170:173], v[134:137], v[2:5]
	v_mfma_f32_16x16x32_bf16 v[6:9], v[178:181], v[134:137], v[6:9]
	ds_read_b128 v[134:137], v216 offset:17408
	s_waitcnt lgkmcnt(7)
	v_mfma_f32_16x16x32_bf16 v[10:13], v[170:173], v[138:141], v[10:13]
	v_mfma_f32_16x16x32_bf16 v[14:17], v[178:181], v[138:141], v[14:17]
	ds_read_b128 v[138:141], v216 offset:19456
	s_waitcnt lgkmcnt(7)
	v_mfma_f32_16x16x32_bf16 v[18:21], v[170:173], v[142:145], v[18:21]
	v_mfma_f32_16x16x32_bf16 v[22:25], v[178:181], v[142:145], v[22:25]
	ds_read_b128 v[142:145], v216 offset:21504
	s_waitcnt lgkmcnt(7)
	v_mfma_f32_16x16x32_bf16 v[26:29], v[170:173], v[146:149], v[26:29]
	v_mfma_f32_16x16x32_bf16 v[30:33], v[178:181], v[146:149], v[30:33]
	ds_read_b128 v[146:149], v216 offset:23552
	s_waitcnt lgkmcnt(7)
	v_mfma_f32_16x16x32_bf16 v[34:37], v[170:173], v[150:153], v[34:37]
	v_mfma_f32_16x16x32_bf16 v[38:41], v[178:181], v[150:153], v[38:41]
	ds_read_b128 v[150:153], v216 offset:25600
	s_waitcnt lgkmcnt(7)
	v_mfma_f32_16x16x32_bf16 v[42:45], v[170:173], v[154:157], v[42:45]
	v_mfma_f32_16x16x32_bf16 v[46:49], v[178:181], v[154:157], v[46:49]
	ds_read_b128 v[154:157], v216 offset:27648
	s_waitcnt lgkmcnt(7)
	v_mfma_f32_16x16x32_bf16 v[50:53], v[170:173], v[158:161], v[50:53]
	v_mfma_f32_16x16x32_bf16 v[54:57], v[178:181], v[158:161], v[54:57]
	ds_read_b128 v[158:161], v216 offset:29696
	s_waitcnt lgkmcnt(7)
	v_mfma_f32_16x16x32_bf16 v[58:61], v[170:173], v[162:165], v[58:61]
	v_mfma_f32_16x16x32_bf16 v[62:65], v[178:181], v[162:165], v[62:65]
	ds_read_b128 v[162:165], v216 offset:31744
	s_waitcnt vmcnt(4) lgkmcnt(0)
	s_barrier
	v_mfma_f32_16x16x32_bf16 v[66:69], v[170:173], v[134:137], v[66:69]
	s_add_u32 m0, s22, 0x0
	v_mov_b32_e32 v223, v217
	global_load_lds_dwordx4 v223, s[6:7]
	v_mfma_f32_16x16x32_bf16 v[70:73], v[178:181], v[134:137], v[70:73]
	s_add_u32 m0, s22, 0x400
	v_add_u32_e32 v224, 0x40, v217
	global_load_lds_dwordx4 v224, s[6:7]
	ds_read_b128 v[134:137], v216 offset:32768
	s_waitcnt lgkmcnt(7)
	v_mfma_f32_16x16x32_bf16 v[74:77], v[170:173], v[138:141], v[74:77]
	s_add_u32 m0, s22, 0x800
	v_add_u32_e32 v223, 0x8000, v217
	global_load_lds_dwordx4 v223, s[6:7]
	v_mfma_f32_16x16x32_bf16 v[78:81], v[178:181], v[138:141], v[78:81]
	s_add_u32 m0, s22, 0xc00
	v_add_u32_e32 v224, 0x8040, v217
	global_load_lds_dwordx4 v224, s[6:7]
	ds_read_b128 v[138:141], v216 offset:34816
	s_waitcnt lgkmcnt(7)
	v_mfma_f32_16x16x32_bf16 v[82:85], v[170:173], v[142:145], v[82:85]
	s_add_u32 m0, s22, 0x1000
	v_add_u32_e32 v223, 0x10000, v217
	global_load_lds_dwordx4 v223, s[6:7]
	v_mfma_f32_16x16x32_bf16 v[86:89], v[178:181], v[142:145], v[86:89]
	s_add_u32 m0, s22, 0x1400
	v_add_u32_e32 v224, 0x10040, v217
	global_load_lds_dwordx4 v224, s[6:7]
	ds_read_b128 v[142:145], v216 offset:36864
	s_waitcnt lgkmcnt(7)
	v_mfma_f32_16x16x32_bf16 v[90:93], v[170:173], v[146:149], v[90:93]
	s_add_u32 m0, s22, 0x1800
	v_add_u32_e32 v223, 0x18000, v217
	global_load_lds_dwordx4 v223, s[6:7]
	v_mfma_f32_16x16x32_bf16 v[94:97], v[178:181], v[146:149], v[94:97]
	s_add_u32 m0, s22, 0x1c00
	v_add_u32_e32 v224, 0x18040, v217
	global_load_lds_dwordx4 v224, s[6:7]
	ds_read_b128 v[146:149], v216 offset:38912
	s_waitcnt lgkmcnt(7)
	v_mfma_f32_16x16x32_bf16 v[98:101], v[170:173], v[150:153], v[98:101]
	v_mfma_f32_16x16x32_bf16 v[102:105], v[178:181], v[150:153], v[102:105]
	ds_read_b128 v[150:153], v216 offset:40960
	s_waitcnt lgkmcnt(7)
	v_mfma_f32_16x16x32_bf16 v[106:109], v[170:173], v[154:157], v[106:109]
	v_mfma_f32_16x16x32_bf16 v[110:113], v[178:181], v[154:157], v[110:113]
	ds_read_b128 v[154:157], v216 offset:43008
	s_waitcnt lgkmcnt(7)
	v_mfma_f32_16x16x32_bf16 v[114:117], v[170:173], v[158:161], v[114:117]
	v_mfma_f32_16x16x32_bf16 v[118:121], v[178:181], v[158:161], v[118:121]
	ds_read_b128 v[158:161], v216 offset:45056
	s_waitcnt lgkmcnt(7)
	v_mfma_f32_16x16x32_bf16 v[122:125], v[170:173], v[162:165], v[122:125]
	v_mfma_f32_16x16x32_bf16 v[126:129], v[178:181], v[162:165], v[126:129]
	v_add_u32_e32 v217, 0x80, v217
	v_add_u32_e32 v220, 0x800, v220
	v_add_u32_e32 v221, 0x800, v221
	s_lshr_b32 s3, s14, 4
	s_lshl_b32 s17, s15, 1
	s_add_u32 s3, s3, s17
	s_mul_i32 s17, s3, 0x8000
	s_add_u32 s8, s20, s17
	s_addc_u32 s9, s21, 0
	v_mov_b32_e32 v220, v222
	v_add_u32_e32 v221, 0x8000, v222
	ds_read_b128 v[162:165], v216 offset:47104
	s_waitcnt vmcnt(8) lgkmcnt(7)
	v_mfma_f32_16x16x32_bf16 v[2:5], v[196:199], v[134:137], v[2:5]
	v_mfma_f32_16x16x32_bf16 v[6:9], v[204:207], v[134:137], v[6:9]
	ds_read_b128 v[134:137], v216 offset:49152
	s_waitcnt lgkmcnt(7)
	v_mfma_f32_16x16x32_bf16 v[10:13], v[196:199], v[138:141], v[10:13]
	v_mfma_f32_16x16x32_bf16 v[14:17], v[204:207], v[138:141], v[14:17]
	ds_read_b128 v[138:141], v216 offset:51200
	s_waitcnt lgkmcnt(7)
	v_mfma_f32_16x16x32_bf16 v[18:21], v[196:199], v[142:145], v[18:21]
	v_mfma_f32_16x16x32_bf16 v[22:25], v[204:207], v[142:145], v[22:25]
	ds_read_b128 v[142:145], v216 offset:53248
	s_waitcnt lgkmcnt(7)
	v_mfma_f32_16x16x32_bf16 v[26:29], v[196:199], v[146:149], v[26:29]
	v_mfma_f32_16x16x32_bf16 v[30:33], v[204:207], v[146:149], v[30:33]
	ds_read_b128 v[146:149], v216 offset:55296
	s_waitcnt lgkmcnt(7)
	v_mfma_f32_16x16x32_bf16 v[34:37], v[196:199], v[150:153], v[34:37]
	global_load_dwordx4 v[166:169], v220, s[8:9]
	v_mfma_f32_16x16x32_bf16 v[38:41], v[204:207], v[150:153], v[38:41]
	ds_read_b128 v[150:153], v216 offset:57344
	s_waitcnt lgkmcnt(7)
	v_mfma_f32_16x16x32_bf16 v[42:45], v[196:199], v[154:157], v[42:45]
	global_load_dwordx4 v[170:173], v220, s[8:9] offset:1024
	v_mfma_f32_16x16x32_bf16 v[46:49], v[204:207], v[154:157], v[46:49]
	ds_read_b128 v[154:157], v216 offset:59392
	s_waitcnt lgkmcnt(7)
	v_mfma_f32_16x16x32_bf16 v[50:53], v[196:199], v[158:161], v[50:53]
	global_load_dwordx4 v[174:177], v221, s[8:9]
	v_mfma_f32_16x16x32_bf16 v[54:57], v[204:207], v[158:161], v[54:57]
	ds_read_b128 v[158:161], v216 offset:61440
	s_waitcnt lgkmcnt(7)
	v_mfma_f32_16x16x32_bf16 v[58:61], v[196:199], v[162:165], v[58:61]
	global_load_dwordx4 v[178:181], v221, s[8:9] offset:1024
	v_mfma_f32_16x16x32_bf16 v[62:65], v[204:207], v[162:165], v[62:65]
	ds_read_b128 v[162:165], v216 offset:63488
	s_waitcnt lgkmcnt(7)
	v_mfma_f32_16x16x32_bf16 v[66:69], v[196:199], v[134:137], v[66:69]
	v_mfma_f32_16x16x32_bf16 v[70:73], v[204:207], v[134:137], v[70:73]
	ds_read_b128 v[134:137], v216 offset:33792
	s_waitcnt lgkmcnt(7)
	v_mfma_f32_16x16x32_bf16 v[74:77], v[196:199], v[138:141], v[74:77]
	v_mfma_f32_16x16x32_bf16 v[78:81], v[204:207], v[138:141], v[78:81]
	ds_read_b128 v[138:141], v216 offset:35840
	s_waitcnt lgkmcnt(7)
	v_mfma_f32_16x16x32_bf16 v[82:85], v[196:199], v[142:145], v[82:85]
	v_mfma_f32_16x16x32_bf16 v[86:89], v[204:207], v[142:145], v[86:89]
	ds_read_b128 v[142:145], v216 offset:37888
	s_waitcnt lgkmcnt(7)
	v_mfma_f32_16x16x32_bf16 v[90:93], v[196:199], v[146:149], v[90:93]
	v_mfma_f32_16x16x32_bf16 v[94:97], v[204:207], v[146:149], v[94:97]
	ds_read_b128 v[146:149], v216 offset:39936
	s_waitcnt lgkmcnt(7)
	v_mfma_f32_16x16x32_bf16 v[98:101], v[196:199], v[150:153], v[98:101]
	v_mfma_f32_16x16x32_bf16 v[102:105], v[204:207], v[150:153], v[102:105]
	ds_read_b128 v[150:153], v216 offset:41984
	s_waitcnt lgkmcnt(7)
	v_mfma_f32_16x16x32_bf16 v[106:109], v[196:199], v[154:157], v[106:109]
	v_mfma_f32_16x16x32_bf16 v[110:113], v[204:207], v[154:157], v[110:113]
	ds_read_b128 v[154:157], v216 offset:44032
	s_waitcnt lgkmcnt(7)
	v_mfma_f32_16x16x32_bf16 v[114:117], v[196:199], v[158:161], v[114:117]
	v_mfma_f32_16x16x32_bf16 v[118:121], v[204:207], v[158:161], v[118:121]
	ds_read_b128 v[158:161], v216 offset:46080
	s_waitcnt lgkmcnt(7)
	v_mfma_f32_16x16x32_bf16 v[122:125], v[196:199], v[162:165], v[122:125]
	v_mfma_f32_16x16x32_bf16 v[126:129], v[204:207], v[162:165], v[126:129]
	ds_read_b128 v[162:165], v216 offset:48128
	s_waitcnt lgkmcnt(7)
	v_mfma_f32_16x16x32_bf16 v[2:5], v[200:203], v[134:137], v[2:5]
	v_mfma_f32_16x16x32_bf16 v[6:9], v[212:215], v[134:137], v[6:9]
	ds_read_b128 v[134:137], v216 offset:50176
	s_waitcnt lgkmcnt(7)
	v_mfma_f32_16x16x32_bf16 v[10:13], v[200:203], v[138:141], v[10:13]
	v_mfma_f32_16x16x32_bf16 v[14:17], v[212:215], v[138:141], v[14:17]
	ds_read_b128 v[138:141], v216 offset:52224
	s_waitcnt lgkmcnt(7)
	v_mfma_f32_16x16x32_bf16 v[18:21], v[200:203], v[142:145], v[18:21]
	v_mfma_f32_16x16x32_bf16 v[22:25], v[212:215], v[142:145], v[22:25]
	ds_read_b128 v[142:145], v216 offset:54272
	s_waitcnt lgkmcnt(7)
	v_mfma_f32_16x16x32_bf16 v[26:29], v[200:203], v[146:149], v[26:29]
	v_mfma_f32_16x16x32_bf16 v[30:33], v[212:215], v[146:149], v[30:33]
	ds_read_b128 v[146:149], v216 offset:56320
	s_waitcnt lgkmcnt(7)
	v_mfma_f32_16x16x32_bf16 v[34:37], v[200:203], v[150:153], v[34:37]
	v_mfma_f32_16x16x32_bf16 v[38:41], v[212:215], v[150:153], v[38:41]
	ds_read_b128 v[150:153], v216 offset:58368
	s_waitcnt lgkmcnt(7)
	v_mfma_f32_16x16x32_bf16 v[42:45], v[200:203], v[154:157], v[42:45]
	v_mfma_f32_16x16x32_bf16 v[46:49], v[212:215], v[154:157], v[46:49]
	ds_read_b128 v[154:157], v216 offset:60416
	s_waitcnt lgkmcnt(7)
	v_mfma_f32_16x16x32_bf16 v[50:53], v[200:203], v[158:161], v[50:53]
	v_mfma_f32_16x16x32_bf16 v[54:57], v[212:215], v[158:161], v[54:57]
	ds_read_b128 v[158:161], v216 offset:62464
	s_waitcnt lgkmcnt(7)
	v_mfma_f32_16x16x32_bf16 v[58:61], v[200:203], v[162:165], v[58:61]
	v_mfma_f32_16x16x32_bf16 v[62:65], v[212:215], v[162:165], v[62:65]
	ds_read_b128 v[162:165], v216 offset:64512
	s_waitcnt vmcnt(4) lgkmcnt(0)
	s_barrier
	v_mfma_f32_16x16x32_bf16 v[66:69], v[200:203], v[134:137], v[66:69]
	s_add_u32 m0, s22, 0x8000
	v_mov_b32_e32 v223, v217
	global_load_lds_dwordx4 v223, s[6:7]
	v_mfma_f32_16x16x32_bf16 v[70:73], v[212:215], v[134:137], v[70:73]
	s_add_u32 m0, s22, 0x8400
	v_add_u32_e32 v224, 0x40, v217
	global_load_lds_dwordx4 v224, s[6:7]
	ds_read_b128 v[134:137], v216
	s_waitcnt lgkmcnt(7)
	v_mfma_f32_16x16x32_bf16 v[74:77], v[200:203], v[138:141], v[74:77]
	s_add_u32 m0, s22, 0x8800
	v_add_u32_e32 v223, 0x8000, v217
	global_load_lds_dwordx4 v223, s[6:7]
	v_mfma_f32_16x16x32_bf16 v[78:81], v[212:215], v[138:141], v[78:81]
	s_add_u32 m0, s22, 0x8c00
	v_add_u32_e32 v224, 0x8040, v217
	global_load_lds_dwordx4 v224, s[6:7]
	ds_read_b128 v[138:141], v216 offset:2048
	s_waitcnt lgkmcnt(7)
	v_mfma_f32_16x16x32_bf16 v[82:85], v[200:203], v[142:145], v[82:85]
	s_add_u32 m0, s22, 0x9000
	v_add_u32_e32 v223, 0x10000, v217
	global_load_lds_dwordx4 v223, s[6:7]
	v_mfma_f32_16x16x32_bf16 v[86:89], v[212:215], v[142:145], v[86:89]
	s_add_u32 m0, s22, 0x9400
	v_add_u32_e32 v224, 0x10040, v217
	global_load_lds_dwordx4 v224, s[6:7]
	ds_read_b128 v[142:145], v216 offset:4096
	s_waitcnt lgkmcnt(7)
	v_mfma_f32_16x16x32_bf16 v[90:93], v[200:203], v[146:149], v[90:93]
	s_add_u32 m0, s22, 0x9800
	v_add_u32_e32 v223, 0x18000, v217
	global_load_lds_dwordx4 v223, s[6:7]
	v_mfma_f32_16x16x32_bf16 v[94:97], v[212:215], v[146:149], v[94:97]
	s_add_u32 m0, s22, 0x9c00
	v_add_u32_e32 v224, 0x18040, v217
	global_load_lds_dwordx4 v224, s[6:7]
	ds_read_b128 v[146:149], v216 offset:6144
	s_waitcnt lgkmcnt(7)
	v_mfma_f32_16x16x32_bf16 v[98:101], v[200:203], v[150:153], v[98:101]
	v_mfma_f32_16x16x32_bf16 v[102:105], v[212:215], v[150:153], v[102:105]
	ds_read_b128 v[150:153], v216 offset:8192
	s_waitcnt lgkmcnt(7)
	v_mfma_f32_16x16x32_bf16 v[106:109], v[200:203], v[154:157], v[106:109]
	v_mfma_f32_16x16x32_bf16 v[110:113], v[212:215], v[154:157], v[110:113]
	ds_read_b128 v[154:157], v216 offset:10240
	s_waitcnt lgkmcnt(7)
	v_mfma_f32_16x16x32_bf16 v[114:117], v[200:203], v[158:161], v[114:117]
	v_mfma_f32_16x16x32_bf16 v[118:121], v[212:215], v[158:161], v[118:121]
	ds_read_b128 v[158:161], v216 offset:12288
	s_waitcnt lgkmcnt(7)
	v_mfma_f32_16x16x32_bf16 v[122:125], v[200:203], v[162:165], v[122:125]
	v_mfma_f32_16x16x32_bf16 v[126:129], v[212:215], v[162:165], v[126:129]
	v_add_u32_e32 v217, 0x80, v217
	v_add_u32_e32 v220, 0x800, v220
	v_add_u32_e32 v221, 0x800, v221
	s_mov_b32 s16, 1
	s_branch .Lg256b_wo_epi

.Lg256b_ip_tile:
	s_mul_i32 s17, s13, 0x1440
	s_lshl_b32 s3, s15, 5
	s_add_u32 s3, s3, s14
	s_mul_i32 s3, s3, 2
	s_add_u32 s17, s17, s3
	s_add_u32 s10, s24, s17
	s_addc_u32 s11, s25, 0
	s_cmp_eq_u32 s14, 2560
	s_cselect_b32 s27, 1, 0
	s_cmp_lg_u32 s15, 0
	s_cselect_b32 s3, 1, 0
	s_and_b32 s27, s27, s3
	ds_read_b128 v[162:165], v216 offset:14336
	s_waitcnt vmcnt(0) lgkmcnt(7)
	v_mfma_f32_16x16x32_bf16 v[2:5], v[166:169], v[134:137], 0
	v_mfma_f32_16x16x32_bf16 v[6:9], v[174:177], v[134:137], 0
	ds_read_b128 v[134:137], v216 offset:16384
	s_waitcnt lgkmcnt(7)
	v_mfma_f32_16x16x32_bf16 v[10:13], v[166:169], v[138:141], 0
	v_mfma_f32_16x16x32_bf16 v[14:17], v[174:177], v[138:141], 0
	ds_read_b128 v[138:141], v216 offset:18432
	s_waitcnt lgkmcnt(7)
	v_mfma_f32_16x16x32_bf16 v[18:21], v[166:169], v[142:145], 0
	v_mfma_f32_16x16x32_bf16 v[22:25], v[174:177], v[142:145], 0
	ds_read_b128 v[142:145], v216 offset:20480
	s_waitcnt lgkmcnt(7)
	v_mfma_f32_16x16x32_bf16 v[26:29], v[166:169], v[146:149], 0
	v_mfma_f32_16x16x32_bf16 v[30:33], v[174:177], v[146:149], 0
	ds_read_b128 v[146:149], v216 offset:22528
	s_waitcnt lgkmcnt(7)
	v_mfma_f32_16x16x32_bf16 v[34:37], v[166:169], v[150:153], 0
	global_load_dwordx4 v[196:199], v220, s[8:9]
	v_mfma_f32_16x16x32_bf16 v[38:41], v[174:177], v[150:153], 0
	ds_read_b128 v[150:153], v216 offset:24576
	s_waitcnt lgkmcnt(7)
	v_mfma_f32_16x16x32_bf16 v[42:45], v[166:169], v[154:157], 0
	global_load_dwordx4 v[200:203], v220, s[8:9] offset:1024
	v_mfma_f32_16x16x32_bf16 v[46:49], v[174:177], v[154:157], 0
	ds_read_b128 v[154:157], v216 offset:26624
	s_waitcnt lgkmcnt(7)
	v_mfma_f32_16x16x32_bf16 v[50:53], v[166:169], v[158:161], 0
	global_load_dwordx4 v[204:207], v221, s[8:9]
	v_mfma_f32_16x16x32_bf16 v[54:57], v[174:177], v[158:161], 0
	ds_read_b128 v[158:161], v216 offset:28672
	s_waitcnt lgkmcnt(7)
	v_mfma_f32_16x16x32_bf16 v[58:61], v[166:169], v[162:165], 0
	global_load_dwordx4 v[212:215], v221, s[8:9] offset:1024
	v_mfma_f32_16x16x32_bf16 v[62:65], v[174:177], v[162:165], 0
	ds_read_b128 v[162:165], v216 offset:30720
	s_waitcnt lgkmcnt(7)
	v_mfma_f32_16x16x32_bf16 v[66:69], v[166:169], v[134:137], 0
	v_mfma_f32_16x16x32_bf16 v[70:73], v[174:177], v[134:137], 0
	ds_read_b128 v[134:137], v216 offset:1024
	s_waitcnt lgkmcnt(7)
	v_mfma_f32_16x16x32_bf16 v[74:77], v[166:169], v[138:141], 0
	v_mfma_f32_16x16x32_bf16 v[78:81], v[174:177], v[138:141], 0
	ds_read_b128 v[138:141], v216 offset:3072
	s_waitcnt lgkmcnt(7)
	v_mfma_f32_16x16x32_bf16 v[82:85], v[166:169], v[142:145], 0
	v_mfma_f32_16x16x32_bf16 v[86:89], v[174:177], v[142:145], 0
	ds_read_b128 v[142:145], v216 offset:5120
	s_waitcnt lgkmcnt(7)
	v_mfma_f32_16x16x32_bf16 v[90:93], v[166:169], v[146:149], 0
	v_mfma_f32_16x16x32_bf16 v[94:97], v[174:177], v[146:149], 0
	ds_read_b128 v[146:149], v216 offset:7168
	s_waitcnt lgkmcnt(7)
	v_mfma_f32_16x16x32_bf16 v[98:101], v[166:169], v[150:153], 0
	v_mfma_f32_16x16x32_bf16 v[102:105], v[174:177], v[150:153], 0
	ds_read_b128 v[150:153], v216 offset:9216
	s_waitcnt lgkmcnt(7)
	v_mfma_f32_16x16x32_bf16 v[106:109], v[166:169], v[154:157], 0
	v_mfma_f32_16x16x32_bf16 v[110:113], v[174:177], v[154:157], 0
	ds_read_b128 v[154:157], v216 offset:11264
	s_waitcnt lgkmcnt(7)
	v_mfma_f32_16x16x32_bf16 v[114:117], v[166:169], v[158:161], 0
	v_mfma_f32_16x16x32_bf16 v[118:121], v[174:177], v[158:161], 0
	ds_read_b128 v[158:161], v216 offset:13312
	s_waitcnt lgkmcnt(7)
	v_mfma_f32_16x16x32_bf16 v[122:125], v[166:169], v[162:165], 0
	v_mfma_f32_16x16x32_bf16 v[126:129], v[174:177], v[162:165], 0
	ds_read_b128 v[162:165], v216 offset:15360
	s_waitcnt lgkmcnt(7)
	v_mfma_f32_16x16x32_bf16 v[2:5], v[170:173], v[134:137], v[2:5]
	v_mfma_f32_16x16x32_bf16 v[6:9], v[178:181], v[134:137], v[6:9]
	ds_read_b128 v[134:137], v216 offset:17408
	s_waitcnt lgkmcnt(7)
	v_mfma_f32_16x16x32_bf16 v[10:13], v[170:173], v[138:141], v[10:13]
	v_mfma_f32_16x16x32_bf16 v[14:17], v[178:181], v[138:141], v[14:17]
	ds_read_b128 v[138:141], v216 offset:19456
	s_waitcnt lgkmcnt(7)
	v_mfma_f32_16x16x32_bf16 v[18:21], v[170:173], v[142:145], v[18:21]
	v_mfma_f32_16x16x32_bf16 v[22:25], v[178:181], v[142:145], v[22:25]
	ds_read_b128 v[142:145], v216 offset:21504
	s_waitcnt lgkmcnt(7)
	v_mfma_f32_16x16x32_bf16 v[26:29], v[170:173], v[146:149], v[26:29]
	v_mfma_f32_16x16x32_bf16 v[30:33], v[178:181], v[146:149], v[30:33]
	ds_read_b128 v[146:149], v216 offset:23552
	s_waitcnt lgkmcnt(7)
	v_mfma_f32_16x16x32_bf16 v[34:37], v[170:173], v[150:153], v[34:37]
	v_mfma_f32_16x16x32_bf16 v[38:41], v[178:181], v[150:153], v[38:41]
	ds_read_b128 v[150:153], v216 offset:25600
	s_waitcnt lgkmcnt(7)
	v_mfma_f32_16x16x32_bf16 v[42:45], v[170:173], v[154:157], v[42:45]
	v_mfma_f32_16x16x32_bf16 v[46:49], v[178:181], v[154:157], v[46:49]
	ds_read_b128 v[154:157], v216 offset:27648
	s_waitcnt lgkmcnt(7)
	v_mfma_f32_16x16x32_bf16 v[50:53], v[170:173], v[158:161], v[50:53]
	v_mfma_f32_16x16x32_bf16 v[54:57], v[178:181], v[158:161], v[54:57]
	ds_read_b128 v[158:161], v216 offset:29696
	s_waitcnt lgkmcnt(7)
	v_mfma_f32_16x16x32_bf16 v[58:61], v[170:173], v[162:165], v[58:61]
	v_mfma_f32_16x16x32_bf16 v[62:65], v[178:181], v[162:165], v[62:65]
	ds_read_b128 v[162:165], v216 offset:31744
	s_waitcnt vmcnt(0) lgkmcnt(0)
	s_barrier
	v_mfma_f32_16x16x32_bf16 v[66:69], v[170:173], v[134:137], v[66:69]
	s_add_u32 m0, s22, 0x0
	v_mov_b32_e32 v223, v217
	global_load_lds_dwordx4 v223, s[6:7]
	v_mfma_f32_16x16x32_bf16 v[70:73], v[178:181], v[134:137], v[70:73]
	s_add_u32 m0, s22, 0x400
	v_add_u32_e32 v224, 0x40, v217
	global_load_lds_dwordx4 v224, s[6:7]
	ds_read_b128 v[134:137], v216 offset:32768
	s_waitcnt lgkmcnt(7)
	v_mfma_f32_16x16x32_bf16 v[74:77], v[170:173], v[138:141], v[74:77]
	s_add_u32 m0, s22, 0x800
	v_add_u32_e32 v223, 0x8000, v217
	global_load_lds_dwordx4 v223, s[6:7]
	v_mfma_f32_16x16x32_bf16 v[78:81], v[178:181], v[138:141], v[78:81]
	s_add_u32 m0, s22, 0xc00
	v_add_u32_e32 v224, 0x8040, v217
	global_load_lds_dwordx4 v224, s[6:7]
	ds_read_b128 v[138:141], v216 offset:34816
	s_waitcnt lgkmcnt(7)
	v_mfma_f32_16x16x32_bf16 v[82:85], v[170:173], v[142:145], v[82:85]
	s_add_u32 m0, s22, 0x1000
	v_add_u32_e32 v223, 0x10000, v217
	global_load_lds_dwordx4 v223, s[6:7]
	v_mfma_f32_16x16x32_bf16 v[86:89], v[178:181], v[142:145], v[86:89]
	s_add_u32 m0, s22, 0x1400
	v_add_u32_e32 v224, 0x10040, v217
	global_load_lds_dwordx4 v224, s[6:7]
	ds_read_b128 v[142:145], v216 offset:36864
	s_waitcnt lgkmcnt(7)
	v_mfma_f32_16x16x32_bf16 v[90:93], v[170:173], v[146:149], v[90:93]
	s_add_u32 m0, s22, 0x1800
	v_add_u32_e32 v223, 0x18000, v217
	global_load_lds_dwordx4 v223, s[6:7]
	v_mfma_f32_16x16x32_bf16 v[94:97], v[178:181], v[146:149], v[94:97]
	s_add_u32 m0, s22, 0x1c00
	v_add_u32_e32 v224, 0x18040, v217
	global_load_lds_dwordx4 v224, s[6:7]
	ds_read_b128 v[146:149], v216 offset:38912
	s_waitcnt lgkmcnt(7)
	v_mfma_f32_16x16x32_bf16 v[98:101], v[170:173], v[150:153], v[98:101]
	v_mfma_f32_16x16x32_bf16 v[102:105], v[178:181], v[150:153], v[102:105]
	ds_read_b128 v[150:153], v216 offset:40960
	s_waitcnt lgkmcnt(7)
	v_mfma_f32_16x16x32_bf16 v[106:109], v[170:173], v[154:157], v[106:109]
	v_mfma_f32_16x16x32_bf16 v[110:113], v[178:181], v[154:157], v[110:113]
	ds_read_b128 v[154:157], v216 offset:43008
	s_waitcnt lgkmcnt(7)
	v_mfma_f32_16x16x32_bf16 v[114:117], v[170:173], v[158:161], v[114:117]
	v_mfma_f32_16x16x32_bf16 v[118:121], v[178:181], v[158:161], v[118:121]
	ds_read_b128 v[158:161], v216 offset:45056
	s_waitcnt lgkmcnt(7)
	v_mfma_f32_16x16x32_bf16 v[122:125], v[170:173], v[162:165], v[122:125]
	v_mfma_f32_16x16x32_bf16 v[126:129], v[178:181], v[162:165], v[126:129]
	v_add_u32_e32 v217, 0x80, v217
	v_add_u32_e32 v220, 0x800, v220
	v_add_u32_e32 v221, 0x800, v221
	ds_read_b128 v[162:165], v216 offset:47104
	s_waitcnt vmcnt(8) lgkmcnt(7)
	v_mfma_f32_16x16x32_bf16 v[2:5], v[196:199], v[134:137], v[2:5]
	v_mfma_f32_16x16x32_bf16 v[6:9], v[204:207], v[134:137], v[6:9]
	ds_read_b128 v[134:137], v216 offset:49152
	s_waitcnt lgkmcnt(7)
	v_mfma_f32_16x16x32_bf16 v[10:13], v[196:199], v[138:141], v[10:13]
	v_mfma_f32_16x16x32_bf16 v[14:17], v[204:207], v[138:141], v[14:17]
	ds_read_b128 v[138:141], v216 offset:51200
	s_waitcnt lgkmcnt(7)
	v_mfma_f32_16x16x32_bf16 v[18:21], v[196:199], v[142:145], v[18:21]
	v_mfma_f32_16x16x32_bf16 v[22:25], v[204:207], v[142:145], v[22:25]
	ds_read_b128 v[142:145], v216 offset:53248
	s_waitcnt lgkmcnt(7)
	v_mfma_f32_16x16x32_bf16 v[26:29], v[196:199], v[146:149], v[26:29]
	v_mfma_f32_16x16x32_bf16 v[30:33], v[204:207], v[146:149], v[30:33]
	ds_read_b128 v[146:149], v216 offset:55296
	s_waitcnt lgkmcnt(7)
	v_mfma_f32_16x16x32_bf16 v[34:37], v[196:199], v[150:153], v[34:37]
	global_load_dwordx4 v[166:169], v220, s[8:9]
	v_mfma_f32_16x16x32_bf16 v[38:41], v[204:207], v[150:153], v[38:41]
	ds_read_b128 v[150:153], v216 offset:57344
	s_waitcnt lgkmcnt(7)
	v_mfma_f32_16x16x32_bf16 v[42:45], v[196:199], v[154:157], v[42:45]
	global_load_dwordx4 v[170:173], v220, s[8:9] offset:1024
	v_mfma_f32_16x16x32_bf16 v[46:49], v[204:207], v[154:157], v[46:49]
	ds_read_b128 v[154:157], v216 offset:59392
	s_waitcnt lgkmcnt(7)
	v_mfma_f32_16x16x32_bf16 v[50:53], v[196:199], v[158:161], v[50:53]
	global_load_dwordx4 v[174:177], v221, s[8:9]
	v_mfma_f32_16x16x32_bf16 v[54:57], v[204:207], v[158:161], v[54:57]
	ds_read_b128 v[158:161], v216 offset:61440
	s_waitcnt lgkmcnt(7)
	v_mfma_f32_16x16x32_bf16 v[58:61], v[196:199], v[162:165], v[58:61]
	global_load_dwordx4 v[178:181], v221, s[8:9] offset:1024
	v_mfma_f32_16x16x32_bf16 v[62:65], v[204:207], v[162:165], v[62:65]
	ds_read_b128 v[162:165], v216 offset:63488
	s_waitcnt lgkmcnt(7)
	v_mfma_f32_16x16x32_bf16 v[66:69], v[196:199], v[134:137], v[66:69]
	v_mfma_f32_16x16x32_bf16 v[70:73], v[204:207], v[134:137], v[70:73]
	ds_read_b128 v[134:137], v216 offset:33792
	s_waitcnt lgkmcnt(7)
	v_mfma_f32_16x16x32_bf16 v[74:77], v[196:199], v[138:141], v[74:77]
	v_mfma_f32_16x16x32_bf16 v[78:81], v[204:207], v[138:141], v[78:81]
	ds_read_b128 v[138:141], v216 offset:35840
	s_waitcnt lgkmcnt(7)
	v_mfma_f32_16x16x32_bf16 v[82:85], v[196:199], v[142:145], v[82:85]
	v_mfma_f32_16x16x32_bf16 v[86:89], v[204:207], v[142:145], v[86:89]
	ds_read_b128 v[142:145], v216 offset:37888
	s_waitcnt lgkmcnt(7)
	v_mfma_f32_16x16x32_bf16 v[90:93], v[196:199], v[146:149], v[90:93]
	v_mfma_f32_16x16x32_bf16 v[94:97], v[204:207], v[146:149], v[94:97]
	ds_read_b128 v[146:149], v216 offset:39936
	s_waitcnt lgkmcnt(7)
	v_mfma_f32_16x16x32_bf16 v[98:101], v[196:199], v[150:153], v[98:101]
	v_mfma_f32_16x16x32_bf16 v[102:105], v[204:207], v[150:153], v[102:105]
	ds_read_b128 v[150:153], v216 offset:41984
	s_waitcnt lgkmcnt(7)
	v_mfma_f32_16x16x32_bf16 v[106:109], v[196:199], v[154:157], v[106:109]
	v_mfma_f32_16x16x32_bf16 v[110:113], v[204:207], v[154:157], v[110:113]
	ds_read_b128 v[154:157], v216 offset:44032
	s_waitcnt lgkmcnt(7)
	v_mfma_f32_16x16x32_bf16 v[114:117], v[196:199], v[158:161], v[114:117]
	v_mfma_f32_16x16x32_bf16 v[118:121], v[204:207], v[158:161], v[118:121]
	ds_read_b128 v[158:161], v216 offset:46080
	s_waitcnt lgkmcnt(7)
	v_mfma_f32_16x16x32_bf16 v[122:125], v[196:199], v[162:165], v[122:125]
	v_mfma_f32_16x16x32_bf16 v[126:129], v[204:207], v[162:165], v[126:129]
	ds_read_b128 v[162:165], v216 offset:48128
	s_waitcnt lgkmcnt(7)
	v_mfma_f32_16x16x32_bf16 v[2:5], v[200:203], v[134:137], v[2:5]
	v_mfma_f32_16x16x32_bf16 v[6:9], v[212:215], v[134:137], v[6:9]
	ds_read_b128 v[134:137], v216 offset:50176
	s_waitcnt lgkmcnt(7)
	v_mfma_f32_16x16x32_bf16 v[10:13], v[200:203], v[138:141], v[10:13]
	v_mfma_f32_16x16x32_bf16 v[14:17], v[212:215], v[138:141], v[14:17]
	ds_read_b128 v[138:141], v216 offset:52224
	s_waitcnt lgkmcnt(7)
	v_mfma_f32_16x16x32_bf16 v[18:21], v[200:203], v[142:145], v[18:21]
	v_mfma_f32_16x16x32_bf16 v[22:25], v[212:215], v[142:145], v[22:25]
	ds_read_b128 v[142:145], v216 offset:54272
	s_waitcnt lgkmcnt(7)
	v_mfma_f32_16x16x32_bf16 v[26:29], v[200:203], v[146:149], v[26:29]
	v_mfma_f32_16x16x32_bf16 v[30:33], v[212:215], v[146:149], v[30:33]
	ds_read_b128 v[146:149], v216 offset:56320
	s_waitcnt lgkmcnt(7)
	v_mfma_f32_16x16x32_bf16 v[34:37], v[200:203], v[150:153], v[34:37]
	v_mfma_f32_16x16x32_bf16 v[38:41], v[212:215], v[150:153], v[38:41]
	ds_read_b128 v[150:153], v216 offset:58368
	s_waitcnt lgkmcnt(7)
	v_mfma_f32_16x16x32_bf16 v[42:45], v[200:203], v[154:157], v[42:45]
	v_mfma_f32_16x16x32_bf16 v[46:49], v[212:215], v[154:157], v[46:49]
	ds_read_b128 v[154:157], v216 offset:60416
	s_waitcnt lgkmcnt(7)
	v_mfma_f32_16x16x32_bf16 v[50:53], v[200:203], v[158:161], v[50:53]
	v_mfma_f32_16x16x32_bf16 v[54:57], v[212:215], v[158:161], v[54:57]
	ds_read_b128 v[158:161], v216 offset:62464
	s_waitcnt lgkmcnt(7)
	v_mfma_f32_16x16x32_bf16 v[58:61], v[200:203], v[162:165], v[58:61]
	v_mfma_f32_16x16x32_bf16 v[62:65], v[212:215], v[162:165], v[62:65]
	ds_read_b128 v[162:165], v216 offset:64512
	s_waitcnt vmcnt(4) lgkmcnt(0)
	s_barrier
	v_mfma_f32_16x16x32_bf16 v[66:69], v[200:203], v[134:137], v[66:69]
	s_add_u32 m0, s22, 0x8000
	v_mov_b32_e32 v223, v217
	global_load_lds_dwordx4 v223, s[6:7]
	v_mfma_f32_16x16x32_bf16 v[70:73], v[212:215], v[134:137], v[70:73]
	s_add_u32 m0, s22, 0x8400
	v_add_u32_e32 v224, 0x40, v217
	global_load_lds_dwordx4 v224, s[6:7]
	ds_read_b128 v[134:137], v216
	s_waitcnt lgkmcnt(7)
	v_mfma_f32_16x16x32_bf16 v[74:77], v[200:203], v[138:141], v[74:77]
	s_add_u32 m0, s22, 0x8800
	v_add_u32_e32 v223, 0x8000, v217
	global_load_lds_dwordx4 v223, s[6:7]
	v_mfma_f32_16x16x32_bf16 v[78:81], v[212:215], v[138:141], v[78:81]
	s_add_u32 m0, s22, 0x8c00
	v_add_u32_e32 v224, 0x8040, v217
	global_load_lds_dwordx4 v224, s[6:7]
	ds_read_b128 v[138:141], v216 offset:2048
	s_waitcnt lgkmcnt(7)
	v_mfma_f32_16x16x32_bf16 v[82:85], v[200:203], v[142:145], v[82:85]
	s_add_u32 m0, s22, 0x9000
	v_add_u32_e32 v223, 0x10000, v217
	global_load_lds_dwordx4 v223, s[6:7]
	v_mfma_f32_16x16x32_bf16 v[86:89], v[212:215], v[142:145], v[86:89]
	s_add_u32 m0, s22, 0x9400
	v_add_u32_e32 v224, 0x10040, v217
	global_load_lds_dwordx4 v224, s[6:7]
	ds_read_b128 v[142:145], v216 offset:4096
	s_waitcnt lgkmcnt(7)
	v_mfma_f32_16x16x32_bf16 v[90:93], v[200:203], v[146:149], v[90:93]
	s_add_u32 m0, s22, 0x9800
	v_add_u32_e32 v223, 0x18000, v217
	global_load_lds_dwordx4 v223, s[6:7]
	v_mfma_f32_16x16x32_bf16 v[94:97], v[212:215], v[146:149], v[94:97]
	s_add_u32 m0, s22, 0x9c00
	v_add_u32_e32 v224, 0x18040, v217
	global_load_lds_dwordx4 v224, s[6:7]
	ds_read_b128 v[146:149], v216 offset:6144
	s_waitcnt lgkmcnt(7)
	v_mfma_f32_16x16x32_bf16 v[98:101], v[200:203], v[150:153], v[98:101]
	v_mfma_f32_16x16x32_bf16 v[102:105], v[212:215], v[150:153], v[102:105]
	ds_read_b128 v[150:153], v216 offset:8192
	s_waitcnt lgkmcnt(7)
	v_mfma_f32_16x16x32_bf16 v[106:109], v[200:203], v[154:157], v[106:109]
	v_mfma_f32_16x16x32_bf16 v[110:113], v[212:215], v[154:157], v[110:113]
	ds_read_b128 v[154:157], v216 offset:10240
	s_waitcnt lgkmcnt(7)
	v_mfma_f32_16x16x32_bf16 v[114:117], v[200:203], v[158:161], v[114:117]
	v_mfma_f32_16x16x32_bf16 v[118:121], v[212:215], v[158:161], v[118:121]
	ds_read_b128 v[158:161], v216 offset:12288
	s_waitcnt lgkmcnt(7)
	v_mfma_f32_16x16x32_bf16 v[122:125], v[200:203], v[162:165], v[122:125]
	v_mfma_f32_16x16x32_bf16 v[126:129], v[212:215], v[162:165], v[126:129]
	v_add_u32_e32 v217, 0x80, v217
	v_add_u32_e32 v220, 0x800, v220
	v_add_u32_e32 v221, 0x800, v221
	s_mov_b32 s16, 6

.Lg256b_ip_next_ok:
	s_lshl_b32 s13, s13, 8
	s_lshl_b32 s14, s14, 7
	s_lshl_b32 s3, s15, 6
	s_add_u32 s17, s3, s13
	s_mul_i32 s17, s17, 0x800
	s_add_u32 s6, s18, s17
	s_addc_u32 s7, s19, 0
	v_mov_b32_e32 v217, v218
	ds_read_b128 v[162:165], v216 offset:14336
	s_waitcnt vmcnt(8) lgkmcnt(7)
	v_mfma_f32_16x16x32_bf16 v[2:5], v[166:169], v[134:137], v[2:5]
	v_mfma_f32_16x16x32_bf16 v[6:9], v[174:177], v[134:137], v[6:9]
	ds_read_b128 v[134:137], v216 offset:16384
	s_waitcnt lgkmcnt(7)
	v_mfma_f32_16x16x32_bf16 v[10:13], v[166:169], v[138:141], v[10:13]
	v_mfma_f32_16x16x32_bf16 v[14:17], v[174:177], v[138:141], v[14:17]
	ds_read_b128 v[138:141], v216 offset:18432
	s_waitcnt lgkmcnt(7)
	v_mfma_f32_16x16x32_bf16 v[18:21], v[166:169], v[142:145], v[18:21]
	v_mfma_f32_16x16x32_bf16 v[22:25], v[174:177], v[142:145], v[22:25]
	ds_read_b128 v[142:145], v216 offset:20480
	s_waitcnt lgkmcnt(7)
	v_mfma_f32_16x16x32_bf16 v[26:29], v[166:169], v[146:149], v[26:29]
	v_mfma_f32_16x16x32_bf16 v[30:33], v[174:177], v[146:149], v[30:33]
	ds_read_b128 v[146:149], v216 offset:22528
	s_waitcnt lgkmcnt(7)
	v_mfma_f32_16x16x32_bf16 v[34:37], v[166:169], v[150:153], v[34:37]
	global_load_dwordx4 v[196:199], v220, s[8:9]
	v_mfma_f32_16x16x32_bf16 v[38:41], v[174:177], v[150:153], v[38:41]
	ds_read_b128 v[150:153], v216 offset:24576
	s_waitcnt lgkmcnt(7)
	v_mfma_f32_16x16x32_bf16 v[42:45], v[166:169], v[154:157], v[42:45]
	global_load_dwordx4 v[200:203], v220, s[8:9] offset:1024
	v_mfma_f32_16x16x32_bf16 v[46:49], v[174:177], v[154:157], v[46:49]
	ds_read_b128 v[154:157], v216 offset:26624
	s_waitcnt lgkmcnt(7)
	v_mfma_f32_16x16x32_bf16 v[50:53], v[166:169], v[158:161], v[50:53]
	global_load_dwordx4 v[204:207], v221, s[8:9]
	v_mfma_f32_16x16x32_bf16 v[54:57], v[174:177], v[158:161], v[54:57]
	ds_read_b128 v[158:161], v216 offset:28672
	s_waitcnt lgkmcnt(7)
	v_mfma_f32_16x16x32_bf16 v[58:61], v[166:169], v[162:165], v[58:61]
	global_load_dwordx4 v[212:215], v221, s[8:9] offset:1024
	v_mfma_f32_16x16x32_bf16 v[62:65], v[174:177], v[162:165], v[62:65]
	ds_read_b128 v[162:165], v216 offset:30720
	s_waitcnt lgkmcnt(7)
	v_mfma_f32_16x16x32_bf16 v[66:69], v[166:169], v[134:137], v[66:69]
	v_mfma_f32_16x16x32_bf16 v[70:73], v[174:177], v[134:137], v[70:73]
	ds_read_b128 v[134:137], v216 offset:1024
	s_waitcnt lgkmcnt(7)
	v_mfma_f32_16x16x32_bf16 v[74:77], v[166:169], v[138:141], v[74:77]
	v_mfma_f32_16x16x32_bf16 v[78:81], v[174:177], v[138:141], v[78:81]
	ds_read_b128 v[138:141], v216 offset:3072
	s_waitcnt lgkmcnt(7)
	v_mfma_f32_16x16x32_bf16 v[82:85], v[166:169], v[142:145], v[82:85]
	v_mfma_f32_16x16x32_bf16 v[86:89], v[174:177], v[142:145], v[86:89]
	ds_read_b128 v[142:145], v216 offset:5120
	s_waitcnt lgkmcnt(7)
	v_mfma_f32_16x16x32_bf16 v[90:93], v[166:169], v[146:149], v[90:93]
	v_mfma_f32_16x16x32_bf16 v[94:97], v[174:177], v[146:149], v[94:97]
	ds_read_b128 v[146:149], v216 offset:7168
	s_waitcnt lgkmcnt(7)
	v_mfma_f32_16x16x32_bf16 v[98:101], v[166:169], v[150:153], v[98:101]
	v_mfma_f32_16x16x32_bf16 v[102:105], v[174:177], v[150:153], v[102:105]
	ds_read_b128 v[150:153], v216 offset:9216
	s_waitcnt lgkmcnt(7)
	v_mfma_f32_16x16x32_bf16 v[106:109], v[166:169], v[154:157], v[106:109]
	v_mfma_f32_16x16x32_bf16 v[110:113], v[174:177], v[154:157], v[110:113]
	ds_read_b128 v[154:157], v216 offset:11264
	s_waitcnt lgkmcnt(7)
	v_mfma_f32_16x16x32_bf16 v[114:117], v[166:169], v[158:161], v[114:117]
	v_mfma_f32_16x16x32_bf16 v[118:121], v[174:177], v[158:161], v[118:121]
	ds_read_b128 v[158:161], v216 offset:13312
	s_waitcnt lgkmcnt(7)
	v_mfma_f32_16x16x32_bf16 v[122:125], v[166:169], v[162:165], v[122:125]
	v_mfma_f32_16x16x32_bf16 v[126:129], v[174:177], v[162:165], v[126:129]
	ds_read_b128 v[162:165], v216 offset:15360
	s_waitcnt lgkmcnt(7)
	v_mfma_f32_16x16x32_bf16 v[2:5], v[170:173], v[134:137], v[2:5]
	v_mfma_f32_16x16x32_bf16 v[6:9], v[178:181], v[134:137], v[6:9]
	ds_read_b128 v[134:137], v216 offset:17408
	s_waitcnt lgkmcnt(7)
	v_mfma_f32_16x16x32_bf16 v[10:13], v[170:173], v[138:141], v[10:13]
	v_mfma_f32_16x16x32_bf16 v[14:17], v[178:181], v[138:141], v[14:17]
	ds_read_b128 v[138:141], v216 offset:19456
	s_waitcnt lgkmcnt(7)
	v_mfma_f32_16x16x32_bf16 v[18:21], v[170:173], v[142:145], v[18:21]
	v_mfma_f32_16x16x32_bf16 v[22:25], v[178:181], v[142:145], v[22:25]
	ds_read_b128 v[142:145], v216 offset:21504
	s_waitcnt lgkmcnt(7)
	v_mfma_f32_16x16x32_bf16 v[26:29], v[170:173], v[146:149], v[26:29]
	v_mfma_f32_16x16x32_bf16 v[30:33], v[178:181], v[146:149], v[30:33]
	ds_read_b128 v[146:149], v216 offset:23552
	s_waitcnt lgkmcnt(7)
	v_mfma_f32_16x16x32_bf16 v[34:37], v[170:173], v[150:153], v[34:37]
	v_mfma_f32_16x16x32_bf16 v[38:41], v[178:181], v[150:153], v[38:41]
	ds_read_b128 v[150:153], v216 offset:25600
	s_waitcnt lgkmcnt(7)
	v_mfma_f32_16x16x32_bf16 v[42:45], v[170:173], v[154:157], v[42:45]
	v_mfma_f32_16x16x32_bf16 v[46:49], v[178:181], v[154:157], v[46:49]
	ds_read_b128 v[154:157], v216 offset:27648
	s_waitcnt lgkmcnt(7)
	v_mfma_f32_16x16x32_bf16 v[50:53], v[170:173], v[158:161], v[50:53]
	v_mfma_f32_16x16x32_bf16 v[54:57], v[178:181], v[158:161], v[54:57]
	ds_read_b128 v[158:161], v216 offset:29696
	s_waitcnt lgkmcnt(7)
	v_mfma_f32_16x16x32_bf16 v[58:61], v[170:173], v[162:165], v[58:61]
	v_mfma_f32_16x16x32_bf16 v[62:65], v[178:181], v[162:165], v[62:65]
	ds_read_b128 v[162:165], v216 offset:31744
	s_waitcnt vmcnt(4) lgkmcnt(0)
	s_barrier
	v_mfma_f32_16x16x32_bf16 v[66:69], v[170:173], v[134:137], v[66:69]
	s_add_u32 m0, s22, 0x0
	v_mov_b32_e32 v223, v217
	global_load_lds_dwordx4 v223, s[6:7]
	v_mfma_f32_16x16x32_bf16 v[70:73], v[178:181], v[134:137], v[70:73]
	s_add_u32 m0, s22, 0x400
	v_add_u32_e32 v224, 0x40, v217
	global_load_lds_dwordx4 v224, s[6:7]
	ds_read_b128 v[134:137], v216 offset:32768
	s_waitcnt lgkmcnt(7)
	v_mfma_f32_16x16x32_bf16 v[74:77], v[170:173], v[138:141], v[74:77]
	s_add_u32 m0, s22, 0x800
	v_add_u32_e32 v223, 0x8000, v217
	global_load_lds_dwordx4 v223, s[6:7]
	v_mfma_f32_16x16x32_bf16 v[78:81], v[178:181], v[138:141], v[78:81]
	s_add_u32 m0, s22, 0xc00
	v_add_u32_e32 v224, 0x8040, v217
	global_load_lds_dwordx4 v224, s[6:7]
	ds_read_b128 v[138:141], v216 offset:34816
	s_waitcnt lgkmcnt(7)
	v_mfma_f32_16x16x32_bf16 v[82:85], v[170:173], v[142:145], v[82:85]
	s_add_u32 m0, s22, 0x1000
	v_add_u32_e32 v223, 0x10000, v217
	global_load_lds_dwordx4 v223, s[6:7]
	v_mfma_f32_16x16x32_bf16 v[86:89], v[178:181], v[142:145], v[86:89]
	s_add_u32 m0, s22, 0x1400
	v_add_u32_e32 v224, 0x10040, v217
	global_load_lds_dwordx4 v224, s[6:7]
	ds_read_b128 v[142:145], v216 offset:36864
	s_waitcnt lgkmcnt(7)
	v_mfma_f32_16x16x32_bf16 v[90:93], v[170:173], v[146:149], v[90:93]
	s_add_u32 m0, s22, 0x1800
	v_add_u32_e32 v223, 0x18000, v217
	global_load_lds_dwordx4 v223, s[6:7]
	v_mfma_f32_16x16x32_bf16 v[94:97], v[178:181], v[146:149], v[94:97]
	s_add_u32 m0, s22, 0x1c00
	v_add_u32_e32 v224, 0x18040, v217
	global_load_lds_dwordx4 v224, s[6:7]
	ds_read_b128 v[146:149], v216 offset:38912
	s_waitcnt lgkmcnt(7)
	v_mfma_f32_16x16x32_bf16 v[98:101], v[170:173], v[150:153], v[98:101]
	v_mfma_f32_16x16x32_bf16 v[102:105], v[178:181], v[150:153], v[102:105]
	ds_read_b128 v[150:153], v216 offset:40960
	s_waitcnt lgkmcnt(7)
	v_mfma_f32_16x16x32_bf16 v[106:109], v[170:173], v[154:157], v[106:109]
	v_mfma_f32_16x16x32_bf16 v[110:113], v[178:181], v[154:157], v[110:113]
	ds_read_b128 v[154:157], v216 offset:43008
	s_waitcnt lgkmcnt(7)
	v_mfma_f32_16x16x32_bf16 v[114:117], v[170:173], v[158:161], v[114:117]
	v_mfma_f32_16x16x32_bf16 v[118:121], v[178:181], v[158:161], v[118:121]
	ds_read_b128 v[158:161], v216 offset:45056
	s_waitcnt lgkmcnt(7)
	v_mfma_f32_16x16x32_bf16 v[122:125], v[170:173], v[162:165], v[122:125]
	v_mfma_f32_16x16x32_bf16 v[126:129], v[178:181], v[162:165], v[126:129]
	v_add_u32_e32 v217, 0x80, v217
	v_add_u32_e32 v220, 0x800, v220
	v_add_u32_e32 v221, 0x800, v221
	s_lshr_b32 s3, s14, 4
	s_lshl_b32 s17, s15, 1
	s_add_u32 s3, s3, s17
	s_mul_i32 s17, s3, 0x8000
	s_add_u32 s8, s20, s17
	s_addc_u32 s9, s21, 0
	v_mov_b32_e32 v220, v222
	v_add_u32_e32 v221, 0x8000, v222
	ds_read_b128 v[162:165], v216 offset:47104
	s_waitcnt vmcnt(8) lgkmcnt(7)
	v_mfma_f32_16x16x32_bf16 v[2:5], v[196:199], v[134:137], v[2:5]
	v_mfma_f32_16x16x32_bf16 v[6:9], v[204:207], v[134:137], v[6:9]
	ds_read_b128 v[134:137], v216 offset:49152
	s_waitcnt lgkmcnt(7)
	v_mfma_f32_16x16x32_bf16 v[10:13], v[196:199], v[138:141], v[10:13]
	v_mfma_f32_16x16x32_bf16 v[14:17], v[204:207], v[138:141], v[14:17]
	ds_read_b128 v[138:141], v216 offset:51200
	s_waitcnt lgkmcnt(7)
	v_mfma_f32_16x16x32_bf16 v[18:21], v[196:199], v[142:145], v[18:21]
	v_mfma_f32_16x16x32_bf16 v[22:25], v[204:207], v[142:145], v[22:25]
	ds_read_b128 v[142:145], v216 offset:53248
	s_waitcnt lgkmcnt(7)
	v_mfma_f32_16x16x32_bf16 v[26:29], v[196:199], v[146:149], v[26:29]
	v_mfma_f32_16x16x32_bf16 v[30:33], v[204:207], v[146:149], v[30:33]
	ds_read_b128 v[146:149], v216 offset:55296
	s_waitcnt lgkmcnt(7)
	v_mfma_f32_16x16x32_bf16 v[34:37], v[196:199], v[150:153], v[34:37]
	global_load_dwordx4 v[166:169], v220, s[8:9]
	v_mfma_f32_16x16x32_bf16 v[38:41], v[204:207], v[150:153], v[38:41]
	ds_read_b128 v[150:153], v216 offset:57344
	s_waitcnt lgkmcnt(7)
	v_mfma_f32_16x16x32_bf16 v[42:45], v[196:199], v[154:157], v[42:45]
	global_load_dwordx4 v[170:173], v220, s[8:9] offset:1024
	v_mfma_f32_16x16x32_bf16 v[46:49], v[204:207], v[154:157], v[46:49]
	ds_read_b128 v[154:157], v216 offset:59392
	s_waitcnt lgkmcnt(7)
	v_mfma_f32_16x16x32_bf16 v[50:53], v[196:199], v[158:161], v[50:53]
	global_load_dwordx4 v[174:177], v221, s[8:9]
	v_mfma_f32_16x16x32_bf16 v[54:57], v[204:207], v[158:161], v[54:57]
	ds_read_b128 v[158:161], v216 offset:61440
	s_waitcnt lgkmcnt(7)
	v_mfma_f32_16x16x32_bf16 v[58:61], v[196:199], v[162:165], v[58:61]
	global_load_dwordx4 v[178:181], v221, s[8:9] offset:1024
	v_mfma_f32_16x16x32_bf16 v[62:65], v[204:207], v[162:165], v[62:65]
	ds_read_b128 v[162:165], v216 offset:63488
	s_waitcnt lgkmcnt(7)
	v_mfma_f32_16x16x32_bf16 v[66:69], v[196:199], v[134:137], v[66:69]
	v_mfma_f32_16x16x32_bf16 v[70:73], v[204:207], v[134:137], v[70:73]
	ds_read_b128 v[134:137], v216 offset:33792
	s_waitcnt lgkmcnt(7)
	v_mfma_f32_16x16x32_bf16 v[74:77], v[196:199], v[138:141], v[74:77]
	v_mfma_f32_16x16x32_bf16 v[78:81], v[204:207], v[138:141], v[78:81]
	ds_read_b128 v[138:141], v216 offset:35840
	s_waitcnt lgkmcnt(7)
	v_mfma_f32_16x16x32_bf16 v[82:85], v[196:199], v[142:145], v[82:85]
	v_mfma_f32_16x16x32_bf16 v[86:89], v[204:207], v[142:145], v[86:89]
	ds_read_b128 v[142:145], v216 offset:37888
	s_waitcnt lgkmcnt(7)
	v_mfma_f32_16x16x32_bf16 v[90:93], v[196:199], v[146:149], v[90:93]
	v_mfma_f32_16x16x32_bf16 v[94:97], v[204:207], v[146:149], v[94:97]
	ds_read_b128 v[146:149], v216 offset:39936
	s_waitcnt lgkmcnt(7)
	v_mfma_f32_16x16x32_bf16 v[98:101], v[196:199], v[150:153], v[98:101]
	v_mfma_f32_16x16x32_bf16 v[102:105], v[204:207], v[150:153], v[102:105]
	ds_read_b128 v[150:153], v216 offset:41984
	s_waitcnt lgkmcnt(7)
	v_mfma_f32_16x16x32_bf16 v[106:109], v[196:199], v[154:157], v[106:109]
	v_mfma_f32_16x16x32_bf16 v[110:113], v[204:207], v[154:157], v[110:113]
	ds_read_b128 v[154:157], v216 offset:44032
	s_waitcnt lgkmcnt(7)
	v_mfma_f32_16x16x32_bf16 v[114:117], v[196:199], v[158:161], v[114:117]
	v_mfma_f32_16x16x32_bf16 v[118:121], v[204:207], v[158:161], v[118:121]
	ds_read_b128 v[158:161], v216 offset:46080
	s_waitcnt lgkmcnt(7)
	v_mfma_f32_16x16x32_bf16 v[122:125], v[196:199], v[162:165], v[122:125]
	v_mfma_f32_16x16x32_bf16 v[126:129], v[204:207], v[162:165], v[126:129]
	ds_read_b128 v[162:165], v216 offset:48128
	s_waitcnt lgkmcnt(7)
	v_mfma_f32_16x16x32_bf16 v[2:5], v[200:203], v[134:137], v[2:5]
	v_mfma_f32_16x16x32_bf16 v[6:9], v[212:215], v[134:137], v[6:9]
	ds_read_b128 v[134:137], v216 offset:50176
	s_waitcnt lgkmcnt(7)
	v_mfma_f32_16x16x32_bf16 v[10:13], v[200:203], v[138:141], v[10:13]
	v_mfma_f32_16x16x32_bf16 v[14:17], v[212:215], v[138:141], v[14:17]
	ds_read_b128 v[138:141], v216 offset:52224
	s_waitcnt lgkmcnt(7)
	v_mfma_f32_16x16x32_bf16 v[18:21], v[200:203], v[142:145], v[18:21]
	v_mfma_f32_16x16x32_bf16 v[22:25], v[212:215], v[142:145], v[22:25]
	ds_read_b128 v[142:145], v216 offset:54272
	s_waitcnt lgkmcnt(7)
	v_mfma_f32_16x16x32_bf16 v[26:29], v[200:203], v[146:149], v[26:29]
	v_mfma_f32_16x16x32_bf16 v[30:33], v[212:215], v[146:149], v[30:33]
	ds_read_b128 v[146:149], v216 offset:56320
	s_waitcnt lgkmcnt(7)
	v_mfma_f32_16x16x32_bf16 v[34:37], v[200:203], v[150:153], v[34:37]
	v_mfma_f32_16x16x32_bf16 v[38:41], v[212:215], v[150:153], v[38:41]
	ds_read_b128 v[150:153], v216 offset:58368
	s_waitcnt lgkmcnt(7)
	v_mfma_f32_16x16x32_bf16 v[42:45], v[200:203], v[154:157], v[42:45]
	v_mfma_f32_16x16x32_bf16 v[46:49], v[212:215], v[154:157], v[46:49]
	ds_read_b128 v[154:157], v216 offset:60416
	s_waitcnt lgkmcnt(7)
	v_mfma_f32_16x16x32_bf16 v[50:53], v[200:203], v[158:161], v[50:53]
	v_mfma_f32_16x16x32_bf16 v[54:57], v[212:215], v[158:161], v[54:57]
	ds_read_b128 v[158:161], v216 offset:62464
	s_waitcnt lgkmcnt(7)
	v_mfma_f32_16x16x32_bf16 v[58:61], v[200:203], v[162:165], v[58:61]
	v_mfma_f32_16x16x32_bf16 v[62:65], v[212:215], v[162:165], v[62:65]
	ds_read_b128 v[162:165], v216 offset:64512
	s_waitcnt vmcnt(4) lgkmcnt(0)
	s_barrier
	v_mfma_f32_16x16x32_bf16 v[66:69], v[200:203], v[134:137], v[66:69]
	s_add_u32 m0, s22, 0x8000
	v_mov_b32_e32 v223, v217
	global_load_lds_dwordx4 v223, s[6:7]
	v_mfma_f32_16x16x32_bf16 v[70:73], v[212:215], v[134:137], v[70:73]
	s_add_u32 m0, s22, 0x8400
	v_add_u32_e32 v224, 0x40, v217
	global_load_lds_dwordx4 v224, s[6:7]
	ds_read_b128 v[134:137], v216
	s_waitcnt lgkmcnt(7)
	v_mfma_f32_16x16x32_bf16 v[74:77], v[200:203], v[138:141], v[74:77]
	s_add_u32 m0, s22, 0x8800
	v_add_u32_e32 v223, 0x8000, v217
	global_load_lds_dwordx4 v223, s[6:7]
	v_mfma_f32_16x16x32_bf16 v[78:81], v[212:215], v[138:141], v[78:81]
	s_add_u32 m0, s22, 0x8c00
	v_add_u32_e32 v224, 0x8040, v217
	global_load_lds_dwordx4 v224, s[6:7]
	ds_read_b128 v[138:141], v216 offset:2048
	s_waitcnt lgkmcnt(7)
	v_mfma_f32_16x16x32_bf16 v[82:85], v[200:203], v[142:145], v[82:85]
	s_add_u32 m0, s22, 0x9000
	v_add_u32_e32 v223, 0x10000, v217
	global_load_lds_dwordx4 v223, s[6:7]
	v_mfma_f32_16x16x32_bf16 v[86:89], v[212:215], v[142:145], v[86:89]
	s_add_u32 m0, s22, 0x9400
	v_add_u32_e32 v224, 0x10040, v217
	global_load_lds_dwordx4 v224, s[6:7]
	ds_read_b128 v[142:145], v216 offset:4096
	s_waitcnt lgkmcnt(7)
	v_mfma_f32_16x16x32_bf16 v[90:93], v[200:203], v[146:149], v[90:93]
	s_add_u32 m0, s22, 0x9800
	v_add_u32_e32 v223, 0x18000, v217
	global_load_lds_dwordx4 v223, s[6:7]
	v_mfma_f32_16x16x32_bf16 v[94:97], v[212:215], v[146:149], v[94:97]
	s_add_u32 m0, s22, 0x9c00
	v_add_u32_e32 v224, 0x18040, v217
	global_load_lds_dwordx4 v224, s[6:7]
	ds_read_b128 v[146:149], v216 offset:6144
	s_waitcnt lgkmcnt(7)
	v_mfma_f32_16x16x32_bf16 v[98:101], v[200:203], v[150:153], v[98:101]
	v_mfma_f32_16x16x32_bf16 v[102:105], v[212:215], v[150:153], v[102:105]
	ds_read_b128 v[150:153], v216 offset:8192
	s_waitcnt lgkmcnt(7)
	v_mfma_f32_16x16x32_bf16 v[106:109], v[200:203], v[154:157], v[106:109]
	v_mfma_f32_16x16x32_bf16 v[110:113], v[212:215], v[154:157], v[110:113]
	ds_read_b128 v[154:157], v216 offset:10240
	s_waitcnt lgkmcnt(7)
	v_mfma_f32_16x16x32_bf16 v[114:117], v[200:203], v[158:161], v[114:117]
	v_mfma_f32_16x16x32_bf16 v[118:121], v[212:215], v[158:161], v[118:121]
	ds_read_b128 v[158:161], v216 offset:12288
	s_waitcnt lgkmcnt(7)
	v_mfma_f32_16x16x32_bf16 v[122:125], v[200:203], v[162:165], v[122:125]
	v_mfma_f32_16x16x32_bf16 v[126:129], v[212:215], v[162:165], v[126:129]
	v_add_u32_e32 v217, 0x80, v217
	v_add_u32_e32 v220, 0x800, v220
	v_add_u32_e32 v221, 0x800, v221
	s_mov_b32 s16, 1
	s_branch .Lg256b_ip_epi
